# code placement: K-loop heads on 256-byte boundaries
# baseline (speedup 1.0000x reference)
.Lpeel_327:
	ds_read_b128 v[128:131], v177
	ds_read_b128 v[132:135], v177 offset:1024
	ds_read_b128 v[136:139], v177 offset:2048
	ds_read_b128 v[140:143], v177 offset:3072
	ds_read_b128 v[160:163], v178
	ds_read_b128 v[164:167], v178 offset:1024
	ds_read_b128 v[168:171], v178 offset:2048
	ds_read_b128 v[180:183], v178 offset:3072
	s_add_i32 s87, s40, 2
	s_add_u32 s41, s38, 0xfffc0080
	s_addc_u32 s42, s39, -1
	s_cmp_eq_u32 s57, s40
	s_cselect_b32 s40, s84, s85
	s_cselect_b32 s43, s81, s42
	s_cselect_b32 s42, s82, s41
	s_cselect_b32 s41, s83, s86
	s_add_i32 m0, s48, 0xc000
	ds_read_b128 v[184:187], v179
	ds_read_b128 v[188:191], v179 offset:1024
	ds_read_b128 v[192:195], v179 offset:2048
	ds_read_b128 v[196:199], v179 offset:3072
	ds_read_b128 v[202:205], v179 offset:4096
	ds_read_b128 v[206:209], v179 offset:5120
	ds_read_b128 v[210:213], v179 offset:6144
	ds_read_b128 v[214:217], v179 offset:7168
	global_load_lds_dwordx4 v152, s[38:39]
	s_add_i32 m0, s48, 0xe000
	s_nop 0
	global_load_lds_dwordx4 v154, s[38:39]
	s_waitcnt vmcnt(8)
	s_waitcnt lgkmcnt(0)
	s_setprio 1
	s_barrier
	v_mfma_f32_16x16x32_bf16 v[124:127], v[128:131], v[184:187], 0
	v_mfma_f32_16x16x32_bf16 v[120:123], v[136:139], v[184:187], 0
	v_mfma_f32_16x16x32_bf16 v[108:111], v[128:131], v[192:195], 0
	v_mfma_f32_16x16x32_bf16 v[104:107], v[136:139], v[192:195], 0
	v_mfma_f32_16x16x32_bf16 v[92:95], v[128:131], v[202:205], 0
	v_mfma_f32_16x16x32_bf16 v[88:91], v[136:139], v[202:205], 0
	v_mfma_f32_16x16x32_bf16 v[76:79], v[128:131], v[210:213], 0
	v_mfma_f32_16x16x32_bf16 v[72:75], v[136:139], v[210:213], 0
	v_mfma_f32_16x16x32_bf16 v[124:127], v[132:135], v[188:191], v[124:127]
	v_mfma_f32_16x16x32_bf16 v[120:123], v[140:143], v[188:191], v[120:123]
	v_mfma_f32_16x16x32_bf16 v[108:111], v[132:135], v[196:199], v[108:111]
	v_mfma_f32_16x16x32_bf16 v[104:107], v[140:143], v[196:199], v[104:107]
	v_mfma_f32_16x16x32_bf16 v[92:95], v[132:135], v[206:209], v[92:95]
	v_mfma_f32_16x16x32_bf16 v[88:91], v[140:143], v[206:209], v[88:91]
	v_mfma_f32_16x16x32_bf16 v[76:79], v[132:135], v[214:217], v[76:79]
	v_mfma_f32_16x16x32_bf16 v[72:75], v[140:143], v[214:217], v[72:75]
	v_mfma_f32_16x16x32_bf16 v[116:119], v[160:163], v[184:187], 0
	v_mfma_f32_16x16x32_bf16 v[112:115], v[168:171], v[184:187], 0
	v_mfma_f32_16x16x32_bf16 v[100:103], v[160:163], v[192:195], 0
	v_mfma_f32_16x16x32_bf16 v[96:99], v[168:171], v[192:195], 0
	v_mfma_f32_16x16x32_bf16 v[84:87], v[160:163], v[202:205], 0
	v_mfma_f32_16x16x32_bf16 v[80:83], v[168:171], v[202:205], 0
	v_mfma_f32_16x16x32_bf16 v[68:71], v[160:163], v[210:213], 0
	v_mfma_f32_16x16x32_bf16 v[64:67], v[168:171], v[210:213], 0
	v_mfma_f32_16x16x32_bf16 v[116:119], v[164:167], v[188:191], v[116:119]
	v_mfma_f32_16x16x32_bf16 v[112:115], v[180:183], v[188:191], v[112:115]
	v_mfma_f32_16x16x32_bf16 v[100:103], v[164:167], v[196:199], v[100:103]
	v_mfma_f32_16x16x32_bf16 v[96:99], v[180:183], v[196:199], v[96:99]
	v_mfma_f32_16x16x32_bf16 v[84:87], v[164:167], v[206:209], v[84:87]
	v_mfma_f32_16x16x32_bf16 v[80:83], v[180:183], v[206:209], v[80:83]
	v_mfma_f32_16x16x32_bf16 v[68:71], v[164:167], v[214:217], v[68:71]
	v_mfma_f32_16x16x32_bf16 v[64:67], v[180:183], v[214:217], v[64:67]
	s_barrier
	s_setprio 0
	s_add_i32 s88, s58, s33
	v_lshl_add_u64 v[172:173], s[40:41], 0, v[148:149]
	s_mov_b32 m0, s88
	ds_read_b128 v[184:187], v179 offset:16384
	ds_read_b128 v[188:191], v179 offset:17408
	ds_read_b128 v[192:195], v179 offset:18432
	ds_read_b128 v[196:199], v179 offset:19456
	ds_read_b128 v[202:205], v179 offset:20480
	ds_read_b128 v[206:209], v179 offset:21504
	ds_read_b128 v[210:213], v179 offset:22528
	ds_read_b128 v[214:217], v179 offset:23552
	global_load_lds_dwordx4 v[172:173], off
	s_add_i32 m0, s88, 0x2000
	s_add_u32 s88, s40, 0x40000
	v_lshl_add_u64 v[218:219], s[40:41], 0, v[144:145]
	s_addc_u32 s89, s41, 0
	s_add_i32 s90, s64, s33
	global_load_lds_dwordx4 v[218:219], off
	s_mov_b32 m0, s90
	v_lshl_add_u64 v[222:223], s[42:43], 0, v[146:147]
	global_load_lds_dwordx4 v148, s[88:89]
	s_add_i32 m0, s90, 0x2000
	s_nop 0
	global_load_lds_dwordx4 v144, s[88:89]
	v_lshl_add_u64 v[220:221], s[42:43], 0, v[150:151]
	s_mov_b32 m0, s48
	s_nop 0
	global_load_lds_dwordx4 v[220:221], off
	s_mov_b32 m0, s49
	s_nop 0
	global_load_lds_dwordx4 v[222:223], off
	s_waitcnt vmcnt(8)
	s_waitcnt lgkmcnt(0)
	s_setprio 1
	s_barrier
	v_mfma_f32_16x16x32_bf16 v[60:63], v[128:131], v[184:187], 0
	v_mfma_f32_16x16x32_bf16 v[56:59], v[136:139], v[184:187], 0
	v_mfma_f32_16x16x32_bf16 v[44:47], v[128:131], v[192:195], 0
	v_mfma_f32_16x16x32_bf16 v[40:43], v[136:139], v[192:195], 0
	v_mfma_f32_16x16x32_bf16 v[28:31], v[128:131], v[202:205], 0
	v_mfma_f32_16x16x32_bf16 v[24:27], v[136:139], v[202:205], 0
	v_mfma_f32_16x16x32_bf16 v[12:15], v[128:131], v[210:213], 0
	v_mfma_f32_16x16x32_bf16 v[8:11], v[136:139], v[210:213], 0
	v_mfma_f32_16x16x32_bf16 v[60:63], v[132:135], v[188:191], v[60:63]
	v_mfma_f32_16x16x32_bf16 v[56:59], v[140:143], v[188:191], v[56:59]
	v_mfma_f32_16x16x32_bf16 v[44:47], v[132:135], v[196:199], v[44:47]
	v_mfma_f32_16x16x32_bf16 v[40:43], v[140:143], v[196:199], v[40:43]
	v_mfma_f32_16x16x32_bf16 v[28:31], v[132:135], v[206:209], v[28:31]
	v_mfma_f32_16x16x32_bf16 v[24:27], v[140:143], v[206:209], v[24:27]
	v_mfma_f32_16x16x32_bf16 v[12:15], v[132:135], v[214:217], v[12:15]
	v_mfma_f32_16x16x32_bf16 v[8:11], v[140:143], v[214:217], v[8:11]
	v_mfma_f32_16x16x32_bf16 v[52:55], v[160:163], v[184:187], 0
	v_mfma_f32_16x16x32_bf16 v[48:51], v[168:171], v[184:187], 0
	v_mfma_f32_16x16x32_bf16 v[36:39], v[160:163], v[192:195], 0
	v_mfma_f32_16x16x32_bf16 v[32:35], v[168:171], v[192:195], 0
	v_mfma_f32_16x16x32_bf16 v[20:23], v[160:163], v[202:205], 0
	v_mfma_f32_16x16x32_bf16 v[16:19], v[168:171], v[202:205], 0
	v_mfma_f32_16x16x32_bf16 v[4:7], v[160:163], v[210:213], 0
	v_mfma_f32_16x16x32_bf16 v[0:3], v[168:171], v[210:213], 0
	v_mfma_f32_16x16x32_bf16 v[52:55], v[164:167], v[188:191], v[52:55]
	v_mfma_f32_16x16x32_bf16 v[48:51], v[180:183], v[188:191], v[48:51]
	v_mfma_f32_16x16x32_bf16 v[36:39], v[164:167], v[196:199], v[36:39]
	v_mfma_f32_16x16x32_bf16 v[32:35], v[180:183], v[196:199], v[32:35]
	v_mfma_f32_16x16x32_bf16 v[20:23], v[164:167], v[206:209], v[20:23]
	v_mfma_f32_16x16x32_bf16 v[16:19], v[180:183], v[206:209], v[16:19]
	v_mfma_f32_16x16x32_bf16 v[4:7], v[164:167], v[214:217], v[4:7]
	v_mfma_f32_16x16x32_bf16 v[0:3], v[180:183], v[214:217], v[0:3]
	s_barrier
	s_setprio 0
	s_add_i32 s88, 0, 0x18000
	s_add_i32 s89, 0, 0x1c000
	v_add_u32_e32 v140, s88, v175
	v_add_u32_e32 v180, s89, v175
	ds_read_b128 v[128:131], v140
	ds_read_b128 v[132:135], v140 offset:1024
	ds_read_b128 v[136:139], v140 offset:2048
	ds_read_b128 v[140:143], v140 offset:3072
	ds_read_b128 v[160:163], v180
	ds_read_b128 v[164:167], v180 offset:1024
	ds_read_b128 v[168:171], v180 offset:2048
	ds_read_b128 v[180:183], v180 offset:3072
	s_add_u32 s42, s42, 0x40000
	s_addc_u32 s43, s43, 0
	s_mov_b32 m0, s50
	ds_read_b128 v[184:187], v179 offset:32768
	ds_read_b128 v[188:191], v179 offset:33792
	ds_read_b128 v[192:195], v179 offset:34816
	ds_read_b128 v[196:199], v179 offset:35840
	ds_read_b128 v[202:205], v179 offset:36864
	ds_read_b128 v[206:209], v179 offset:37888
	ds_read_b128 v[210:213], v179 offset:38912
	ds_read_b128 v[214:217], v179 offset:39936
	global_load_lds_dwordx4 v150, s[42:43]
	s_mov_b32 m0, s51
	s_nop 0
	global_load_lds_dwordx4 v146, s[42:43]
	s_waitcnt vmcnt(8)
	s_waitcnt lgkmcnt(0)
	s_setprio 1
	s_barrier
	v_mfma_f32_16x16x32_bf16 v[124:127], v[128:131], v[184:187], v[124:127]
	v_mfma_f32_16x16x32_bf16 v[120:123], v[136:139], v[184:187], v[120:123]
	v_mfma_f32_16x16x32_bf16 v[108:111], v[128:131], v[192:195], v[108:111]
	v_mfma_f32_16x16x32_bf16 v[104:107], v[136:139], v[192:195], v[104:107]
	v_mfma_f32_16x16x32_bf16 v[92:95], v[128:131], v[202:205], v[92:95]
	v_mfma_f32_16x16x32_bf16 v[88:91], v[136:139], v[202:205], v[88:91]
	v_mfma_f32_16x16x32_bf16 v[76:79], v[128:131], v[210:213], v[76:79]
	v_mfma_f32_16x16x32_bf16 v[72:75], v[136:139], v[210:213], v[72:75]
	v_mfma_f32_16x16x32_bf16 v[124:127], v[132:135], v[188:191], v[124:127]
	v_mfma_f32_16x16x32_bf16 v[120:123], v[140:143], v[188:191], v[120:123]
	v_mfma_f32_16x16x32_bf16 v[108:111], v[132:135], v[196:199], v[108:111]
	v_mfma_f32_16x16x32_bf16 v[104:107], v[140:143], v[196:199], v[104:107]
	v_mfma_f32_16x16x32_bf16 v[92:95], v[132:135], v[206:209], v[92:95]
	v_mfma_f32_16x16x32_bf16 v[88:91], v[140:143], v[206:209], v[88:91]
	v_mfma_f32_16x16x32_bf16 v[76:79], v[132:135], v[214:217], v[76:79]
	v_mfma_f32_16x16x32_bf16 v[72:75], v[140:143], v[214:217], v[72:75]
	v_mfma_f32_16x16x32_bf16 v[116:119], v[160:163], v[184:187], v[116:119]
	v_mfma_f32_16x16x32_bf16 v[112:115], v[168:171], v[184:187], v[112:115]
	v_mfma_f32_16x16x32_bf16 v[100:103], v[160:163], v[192:195], v[100:103]
	v_mfma_f32_16x16x32_bf16 v[96:99], v[168:171], v[192:195], v[96:99]
	v_mfma_f32_16x16x32_bf16 v[84:87], v[160:163], v[202:205], v[84:87]
	v_mfma_f32_16x16x32_bf16 v[80:83], v[168:171], v[202:205], v[80:83]
	v_mfma_f32_16x16x32_bf16 v[68:71], v[160:163], v[210:213], v[68:71]
	v_mfma_f32_16x16x32_bf16 v[64:67], v[168:171], v[210:213], v[64:67]
	v_mfma_f32_16x16x32_bf16 v[116:119], v[164:167], v[188:191], v[116:119]
	v_mfma_f32_16x16x32_bf16 v[112:115], v[180:183], v[188:191], v[112:115]
	v_mfma_f32_16x16x32_bf16 v[100:103], v[164:167], v[196:199], v[100:103]
	v_mfma_f32_16x16x32_bf16 v[96:99], v[180:183], v[196:199], v[96:99]
	v_mfma_f32_16x16x32_bf16 v[84:87], v[164:167], v[206:209], v[84:87]
	v_mfma_f32_16x16x32_bf16 v[80:83], v[180:183], v[206:209], v[80:83]
	v_mfma_f32_16x16x32_bf16 v[68:71], v[164:167], v[214:217], v[68:71]
	v_mfma_f32_16x16x32_bf16 v[64:67], v[180:183], v[214:217], v[64:67]
	s_barrier
	s_setprio 0
	s_add_i32 s42, s88, s33
	v_lshl_add_u64 v[172:173], v[172:173], 0, s[10:11]
	s_mov_b32 m0, s42
	ds_read_b128 v[184:187], v179 offset:49152
	ds_read_b128 v[188:191], v179 offset:50176
	ds_read_b128 v[192:195], v179 offset:51200
	ds_read_b128 v[196:199], v179 offset:52224
	ds_read_b128 v[202:205], v179 offset:53248
	ds_read_b128 v[206:209], v179 offset:54272
	ds_read_b128 v[210:213], v179 offset:55296
	ds_read_b128 v[214:217], v179 offset:56320
	global_load_lds_dwordx4 v[172:173], off
	s_add_i32 m0, s42, 0x2000
	s_add_u32 s40, s40, 0x40080
	v_lshl_add_u64 v[172:173], v[218:219], 0, s[10:11]
	s_addc_u32 s41, s41, 0
	s_add_i32 s42, s89, s33
	global_load_lds_dwordx4 v[172:173], off
	s_mov_b32 m0, s42
	s_nop 0
	global_load_lds_dwordx4 v148, s[40:41]
	s_add_i32 m0, s42, 0x2000
	s_nop 0
	global_load_lds_dwordx4 v144, s[40:41]
	v_lshl_add_u64 v[172:173], v[220:221], 0, s[10:11]
	s_mov_b32 m0, s55
	s_nop 0
	global_load_lds_dwordx4 v[172:173], off
	v_lshl_add_u64 v[172:173], v[222:223], 0, s[10:11]
	s_mov_b32 m0, s56
	s_nop 0
	global_load_lds_dwordx4 v[172:173], off
	s_waitcnt vmcnt(8)
	s_waitcnt lgkmcnt(0)
	s_setprio 1
	s_barrier
	v_mfma_f32_16x16x32_bf16 v[60:63], v[128:131], v[184:187], v[60:63]
	v_mfma_f32_16x16x32_bf16 v[56:59], v[136:139], v[184:187], v[56:59]
	v_mfma_f32_16x16x32_bf16 v[44:47], v[128:131], v[192:195], v[44:47]
	v_mfma_f32_16x16x32_bf16 v[40:43], v[136:139], v[192:195], v[40:43]
	v_mfma_f32_16x16x32_bf16 v[28:31], v[128:131], v[202:205], v[28:31]
	v_mfma_f32_16x16x32_bf16 v[24:27], v[136:139], v[202:205], v[24:27]
	v_mfma_f32_16x16x32_bf16 v[12:15], v[128:131], v[210:213], v[12:15]
	v_mfma_f32_16x16x32_bf16 v[8:11], v[136:139], v[210:213], v[8:11]
	v_mfma_f32_16x16x32_bf16 v[60:63], v[132:135], v[188:191], v[60:63]
	v_mfma_f32_16x16x32_bf16 v[56:59], v[140:143], v[188:191], v[56:59]
	v_mfma_f32_16x16x32_bf16 v[44:47], v[132:135], v[196:199], v[44:47]
	v_mfma_f32_16x16x32_bf16 v[40:43], v[140:143], v[196:199], v[40:43]
	v_mfma_f32_16x16x32_bf16 v[28:31], v[132:135], v[206:209], v[28:31]
	v_mfma_f32_16x16x32_bf16 v[24:27], v[140:143], v[206:209], v[24:27]
	v_mfma_f32_16x16x32_bf16 v[12:15], v[132:135], v[214:217], v[12:15]
	v_mfma_f32_16x16x32_bf16 v[8:11], v[140:143], v[214:217], v[8:11]
	v_mfma_f32_16x16x32_bf16 v[52:55], v[160:163], v[184:187], v[52:55]
	v_mfma_f32_16x16x32_bf16 v[48:51], v[168:171], v[184:187], v[48:51]
	v_mfma_f32_16x16x32_bf16 v[36:39], v[160:163], v[192:195], v[36:39]
	v_mfma_f32_16x16x32_bf16 v[32:35], v[168:171], v[192:195], v[32:35]
	v_mfma_f32_16x16x32_bf16 v[20:23], v[160:163], v[202:205], v[20:23]
	v_mfma_f32_16x16x32_bf16 v[16:19], v[168:171], v[202:205], v[16:19]
	v_mfma_f32_16x16x32_bf16 v[4:7], v[160:163], v[210:213], v[4:7]
	v_mfma_f32_16x16x32_bf16 v[0:3], v[168:171], v[210:213], v[0:3]
	v_mfma_f32_16x16x32_bf16 v[52:55], v[164:167], v[188:191], v[52:55]
	v_mfma_f32_16x16x32_bf16 v[48:51], v[180:183], v[188:191], v[48:51]
	v_mfma_f32_16x16x32_bf16 v[36:39], v[164:167], v[196:199], v[36:39]
	v_mfma_f32_16x16x32_bf16 v[32:35], v[180:183], v[196:199], v[32:35]
	v_mfma_f32_16x16x32_bf16 v[20:23], v[164:167], v[206:209], v[20:23]
	v_mfma_f32_16x16x32_bf16 v[16:19], v[180:183], v[206:209], v[16:19]
	v_mfma_f32_16x16x32_bf16 v[4:7], v[164:167], v[214:217], v[4:7]
	v_mfma_f32_16x16x32_bf16 v[0:3], v[180:183], v[214:217], v[0:3]
	s_barrier
	s_setprio 0
	s_add_u32 s38, s38, 0x100
	s_addc_u32 s39, s39, 0
	s_add_u32 s85, s85, 0x100
	s_addc_u32 s86, s86, 0
	s_cmp_ge_i32 s87, s26
	s_mov_b32 s40, s87
	s_cbranch_scc0 .LBB7_327
	s_branch .Lpeelx_327
	.p2align	8

.Lswi_nobar:
.Lpeel_357:
	s_add_i32 s86, s42, 2
	s_add_u32 s29, s16, 0xfffc0080
	s_addc_u32 s37, s17, -1
	s_add_i32 s74, 0, 0x10000
	s_cmp_eq_u32 s20, s42
	s_cselect_b32 s73, s9, s37
	s_cselect_b32 s72, s13, s29
	v_add_u32_e32 v170, s74, v179
	s_cselect_b32 s43, s28, s57
	s_cselect_b32 s42, s39, s56
	s_add_i32 s29, 0, 0x14000
	ds_read_b128 v[130:133], v170
	ds_read_b128 v[180:183], v170 offset:1024
	ds_read_b128 v[184:187], v170 offset:2048
	ds_read_b128 v[188:191], v170 offset:3072
	v_add_u32_e32 v170, s29, v179
	ds_read_b128 v[192:195], v170
	ds_read_b128 v[196:199], v170 offset:1024
	ds_read_b128 v[204:207], v170 offset:2048
	ds_read_b128 v[208:211], v170 offset:3072
	s_add_i32 m0, s4, 0xc000
	ds_read_b128 v[212:215], v143
	ds_read_b128 v[216:219], v143 offset:1024
	ds_read_b128 v[220:223], v143 offset:2048
	ds_read_b128 v[224:227], v143 offset:3072
	ds_read_b128 v[228:231], v143 offset:4096
	ds_read_b128 v[232:235], v143 offset:5120
	ds_read_b128 v[236:239], v143 offset:6144
	ds_read_b128 v[240:243], v143 offset:7168
	global_load_lds_dwordx4 v174, s[16:17]
	s_add_i32 m0, s4, 0xe000
	s_nop 0
	global_load_lds_dwordx4 v176, s[16:17]
	s_waitcnt vmcnt(8)
	s_waitcnt lgkmcnt(0)
	s_setprio 1
	s_barrier
	v_mfma_f32_16x16x32_bf16 v[126:129], v[130:133], v[212:215], 0
	v_mfma_f32_16x16x32_bf16 v[118:121], v[184:187], v[212:215], 0
	v_mfma_f32_16x16x32_bf16 v[110:113], v[130:133], v[220:223], 0
	v_mfma_f32_16x16x32_bf16 v[102:105], v[184:187], v[220:223], 0
	v_mfma_f32_16x16x32_bf16 v[94:97], v[130:133], v[228:231], 0
	v_mfma_f32_16x16x32_bf16 v[86:89], v[184:187], v[228:231], 0
	v_mfma_f32_16x16x32_bf16 v[78:81], v[130:133], v[236:239], 0
	v_mfma_f32_16x16x32_bf16 v[70:73], v[184:187], v[236:239], 0
	v_mfma_f32_16x16x32_bf16 v[126:129], v[180:183], v[216:219], v[126:129]
	v_mfma_f32_16x16x32_bf16 v[118:121], v[188:191], v[216:219], v[118:121]
	v_mfma_f32_16x16x32_bf16 v[110:113], v[180:183], v[224:227], v[110:113]
	v_mfma_f32_16x16x32_bf16 v[102:105], v[188:191], v[224:227], v[102:105]
	v_mfma_f32_16x16x32_bf16 v[94:97], v[180:183], v[232:235], v[94:97]
	v_mfma_f32_16x16x32_bf16 v[86:89], v[188:191], v[232:235], v[86:89]
	v_mfma_f32_16x16x32_bf16 v[78:81], v[180:183], v[240:243], v[78:81]
	v_mfma_f32_16x16x32_bf16 v[70:73], v[188:191], v[240:243], v[70:73]
	v_mfma_f32_16x16x32_bf16 v[122:125], v[192:195], v[212:215], 0
	v_mfma_f32_16x16x32_bf16 v[114:117], v[204:207], v[212:215], 0
	v_mfma_f32_16x16x32_bf16 v[106:109], v[192:195], v[220:223], 0
	v_mfma_f32_16x16x32_bf16 v[98:101], v[204:207], v[220:223], 0
	v_mfma_f32_16x16x32_bf16 v[90:93], v[192:195], v[228:231], 0
	v_mfma_f32_16x16x32_bf16 v[82:85], v[204:207], v[228:231], 0
	v_mfma_f32_16x16x32_bf16 v[74:77], v[192:195], v[236:239], 0
	v_mfma_f32_16x16x32_bf16 v[66:69], v[204:207], v[236:239], 0
	v_mfma_f32_16x16x32_bf16 v[122:125], v[196:199], v[216:219], v[122:125]
	v_mfma_f32_16x16x32_bf16 v[114:117], v[208:211], v[216:219], v[114:117]
	v_mfma_f32_16x16x32_bf16 v[106:109], v[196:199], v[224:227], v[106:109]
	v_mfma_f32_16x16x32_bf16 v[98:101], v[208:211], v[224:227], v[98:101]
	v_mfma_f32_16x16x32_bf16 v[90:93], v[196:199], v[232:235], v[90:93]
	v_mfma_f32_16x16x32_bf16 v[82:85], v[208:211], v[232:235], v[82:85]
	v_mfma_f32_16x16x32_bf16 v[74:77], v[196:199], v[240:243], v[74:77]
	v_mfma_f32_16x16x32_bf16 v[66:69], v[208:211], v[240:243], v[66:69]
	s_barrier
	s_setprio 0
	s_add_i32 s37, s74, s84
	v_lshl_add_u64 v[244:245], s[42:43], 0, v[138:139]
	s_mov_b32 m0, s37
	ds_read_b128 v[212:215], v143 offset:16384
	ds_read_b128 v[216:219], v143 offset:17408
	ds_read_b128 v[220:223], v143 offset:18432
	ds_read_b128 v[224:227], v143 offset:19456
	ds_read_b128 v[228:231], v143 offset:20480
	ds_read_b128 v[232:235], v143 offset:21504
	ds_read_b128 v[236:239], v143 offset:22528
	ds_read_b128 v[240:243], v143 offset:23552
	global_load_lds_dwordx4 v[244:245], off
	s_add_i32 m0, s37, 0x2000
	s_add_u32 s74, s42, 0x40000
	v_lshl_add_u64 v[246:247], s[42:43], 0, v[134:135]
	s_addc_u32 s75, s43, 0
	s_add_i32 s29, s29, s84
	global_load_lds_dwordx4 v[246:247], off
	s_mov_b32 m0, s29
	v_lshl_add_u64 v[170:171], s[72:73], 0, v[136:137]
	global_load_lds_dwordx4 v138, s[74:75]
	s_add_i32 m0, s29, 0x2000
	s_nop 0
	global_load_lds_dwordx4 v134, s[74:75]
	v_lshl_add_u64 v[248:249], s[72:73], 0, v[140:141]
	s_mov_b32 m0, s4
	s_nop 0
	global_load_lds_dwordx4 v[248:249], off
	s_mov_b32 m0, s5
	s_nop 0
	global_load_lds_dwordx4 v[170:171], off
	s_lshl_b32 s101, s38, 14
	s_add_i32 s101, s101, s84
	s_add_u32 s100, s66, s101
	s_addc_u32 s101, s67, 0
	v_lshlrev_b32_e32 v172, 4, v163
	v_add_u32_e32 v173, 0x2000, v172
	s_add_i32 m0, s84, 0x20000
	s_nop 0
	global_load_lds_dwordx4 v172, s[100:101]
	s_add_i32 m0, s84, 0x22000
	s_nop 0
	global_load_lds_dwordx4 v173, s[100:101]
	s_waitcnt vmcnt(8)
	s_waitcnt lgkmcnt(0)
	s_setprio 1
	s_barrier
	v_mfma_f32_16x16x32_bf16 v[62:65], v[130:133], v[212:215], 0
	v_mfma_f32_16x16x32_bf16 v[54:57], v[184:187], v[212:215], 0
	v_mfma_f32_16x16x32_bf16 v[46:49], v[130:133], v[220:223], 0
	v_mfma_f32_16x16x32_bf16 v[38:41], v[184:187], v[220:223], 0
	v_mfma_f32_16x16x32_bf16 v[30:33], v[130:133], v[228:231], 0
	v_mfma_f32_16x16x32_bf16 v[22:25], v[184:187], v[228:231], 0
	v_mfma_f32_16x16x32_bf16 v[14:17], v[130:133], v[236:239], 0
	v_mfma_f32_16x16x32_bf16 v[6:9], v[184:187], v[236:239], 0
	v_mfma_f32_16x16x32_bf16 v[62:65], v[180:183], v[216:219], v[62:65]
	v_mfma_f32_16x16x32_bf16 v[54:57], v[188:191], v[216:219], v[54:57]
	v_mfma_f32_16x16x32_bf16 v[46:49], v[180:183], v[224:227], v[46:49]
	v_mfma_f32_16x16x32_bf16 v[38:41], v[188:191], v[224:227], v[38:41]
	v_mfma_f32_16x16x32_bf16 v[30:33], v[180:183], v[232:235], v[30:33]
	v_mfma_f32_16x16x32_bf16 v[22:25], v[188:191], v[232:235], v[22:25]
	v_mfma_f32_16x16x32_bf16 v[14:17], v[180:183], v[240:243], v[14:17]
	v_mfma_f32_16x16x32_bf16 v[6:9], v[188:191], v[240:243], v[6:9]
	v_mfma_f32_16x16x32_bf16 v[58:61], v[192:195], v[212:215], 0
	v_mfma_f32_16x16x32_bf16 v[50:53], v[204:207], v[212:215], 0
	v_mfma_f32_16x16x32_bf16 v[42:45], v[192:195], v[220:223], 0
	v_mfma_f32_16x16x32_bf16 v[34:37], v[204:207], v[220:223], 0
	v_mfma_f32_16x16x32_bf16 v[26:29], v[192:195], v[228:231], 0
	v_mfma_f32_16x16x32_bf16 v[18:21], v[204:207], v[228:231], 0
	v_mfma_f32_16x16x32_bf16 v[10:13], v[192:195], v[236:239], 0
	v_mfma_f32_16x16x32_bf16 v[2:5], v[204:207], v[236:239], 0
	v_mfma_f32_16x16x32_bf16 v[58:61], v[196:199], v[216:219], v[58:61]
	v_mfma_f32_16x16x32_bf16 v[50:53], v[208:211], v[216:219], v[50:53]
	v_mfma_f32_16x16x32_bf16 v[42:45], v[196:199], v[224:227], v[42:45]
	v_mfma_f32_16x16x32_bf16 v[34:37], v[208:211], v[224:227], v[34:37]
	v_mfma_f32_16x16x32_bf16 v[26:29], v[196:199], v[232:235], v[26:29]
	v_mfma_f32_16x16x32_bf16 v[18:21], v[208:211], v[232:235], v[18:21]
	v_mfma_f32_16x16x32_bf16 v[10:13], v[196:199], v[240:243], v[10:13]
	v_mfma_f32_16x16x32_bf16 v[2:5], v[208:211], v[240:243], v[2:5]
	s_barrier
	s_setprio 0
	s_add_i32 s29, 0, 0x18000
	v_add_u32_e32 v172, s29, v179
	s_add_i32 s37, 0, 0x1c000
	ds_read_b128 v[130:133], v172
	ds_read_b128 v[180:183], v172 offset:1024
	ds_read_b128 v[184:187], v172 offset:2048
	ds_read_b128 v[188:191], v172 offset:3072
	v_add_u32_e32 v172, s37, v179
	ds_read_b128 v[192:195], v172
	ds_read_b128 v[196:199], v172 offset:1024
	ds_read_b128 v[204:207], v172 offset:2048
	ds_read_b128 v[208:211], v172 offset:3072
	s_add_u32 s72, s72, 0x40000
	s_addc_u32 s73, s73, 0
	s_mov_b32 m0, s93
	ds_read_b128 v[212:215], v143 offset:32768
	ds_read_b128 v[216:219], v143 offset:33792
	ds_read_b128 v[220:223], v143 offset:34816
	ds_read_b128 v[224:227], v143 offset:35840
	ds_read_b128 v[228:231], v143 offset:36864
	ds_read_b128 v[232:235], v143 offset:37888
	ds_read_b128 v[236:239], v143 offset:38912
	ds_read_b128 v[240:243], v143 offset:39936
	global_load_lds_dwordx4 v140, s[72:73]
	s_mov_b32 m0, s33
	s_nop 0
	global_load_lds_dwordx4 v136, s[72:73]
	s_waitcnt vmcnt(8)
	s_waitcnt lgkmcnt(0)
	s_setprio 1
	s_barrier
	v_mfma_f32_16x16x32_bf16 v[126:129], v[130:133], v[212:215], v[126:129]
	v_mfma_f32_16x16x32_bf16 v[118:121], v[184:187], v[212:215], v[118:121]
	v_mfma_f32_16x16x32_bf16 v[110:113], v[130:133], v[220:223], v[110:113]
	v_mfma_f32_16x16x32_bf16 v[102:105], v[184:187], v[220:223], v[102:105]
	v_mfma_f32_16x16x32_bf16 v[94:97], v[130:133], v[228:231], v[94:97]
	v_mfma_f32_16x16x32_bf16 v[86:89], v[184:187], v[228:231], v[86:89]
	v_mfma_f32_16x16x32_bf16 v[78:81], v[130:133], v[236:239], v[78:81]
	v_mfma_f32_16x16x32_bf16 v[70:73], v[184:187], v[236:239], v[70:73]
	v_mfma_f32_16x16x32_bf16 v[126:129], v[180:183], v[216:219], v[126:129]
	v_mfma_f32_16x16x32_bf16 v[118:121], v[188:191], v[216:219], v[118:121]
	v_mfma_f32_16x16x32_bf16 v[110:113], v[180:183], v[224:227], v[110:113]
	v_mfma_f32_16x16x32_bf16 v[102:105], v[188:191], v[224:227], v[102:105]
	v_mfma_f32_16x16x32_bf16 v[94:97], v[180:183], v[232:235], v[94:97]
	v_mfma_f32_16x16x32_bf16 v[86:89], v[188:191], v[232:235], v[86:89]
	v_mfma_f32_16x16x32_bf16 v[78:81], v[180:183], v[240:243], v[78:81]
	v_mfma_f32_16x16x32_bf16 v[70:73], v[188:191], v[240:243], v[70:73]
	v_mfma_f32_16x16x32_bf16 v[122:125], v[192:195], v[212:215], v[122:125]
	v_mfma_f32_16x16x32_bf16 v[114:117], v[204:207], v[212:215], v[114:117]
	v_mfma_f32_16x16x32_bf16 v[106:109], v[192:195], v[220:223], v[106:109]
	v_mfma_f32_16x16x32_bf16 v[98:101], v[204:207], v[220:223], v[98:101]
	v_mfma_f32_16x16x32_bf16 v[90:93], v[192:195], v[228:231], v[90:93]
	v_mfma_f32_16x16x32_bf16 v[82:85], v[204:207], v[228:231], v[82:85]
	v_mfma_f32_16x16x32_bf16 v[74:77], v[192:195], v[236:239], v[74:77]
	v_mfma_f32_16x16x32_bf16 v[66:69], v[204:207], v[236:239], v[66:69]
	v_mfma_f32_16x16x32_bf16 v[122:125], v[196:199], v[216:219], v[122:125]
	v_mfma_f32_16x16x32_bf16 v[114:117], v[208:211], v[216:219], v[114:117]
	v_mfma_f32_16x16x32_bf16 v[106:109], v[196:199], v[224:227], v[106:109]
	v_mfma_f32_16x16x32_bf16 v[98:101], v[208:211], v[224:227], v[98:101]
	v_mfma_f32_16x16x32_bf16 v[90:93], v[196:199], v[232:235], v[90:93]
	v_mfma_f32_16x16x32_bf16 v[82:85], v[208:211], v[232:235], v[82:85]
	v_mfma_f32_16x16x32_bf16 v[74:77], v[196:199], v[240:243], v[74:77]
	v_mfma_f32_16x16x32_bf16 v[66:69], v[208:211], v[240:243], v[66:69]
	s_barrier
	s_setprio 0
	s_add_i32 s29, s29, s84
	v_lshl_add_u64 v[172:173], v[244:245], 0, s[24:25]
	s_mov_b32 m0, s29
	ds_read_b128 v[212:215], v143 offset:49152
	ds_read_b128 v[216:219], v143 offset:50176
	ds_read_b128 v[220:223], v143 offset:51200
	ds_read_b128 v[224:227], v143 offset:52224
	ds_read_b128 v[228:231], v143 offset:53248
	ds_read_b128 v[232:235], v143 offset:54272
	ds_read_b128 v[236:239], v143 offset:55296
	ds_read_b128 v[240:243], v143 offset:56320
	global_load_lds_dwordx4 v[172:173], off
	s_add_i32 m0, s29, 0x2000
	s_add_u32 s42, s42, 0x40080
	v_lshl_add_u64 v[172:173], v[246:247], 0, s[24:25]
	s_addc_u32 s43, s43, 0
	s_add_i32 s29, s37, s84
	global_load_lds_dwordx4 v[172:173], off
	s_mov_b32 m0, s29
	v_lshl_add_u64 v[170:171], v[170:171], 0, s[24:25]
	global_load_lds_dwordx4 v138, s[42:43]
	s_add_i32 m0, s29, 0x2000
	s_nop 0
	global_load_lds_dwordx4 v134, s[42:43]
	v_lshl_add_u64 v[172:173], v[248:249], 0, s[24:25]
	s_mov_b32 m0, s97
	s_nop 0
	global_load_lds_dwordx4 v[172:173], off
	s_mov_b32 m0, s3
	s_nop 0
	global_load_lds_dwordx4 v[170:171], off
	s_waitcnt vmcnt(8)
	s_waitcnt lgkmcnt(0)
	s_setprio 1
	s_barrier
	v_mfma_f32_16x16x32_bf16 v[62:65], v[130:133], v[212:215], v[62:65]
	v_mfma_f32_16x16x32_bf16 v[54:57], v[184:187], v[212:215], v[54:57]
	v_mfma_f32_16x16x32_bf16 v[46:49], v[130:133], v[220:223], v[46:49]
	v_mfma_f32_16x16x32_bf16 v[38:41], v[184:187], v[220:223], v[38:41]
	v_mfma_f32_16x16x32_bf16 v[30:33], v[130:133], v[228:231], v[30:33]
	v_mfma_f32_16x16x32_bf16 v[22:25], v[184:187], v[228:231], v[22:25]
	v_mfma_f32_16x16x32_bf16 v[14:17], v[130:133], v[236:239], v[14:17]
	v_mfma_f32_16x16x32_bf16 v[6:9], v[184:187], v[236:239], v[6:9]
	v_mfma_f32_16x16x32_bf16 v[62:65], v[180:183], v[216:219], v[62:65]
	v_mfma_f32_16x16x32_bf16 v[54:57], v[188:191], v[216:219], v[54:57]
	v_mfma_f32_16x16x32_bf16 v[46:49], v[180:183], v[224:227], v[46:49]
	v_mfma_f32_16x16x32_bf16 v[38:41], v[188:191], v[224:227], v[38:41]
	v_mfma_f32_16x16x32_bf16 v[30:33], v[180:183], v[232:235], v[30:33]
	v_mfma_f32_16x16x32_bf16 v[22:25], v[188:191], v[232:235], v[22:25]
	v_mfma_f32_16x16x32_bf16 v[14:17], v[180:183], v[240:243], v[14:17]
	v_mfma_f32_16x16x32_bf16 v[6:9], v[188:191], v[240:243], v[6:9]
	v_mfma_f32_16x16x32_bf16 v[58:61], v[192:195], v[212:215], v[58:61]
	v_mfma_f32_16x16x32_bf16 v[50:53], v[204:207], v[212:215], v[50:53]
	v_mfma_f32_16x16x32_bf16 v[42:45], v[192:195], v[220:223], v[42:45]
	v_mfma_f32_16x16x32_bf16 v[34:37], v[204:207], v[220:223], v[34:37]
	v_mfma_f32_16x16x32_bf16 v[26:29], v[192:195], v[228:231], v[26:29]
	v_mfma_f32_16x16x32_bf16 v[18:21], v[204:207], v[228:231], v[18:21]
	v_mfma_f32_16x16x32_bf16 v[10:13], v[192:195], v[236:239], v[10:13]
	v_mfma_f32_16x16x32_bf16 v[2:5], v[204:207], v[236:239], v[2:5]
	v_mfma_f32_16x16x32_bf16 v[58:61], v[196:199], v[216:219], v[58:61]
	v_mfma_f32_16x16x32_bf16 v[50:53], v[208:211], v[216:219], v[50:53]
	v_mfma_f32_16x16x32_bf16 v[42:45], v[196:199], v[224:227], v[42:45]
	v_mfma_f32_16x16x32_bf16 v[34:37], v[208:211], v[224:227], v[34:37]
	v_mfma_f32_16x16x32_bf16 v[26:29], v[196:199], v[232:235], v[26:29]
	v_mfma_f32_16x16x32_bf16 v[18:21], v[208:211], v[232:235], v[18:21]
	v_mfma_f32_16x16x32_bf16 v[10:13], v[196:199], v[240:243], v[10:13]
	v_mfma_f32_16x16x32_bf16 v[2:5], v[208:211], v[240:243], v[2:5]
	s_barrier
	s_setprio 0
	s_lshl_b32 s100, s84, 1
	v_lshl_add_u32 v204, v163, 5, s100
	v_add_u32_e32 v204, 0x20000, v204
	ds_read_b128 v[208:211], v204
	ds_read_b128 v[212:215], v204 offset:16
	s_waitcnt lgkmcnt(0)
	v_add_f32_e32 v208, v208, v209
	v_add_f32_e32 v210, v210, v211
	v_add_f32_e32 v212, v212, v213
	v_add_f32_e32 v214, v214, v215
	v_add_f32_e32 v208, v208, v210
	v_add_f32_e32 v212, v212, v214
	v_add_f32_e32 v208, v208, v212
	v_mov_b32_e32 v209, 0x358637bd
	s_nop 0
	v_add_f32_dpp v208, v208, v208 quad_perm:[1,0,3,2] row_mask:0xf bank_mask:0xf
	v_fmamk_f32 v208, v208, 0x3a800000, v209
	v_rsq_f32_e32 v209, v208
	s_nop 0
	v_mul_f32_e32 v209, 0xbfb8aa3b, v209
	ds_write_b64 v204, v[208:209]
	s_add_u32 s16, s16, 0x100
	s_addc_u32 s17, s17, 0
	s_add_u32 s56, s56, 0x100
	s_addc_u32 s57, s57, 0
	s_cmp_ge_i32 s86, s23
	s_mov_b32 s42, s86
	s_cbranch_scc0 .LBB7_357
	s_branch .Lpeelx_357
	.p2align	8

.Lpeel_434:
	s_add_i32 s75, s72, 2
	s_add_u32 s76, s16, 0x4000
	s_addc_u32 s73, s17, 0
	s_cmp_eq_u32 s3, s72
	s_cselect_b32 s72, s86, s76
	s_cselect_b32 s73, s20, s73
	s_cselect_b32 s84, s37, s29
	s_cselect_b32 s85, s87, s74
	s_add_u32 vcc_lo, s72, 0x8000
	s_addc_u32 vcc_hi, s73, 0
	s_add_i32 s76, 0, 0x10000
	v_add_u32_e32 v0, s76, v205
	s_add_i32 s91, 0, 0x14000
	ds_read_b128 v[132:135], v0
	ds_read_b128 v[136:139], v0 offset:1024
	ds_read_b128 v[140:143], v0 offset:2048
	ds_read_b128 v[144:147], v0 offset:3072
	v_add_u32_e32 v0, s91, v205
	ds_read_b128 v[148:151], v0
	ds_read_b128 v[152:155], v0 offset:1024
	ds_read_b128 v[156:159], v0 offset:2048
	ds_read_b128 v[184:187], v0 offset:3072
	s_waitcnt lgkmcnt(0)
	s_add_i32 m0, s23, 0xc000
	ds_read_b128 v[188:191], v207
	ds_read_b128 v[192:195], v207 offset:1024
	ds_read_b128 v[196:199], v207 offset:2048
	ds_read_b128 v[208:211], v207 offset:3072
	ds_read_b128 v[212:215], v207 offset:4096
	ds_read_b128 v[216:219], v207 offset:5120
	ds_read_b128 v[220:223], v207 offset:6144
	ds_read_b128 v[224:227], v207 offset:7168
	global_load_lds_dwordx4 v180, s[16:17]
	s_add_i32 m0, s23, 0xe000
	s_nop 0
	global_load_lds_dwordx4 v182, s[16:17]
	s_waitcnt vmcnt(8)
	s_waitcnt lgkmcnt(0)
	s_setprio 1
	s_barrier
	v_mfma_f32_16x16x32_bf16 v[128:131], v[132:135], v[188:191], 0
	v_mfma_f32_16x16x32_bf16 v[124:127], v[140:143], v[188:191], 0
	v_mfma_f32_16x16x32_bf16 v[120:123], v[132:135], v[196:199], 0
	v_mfma_f32_16x16x32_bf16 v[116:119], v[140:143], v[196:199], 0
	v_mfma_f32_16x16x32_bf16 v[112:115], v[132:135], v[212:215], 0
	v_mfma_f32_16x16x32_bf16 v[108:111], v[140:143], v[212:215], 0
	v_mfma_f32_16x16x32_bf16 v[104:107], v[132:135], v[220:223], 0
	v_mfma_f32_16x16x32_bf16 v[100:103], v[140:143], v[220:223], 0
	v_mfma_f32_16x16x32_bf16 v[128:131], v[136:139], v[192:195], v[128:131]
	v_mfma_f32_16x16x32_bf16 v[124:127], v[144:147], v[192:195], v[124:127]
	v_mfma_f32_16x16x32_bf16 v[120:123], v[136:139], v[208:211], v[120:123]
	v_mfma_f32_16x16x32_bf16 v[116:119], v[144:147], v[208:211], v[116:119]
	v_mfma_f32_16x16x32_bf16 v[112:115], v[136:139], v[216:219], v[112:115]
	v_mfma_f32_16x16x32_bf16 v[108:111], v[144:147], v[216:219], v[108:111]
	v_mfma_f32_16x16x32_bf16 v[104:107], v[136:139], v[224:227], v[104:107]
	v_mfma_f32_16x16x32_bf16 v[100:103], v[144:147], v[224:227], v[100:103]
	v_mfma_f32_16x16x32_bf16 v[96:99], v[148:151], v[188:191], 0
	v_mfma_f32_16x16x32_bf16 v[92:95], v[156:159], v[188:191], 0
	v_mfma_f32_16x16x32_bf16 v[88:91], v[148:151], v[196:199], 0
	v_mfma_f32_16x16x32_bf16 v[84:87], v[156:159], v[196:199], 0
	v_mfma_f32_16x16x32_bf16 v[80:83], v[148:151], v[212:215], 0
	v_mfma_f32_16x16x32_bf16 v[76:79], v[156:159], v[212:215], 0
	v_mfma_f32_16x16x32_bf16 v[72:75], v[148:151], v[220:223], 0
	v_mfma_f32_16x16x32_bf16 v[64:67], v[156:159], v[220:223], 0
	v_mfma_f32_16x16x32_bf16 v[96:99], v[152:155], v[192:195], v[96:99]
	v_mfma_f32_16x16x32_bf16 v[92:95], v[184:187], v[192:195], v[92:95]
	v_mfma_f32_16x16x32_bf16 v[88:91], v[152:155], v[208:211], v[88:91]
	v_mfma_f32_16x16x32_bf16 v[84:87], v[184:187], v[208:211], v[84:87]
	v_mfma_f32_16x16x32_bf16 v[80:83], v[152:155], v[216:219], v[80:83]
	v_mfma_f32_16x16x32_bf16 v[76:79], v[184:187], v[216:219], v[76:79]
	v_mfma_f32_16x16x32_bf16 v[72:75], v[152:155], v[224:227], v[72:75]
	v_mfma_f32_16x16x32_bf16 v[64:67], v[184:187], v[224:227], v[64:67]
	s_barrier
	s_setprio 0
	s_add_i32 s76, s76, s4
	s_mov_b32 m0, s76
	ds_read_b128 v[188:191], v207 offset:16384
	ds_read_b128 v[192:195], v207 offset:17408
	ds_read_b128 v[196:199], v207 offset:18432
	ds_read_b128 v[208:211], v207 offset:19456
	ds_read_b128 v[212:215], v207 offset:20480
	ds_read_b128 v[216:219], v207 offset:21504
	ds_read_b128 v[220:223], v207 offset:22528
	ds_read_b128 v[224:227], v207 offset:23552
	global_load_lds_dwordx4 v176, s[84:85]
	s_add_i32 m0, s76, 0x2000
	s_add_u32 s76, s84, 0x4000
	s_addc_u32 s77, s85, 0
	s_add_i32 s91, s91, s4
	global_load_lds_dwordx4 v160, s[84:85]
	s_mov_b32 m0, s91
	s_nop 0
	global_load_lds_dwordx4 v176, s[76:77]
	s_add_i32 m0, s91, 0x2000
	s_nop 0
	global_load_lds_dwordx4 v160, s[76:77]
	s_mov_b32 m0, s23
	s_nop 0
	global_load_lds_dwordx4 v178, s[72:73]
	s_mov_b32 m0, s31
	s_nop 0
	global_load_lds_dwordx4 v174, s[72:73]
	s_waitcnt vmcnt(8)
	s_waitcnt lgkmcnt(0)
	s_setprio 1
	s_barrier
	v_mfma_f32_16x16x32_bf16 v[68:71], v[132:135], v[188:191], 0
	v_mfma_f32_16x16x32_bf16 v[60:63], v[140:143], v[188:191], 0
	v_mfma_f32_16x16x32_bf16 v[56:59], v[132:135], v[196:199], 0
	v_mfma_f32_16x16x32_bf16 v[52:55], v[140:143], v[196:199], 0
	v_mfma_f32_16x16x32_bf16 v[48:51], v[132:135], v[212:215], 0
	v_mfma_f32_16x16x32_bf16 v[44:47], v[140:143], v[212:215], 0
	v_mfma_f32_16x16x32_bf16 v[40:43], v[132:135], v[220:223], 0
	v_mfma_f32_16x16x32_bf16 v[36:39], v[140:143], v[220:223], 0
	v_mfma_f32_16x16x32_bf16 v[68:71], v[136:139], v[192:195], v[68:71]
	v_mfma_f32_16x16x32_bf16 v[60:63], v[144:147], v[192:195], v[60:63]
	v_mfma_f32_16x16x32_bf16 v[56:59], v[136:139], v[208:211], v[56:59]
	v_mfma_f32_16x16x32_bf16 v[52:55], v[144:147], v[208:211], v[52:55]
	v_mfma_f32_16x16x32_bf16 v[48:51], v[136:139], v[216:219], v[48:51]
	v_mfma_f32_16x16x32_bf16 v[44:47], v[144:147], v[216:219], v[44:47]
	v_mfma_f32_16x16x32_bf16 v[40:43], v[136:139], v[224:227], v[40:43]
	v_mfma_f32_16x16x32_bf16 v[36:39], v[144:147], v[224:227], v[36:39]
	v_mfma_f32_16x16x32_bf16 v[32:35], v[148:151], v[188:191], 0
	v_mfma_f32_16x16x32_bf16 v[28:31], v[156:159], v[188:191], 0
	v_mfma_f32_16x16x32_bf16 v[24:27], v[148:151], v[196:199], 0
	v_mfma_f32_16x16x32_bf16 v[20:23], v[156:159], v[196:199], 0
	v_mfma_f32_16x16x32_bf16 v[16:19], v[148:151], v[212:215], 0
	v_mfma_f32_16x16x32_bf16 v[12:15], v[156:159], v[212:215], 0
	v_mfma_f32_16x16x32_bf16 v[8:11], v[148:151], v[220:223], 0
	v_mfma_f32_16x16x32_bf16 v[2:5], v[156:159], v[220:223], 0
	v_mfma_f32_16x16x32_bf16 v[32:35], v[152:155], v[192:195], v[32:35]
	v_mfma_f32_16x16x32_bf16 v[28:31], v[184:187], v[192:195], v[28:31]
	v_mfma_f32_16x16x32_bf16 v[24:27], v[152:155], v[208:211], v[24:27]
	v_mfma_f32_16x16x32_bf16 v[20:23], v[184:187], v[208:211], v[20:23]
	v_mfma_f32_16x16x32_bf16 v[16:19], v[152:155], v[216:219], v[16:19]
	v_mfma_f32_16x16x32_bf16 v[12:15], v[184:187], v[216:219], v[12:15]
	v_mfma_f32_16x16x32_bf16 v[8:11], v[152:155], v[224:227], v[8:11]
	v_mfma_f32_16x16x32_bf16 v[2:5], v[184:187], v[224:227], v[2:5]
	s_barrier
	s_setprio 0
	s_add_i32 s76, 0, 0x18000
	v_add_u32_e32 v0, s76, v205
	s_add_i32 s77, 0, 0x1c000
	ds_read_b128 v[132:135], v0
	ds_read_b128 v[136:139], v0 offset:1024
	ds_read_b128 v[140:143], v0 offset:2048
	ds_read_b128 v[144:147], v0 offset:3072
	v_add_u32_e32 v0, s77, v205
	ds_read_b128 v[148:151], v0
	ds_read_b128 v[152:155], v0 offset:1024
	ds_read_b128 v[156:159], v0 offset:2048
	ds_read_b128 v[184:187], v0 offset:3072
	s_add_u32 s72, s72, 0x4000
	s_addc_u32 s73, s73, 0
	s_mov_b32 m0, s33
	ds_read_b128 v[188:191], v207 offset:32768
	ds_read_b128 v[192:195], v207 offset:33792
	ds_read_b128 v[196:199], v207 offset:34816
	ds_read_b128 v[208:211], v207 offset:35840
	ds_read_b128 v[212:215], v207 offset:36864
	ds_read_b128 v[216:219], v207 offset:37888
	ds_read_b128 v[220:223], v207 offset:38912
	ds_read_b128 v[224:227], v207 offset:39936
	global_load_lds_dwordx4 v178, s[72:73]
	s_mov_b32 m0, s93
	s_nop 0
	global_load_lds_dwordx4 v174, s[72:73]
	s_waitcnt vmcnt(8)
	s_waitcnt lgkmcnt(0)
	s_setprio 1
	s_barrier
	v_mfma_f32_16x16x32_bf16 v[128:131], v[132:135], v[188:191], v[128:131]
	v_mfma_f32_16x16x32_bf16 v[124:127], v[140:143], v[188:191], v[124:127]
	v_mfma_f32_16x16x32_bf16 v[120:123], v[132:135], v[196:199], v[120:123]
	v_mfma_f32_16x16x32_bf16 v[116:119], v[140:143], v[196:199], v[116:119]
	v_mfma_f32_16x16x32_bf16 v[112:115], v[132:135], v[212:215], v[112:115]
	v_mfma_f32_16x16x32_bf16 v[108:111], v[140:143], v[212:215], v[108:111]
	v_mfma_f32_16x16x32_bf16 v[104:107], v[132:135], v[220:223], v[104:107]
	v_mfma_f32_16x16x32_bf16 v[100:103], v[140:143], v[220:223], v[100:103]
	v_mfma_f32_16x16x32_bf16 v[128:131], v[136:139], v[192:195], v[128:131]
	v_mfma_f32_16x16x32_bf16 v[124:127], v[144:147], v[192:195], v[124:127]
	v_mfma_f32_16x16x32_bf16 v[120:123], v[136:139], v[208:211], v[120:123]
	v_mfma_f32_16x16x32_bf16 v[116:119], v[144:147], v[208:211], v[116:119]
	v_mfma_f32_16x16x32_bf16 v[112:115], v[136:139], v[216:219], v[112:115]
	v_mfma_f32_16x16x32_bf16 v[108:111], v[144:147], v[216:219], v[108:111]
	v_mfma_f32_16x16x32_bf16 v[104:107], v[136:139], v[224:227], v[104:107]
	v_mfma_f32_16x16x32_bf16 v[100:103], v[144:147], v[224:227], v[100:103]
	v_mfma_f32_16x16x32_bf16 v[96:99], v[148:151], v[188:191], v[96:99]
	v_mfma_f32_16x16x32_bf16 v[92:95], v[156:159], v[188:191], v[92:95]
	v_mfma_f32_16x16x32_bf16 v[88:91], v[148:151], v[196:199], v[88:91]
	v_mfma_f32_16x16x32_bf16 v[84:87], v[156:159], v[196:199], v[84:87]
	v_mfma_f32_16x16x32_bf16 v[80:83], v[148:151], v[212:215], v[80:83]
	v_mfma_f32_16x16x32_bf16 v[76:79], v[156:159], v[212:215], v[76:79]
	v_mfma_f32_16x16x32_bf16 v[72:75], v[148:151], v[220:223], v[72:75]
	v_mfma_f32_16x16x32_bf16 v[64:67], v[156:159], v[220:223], v[64:67]
	v_mfma_f32_16x16x32_bf16 v[96:99], v[152:155], v[192:195], v[96:99]
	v_mfma_f32_16x16x32_bf16 v[92:95], v[184:187], v[192:195], v[92:95]
	v_mfma_f32_16x16x32_bf16 v[88:91], v[152:155], v[208:211], v[88:91]
	v_mfma_f32_16x16x32_bf16 v[84:87], v[184:187], v[208:211], v[84:87]
	v_mfma_f32_16x16x32_bf16 v[80:83], v[152:155], v[216:219], v[80:83]
	v_mfma_f32_16x16x32_bf16 v[76:79], v[184:187], v[216:219], v[76:79]
	v_mfma_f32_16x16x32_bf16 v[72:75], v[152:155], v[224:227], v[72:75]
	v_mfma_f32_16x16x32_bf16 v[64:67], v[184:187], v[224:227], v[64:67]
	s_barrier
	s_setprio 0
	s_add_u32 s72, s84, 0x8000
	s_addc_u32 s73, s85, 0
	s_add_i32 s76, s76, s4
	s_mov_b32 m0, s76
	ds_read_b128 v[188:191], v207 offset:49152
	ds_read_b128 v[192:195], v207 offset:50176
	ds_read_b128 v[196:199], v207 offset:51200
	ds_read_b128 v[208:211], v207 offset:52224
	ds_read_b128 v[212:215], v207 offset:53248
	ds_read_b128 v[216:219], v207 offset:54272
	ds_read_b128 v[220:223], v207 offset:55296
	ds_read_b128 v[224:227], v207 offset:56320
	global_load_lds_dwordx4 v176, s[72:73]
	s_add_i32 m0, s76, 0x2000
	v_lshl_add_u64 v[6:7], s[72:73], 0, v[160:161]
	s_add_u32 s72, s84, 0xc000
	s_addc_u32 s73, s85, 0
	s_add_i32 s76, s77, s4
	global_load_lds_dwordx4 v[6:7], off
	s_mov_b32 m0, s76
	s_nop 0
	global_load_lds_dwordx4 v176, s[72:73]
	s_add_i32 m0, s76, 0x2000
	s_nop 0
	global_load_lds_dwordx4 v160, s[72:73]
	s_mov_b32 m0, s97
	s_nop 0
	global_load_lds_dwordx4 v178, vcc
	s_mov_b32 m0, s38
	s_nop 0
	global_load_lds_dwordx4 v174, vcc
	s_waitcnt vmcnt(8)
	s_waitcnt lgkmcnt(0)
	s_setprio 1
	s_barrier
	v_mfma_f32_16x16x32_bf16 v[68:71], v[132:135], v[188:191], v[68:71]
	v_mfma_f32_16x16x32_bf16 v[60:63], v[140:143], v[188:191], v[60:63]
	v_mfma_f32_16x16x32_bf16 v[56:59], v[132:135], v[196:199], v[56:59]
	v_mfma_f32_16x16x32_bf16 v[52:55], v[140:143], v[196:199], v[52:55]
	v_mfma_f32_16x16x32_bf16 v[48:51], v[132:135], v[212:215], v[48:51]
	v_mfma_f32_16x16x32_bf16 v[44:47], v[140:143], v[212:215], v[44:47]
	v_mfma_f32_16x16x32_bf16 v[40:43], v[132:135], v[220:223], v[40:43]
	v_mfma_f32_16x16x32_bf16 v[36:39], v[140:143], v[220:223], v[36:39]
	v_mfma_f32_16x16x32_bf16 v[68:71], v[136:139], v[192:195], v[68:71]
	v_mfma_f32_16x16x32_bf16 v[60:63], v[144:147], v[192:195], v[60:63]
	v_mfma_f32_16x16x32_bf16 v[56:59], v[136:139], v[208:211], v[56:59]
	v_mfma_f32_16x16x32_bf16 v[52:55], v[144:147], v[208:211], v[52:55]
	v_mfma_f32_16x16x32_bf16 v[48:51], v[136:139], v[216:219], v[48:51]
	v_mfma_f32_16x16x32_bf16 v[44:47], v[144:147], v[216:219], v[44:47]
	v_mfma_f32_16x16x32_bf16 v[40:43], v[136:139], v[224:227], v[40:43]
	v_mfma_f32_16x16x32_bf16 v[36:39], v[144:147], v[224:227], v[36:39]
	v_mfma_f32_16x16x32_bf16 v[32:35], v[148:151], v[188:191], v[32:35]
	v_mfma_f32_16x16x32_bf16 v[28:31], v[156:159], v[188:191], v[28:31]
	v_mfma_f32_16x16x32_bf16 v[24:27], v[148:151], v[196:199], v[24:27]
	v_mfma_f32_16x16x32_bf16 v[20:23], v[156:159], v[196:199], v[20:23]
	v_mfma_f32_16x16x32_bf16 v[16:19], v[148:151], v[212:215], v[16:19]
	v_mfma_f32_16x16x32_bf16 v[12:15], v[156:159], v[212:215], v[12:15]
	v_mfma_f32_16x16x32_bf16 v[6:9], v[148:151], v[220:223], v[8:11]
	v_mfma_f32_16x16x32_bf16 v[2:5], v[156:159], v[220:223], v[2:5]
	v_mfma_f32_16x16x32_bf16 v[32:35], v[152:155], v[192:195], v[32:35]
	v_mfma_f32_16x16x32_bf16 v[28:31], v[184:187], v[192:195], v[28:31]
	v_mfma_f32_16x16x32_bf16 v[24:27], v[152:155], v[208:211], v[24:27]
	v_mfma_f32_16x16x32_bf16 v[20:23], v[184:187], v[208:211], v[20:23]
	v_mfma_f32_16x16x32_bf16 v[16:19], v[152:155], v[216:219], v[16:19]
	v_mfma_f32_16x16x32_bf16 v[12:15], v[184:187], v[216:219], v[12:15]
	v_mfma_f32_16x16x32_bf16 v[8:11], v[152:155], v[224:227], v[6:9]
	v_mfma_f32_16x16x32_bf16 v[4:7], v[184:187], v[224:227], v[2:5]
	s_barrier
	s_setprio 0
	s_add_u32 s29, s29, 0x10000
	s_addc_u32 s74, s74, 0
	s_add_u32 s16, s16, 0x10000
	s_addc_u32 s17, s17, 0
	s_cmp_ge_i32 s75, s39
	s_mov_b32 s72, s75
	s_cbranch_scc0 .LBB7_434
	s_branch .Lpeelx_434
	.p2align	8

.Lpeel_523:
	s_add_i32 s56, s42, 2
	s_add_u32 s29, s16, 0xfffc0080
	s_addc_u32 s37, s17, -1
	s_add_i32 s57, 0, 0x10000
	s_cmp_eq_u32 s84, s42
	s_cselect_b32 s45, s13, s37
	s_cselect_b32 s44, s15, s29
	v_add_u32_e32 v0, s57, v195
	s_cselect_b32 s43, s38, s49
	s_cselect_b32 s42, s39, s48
	s_add_i32 s29, 0, 0x14000
	ds_read_b128 v[130:133], v0
	ds_read_b128 v[150:153], v0 offset:1024
	ds_read_b128 v[154:157], v0 offset:2048
	ds_read_b128 v[158:161], v0 offset:3072
	v_add_u32_e32 v0, s29, v195
	ds_read_b128 v[174:177], v0
	ds_read_b128 v[178:181], v0 offset:1024
	ds_read_b128 v[182:185], v0 offset:2048
	ds_read_b128 v[186:189], v0 offset:3072
	s_add_i32 m0, s5, 0xc000
	ds_read_b128 v[190:193], v196
	ds_read_b128 v[204:207], v196 offset:1024
	ds_read_b128 v[208:211], v196 offset:2048
	ds_read_b128 v[212:215], v196 offset:3072
	ds_read_b128 v[216:219], v196 offset:4096
	ds_read_b128 v[220:223], v196 offset:5120
	ds_read_b128 v[224:227], v196 offset:6144
	ds_read_b128 v[228:231], v196 offset:7168
	global_load_lds_dwordx4 v146, s[16:17]
	s_add_i32 m0, s5, 0xe000
	s_nop 0
	global_load_lds_dwordx4 v148, s[16:17]
	s_waitcnt vmcnt(8)
	s_waitcnt lgkmcnt(0)
	s_setprio 1
	s_barrier
	v_mfma_f32_16x16x32_bf16 v[126:129], v[130:133], v[190:193], 0
	v_mfma_f32_16x16x32_bf16 v[122:125], v[154:157], v[190:193], 0
	v_mfma_f32_16x16x32_bf16 v[110:113], v[130:133], v[208:211], 0
	v_mfma_f32_16x16x32_bf16 v[106:109], v[154:157], v[208:211], 0
	v_mfma_f32_16x16x32_bf16 v[94:97], v[130:133], v[216:219], 0
	v_mfma_f32_16x16x32_bf16 v[90:93], v[154:157], v[216:219], 0
	v_mfma_f32_16x16x32_bf16 v[78:81], v[130:133], v[224:227], 0
	v_mfma_f32_16x16x32_bf16 v[74:77], v[154:157], v[224:227], 0
	v_mfma_f32_16x16x32_bf16 v[126:129], v[150:153], v[204:207], v[126:129]
	v_mfma_f32_16x16x32_bf16 v[122:125], v[158:161], v[204:207], v[122:125]
	v_mfma_f32_16x16x32_bf16 v[110:113], v[150:153], v[212:215], v[110:113]
	v_mfma_f32_16x16x32_bf16 v[106:109], v[158:161], v[212:215], v[106:109]
	v_mfma_f32_16x16x32_bf16 v[94:97], v[150:153], v[220:223], v[94:97]
	v_mfma_f32_16x16x32_bf16 v[90:93], v[158:161], v[220:223], v[90:93]
	v_mfma_f32_16x16x32_bf16 v[78:81], v[150:153], v[228:231], v[78:81]
	v_mfma_f32_16x16x32_bf16 v[74:77], v[158:161], v[228:231], v[74:77]
	v_mfma_f32_16x16x32_bf16 v[118:121], v[174:177], v[190:193], 0
	v_mfma_f32_16x16x32_bf16 v[114:117], v[182:185], v[190:193], 0
	v_mfma_f32_16x16x32_bf16 v[102:105], v[174:177], v[208:211], 0
	v_mfma_f32_16x16x32_bf16 v[98:101], v[182:185], v[208:211], 0
	v_mfma_f32_16x16x32_bf16 v[86:89], v[174:177], v[216:219], 0
	v_mfma_f32_16x16x32_bf16 v[82:85], v[182:185], v[216:219], 0
	v_mfma_f32_16x16x32_bf16 v[70:73], v[174:177], v[224:227], 0
	v_mfma_f32_16x16x32_bf16 v[66:69], v[182:185], v[224:227], 0
	v_mfma_f32_16x16x32_bf16 v[118:121], v[178:181], v[204:207], v[118:121]
	v_mfma_f32_16x16x32_bf16 v[114:117], v[186:189], v[204:207], v[114:117]
	v_mfma_f32_16x16x32_bf16 v[102:105], v[178:181], v[212:215], v[102:105]
	v_mfma_f32_16x16x32_bf16 v[98:101], v[186:189], v[212:215], v[98:101]
	v_mfma_f32_16x16x32_bf16 v[86:89], v[178:181], v[220:223], v[86:89]
	v_mfma_f32_16x16x32_bf16 v[82:85], v[186:189], v[220:223], v[82:85]
	v_mfma_f32_16x16x32_bf16 v[70:73], v[178:181], v[228:231], v[70:73]
	v_mfma_f32_16x16x32_bf16 v[66:69], v[186:189], v[228:231], v[66:69]
	s_barrier
	s_setprio 0
	s_add_i32 s37, s57, s4
	v_lshl_add_u64 v[170:171], s[42:43], 0, v[138:139]
	s_mov_b32 m0, s37
	ds_read_b128 v[190:193], v196 offset:16384
	ds_read_b128 v[204:207], v196 offset:17408
	ds_read_b128 v[208:211], v196 offset:18432
	ds_read_b128 v[212:215], v196 offset:19456
	ds_read_b128 v[216:219], v196 offset:20480
	ds_read_b128 v[220:223], v196 offset:21504
	ds_read_b128 v[224:227], v196 offset:22528
	ds_read_b128 v[228:231], v196 offset:23552
	global_load_lds_dwordx4 v[170:171], off
	s_add_i32 m0, s37, 0x2000
	s_add_u32 s74, s42, 0x40000
	v_lshl_add_u64 v[172:173], s[42:43], 0, v[134:135]
	s_addc_u32 s75, s43, 0
	s_add_i32 s29, s29, s4
	global_load_lds_dwordx4 v[172:173], off
	s_mov_b32 m0, s29
	v_lshl_add_u64 v[232:233], s[44:45], 0, v[136:137]
	global_load_lds_dwordx4 v138, s[74:75]
	s_add_i32 m0, s29, 0x2000
	s_nop 0
	global_load_lds_dwordx4 v134, s[74:75]
	v_lshl_add_u64 v[198:199], s[44:45], 0, v[140:141]
	s_mov_b32 m0, s5
	s_nop 0
	global_load_lds_dwordx4 v[198:199], off
	s_mov_b32 m0, s20
	s_nop 0
	global_load_lds_dwordx4 v[232:233], off
	s_lshl_b32 s101, s28, 14
	s_add_i32 s101, s101, s5
	s_add_u32 s100, s66, s101
	s_addc_u32 s101, s67, 0
	v_lshlrev_b32_e32 v2, 4, v163
	v_add_u32_e32 v3, 0x2000, v2
	s_add_i32 m0, s5, 0x20000
	s_nop 0
	global_load_lds_dwordx4 v2, s[100:101]
	s_add_i32 m0, s5, 0x22000
	s_nop 0
	global_load_lds_dwordx4 v3, s[100:101]
	s_waitcnt vmcnt(8)
	s_waitcnt lgkmcnt(0)
	s_setprio 1
	s_barrier
	v_mfma_f32_16x16x32_bf16 v[62:65], v[130:133], v[190:193], 0
	v_mfma_f32_16x16x32_bf16 v[58:61], v[154:157], v[190:193], 0
	v_mfma_f32_16x16x32_bf16 v[46:49], v[130:133], v[208:211], 0
	v_mfma_f32_16x16x32_bf16 v[42:45], v[154:157], v[208:211], 0
	v_mfma_f32_16x16x32_bf16 v[30:33], v[130:133], v[216:219], 0
	v_mfma_f32_16x16x32_bf16 v[26:29], v[154:157], v[216:219], 0
	v_mfma_f32_16x16x32_bf16 v[14:17], v[130:133], v[224:227], 0
	v_mfma_f32_16x16x32_bf16 v[10:13], v[154:157], v[224:227], 0
	v_mfma_f32_16x16x32_bf16 v[62:65], v[150:153], v[204:207], v[62:65]
	v_mfma_f32_16x16x32_bf16 v[58:61], v[158:161], v[204:207], v[58:61]
	v_mfma_f32_16x16x32_bf16 v[46:49], v[150:153], v[212:215], v[46:49]
	v_mfma_f32_16x16x32_bf16 v[42:45], v[158:161], v[212:215], v[42:45]
	v_mfma_f32_16x16x32_bf16 v[30:33], v[150:153], v[220:223], v[30:33]
	v_mfma_f32_16x16x32_bf16 v[26:29], v[158:161], v[220:223], v[26:29]
	v_mfma_f32_16x16x32_bf16 v[14:17], v[150:153], v[228:231], v[14:17]
	v_mfma_f32_16x16x32_bf16 v[10:13], v[158:161], v[228:231], v[10:13]
	v_mfma_f32_16x16x32_bf16 v[54:57], v[174:177], v[190:193], 0
	v_mfma_f32_16x16x32_bf16 v[50:53], v[182:185], v[190:193], 0
	v_mfma_f32_16x16x32_bf16 v[38:41], v[174:177], v[208:211], 0
	v_mfma_f32_16x16x32_bf16 v[34:37], v[182:185], v[208:211], 0
	v_mfma_f32_16x16x32_bf16 v[22:25], v[174:177], v[216:219], 0
	v_mfma_f32_16x16x32_bf16 v[18:21], v[182:185], v[216:219], 0
	v_mfma_f32_16x16x32_bf16 v[6:9], v[174:177], v[224:227], 0
	v_mfma_f32_16x16x32_bf16 v[2:5], v[182:185], v[224:227], 0
	v_mfma_f32_16x16x32_bf16 v[54:57], v[178:181], v[204:207], v[54:57]
	v_mfma_f32_16x16x32_bf16 v[50:53], v[186:189], v[204:207], v[50:53]
	v_mfma_f32_16x16x32_bf16 v[38:41], v[178:181], v[212:215], v[38:41]
	v_mfma_f32_16x16x32_bf16 v[34:37], v[186:189], v[212:215], v[34:37]
	v_mfma_f32_16x16x32_bf16 v[22:25], v[178:181], v[220:223], v[22:25]
	v_mfma_f32_16x16x32_bf16 v[18:21], v[186:189], v[220:223], v[18:21]
	v_mfma_f32_16x16x32_bf16 v[6:9], v[178:181], v[228:231], v[6:9]
	v_mfma_f32_16x16x32_bf16 v[2:5], v[186:189], v[228:231], v[2:5]
	s_barrier
	s_setprio 0
	s_add_i32 s29, 0, 0x18000
	v_add_u32_e32 v0, s29, v195
	s_add_i32 s37, 0, 0x1c000
	ds_read_b128 v[130:133], v0
	ds_read_b128 v[150:153], v0 offset:1024
	ds_read_b128 v[154:157], v0 offset:2048
	ds_read_b128 v[158:161], v0 offset:3072
	v_add_u32_e32 v0, s37, v195
	ds_read_b128 v[174:177], v0
	ds_read_b128 v[178:181], v0 offset:1024
	ds_read_b128 v[182:185], v0 offset:2048
	ds_read_b128 v[186:189], v0 offset:3072
	s_add_u32 s44, s44, 0x40000
	s_addc_u32 s45, s45, 0
	s_mov_b32 m0, s22
	ds_read_b128 v[190:193], v196 offset:32768
	ds_read_b128 v[204:207], v196 offset:33792
	ds_read_b128 v[208:211], v196 offset:34816
	ds_read_b128 v[212:215], v196 offset:35840
	ds_read_b128 v[216:219], v196 offset:36864
	ds_read_b128 v[220:223], v196 offset:37888
	ds_read_b128 v[224:227], v196 offset:38912
	ds_read_b128 v[228:231], v196 offset:39936
	global_load_lds_dwordx4 v140, s[44:45]
	s_mov_b32 m0, s23
	s_nop 0
	global_load_lds_dwordx4 v136, s[44:45]
	s_waitcnt vmcnt(8)
	s_waitcnt lgkmcnt(0)
	s_setprio 1
	s_barrier
	v_mfma_f32_16x16x32_bf16 v[126:129], v[130:133], v[190:193], v[126:129]
	v_mfma_f32_16x16x32_bf16 v[122:125], v[154:157], v[190:193], v[122:125]
	v_mfma_f32_16x16x32_bf16 v[110:113], v[130:133], v[208:211], v[110:113]
	v_mfma_f32_16x16x32_bf16 v[106:109], v[154:157], v[208:211], v[106:109]
	v_mfma_f32_16x16x32_bf16 v[94:97], v[130:133], v[216:219], v[94:97]
	v_mfma_f32_16x16x32_bf16 v[90:93], v[154:157], v[216:219], v[90:93]
	v_mfma_f32_16x16x32_bf16 v[78:81], v[130:133], v[224:227], v[78:81]
	v_mfma_f32_16x16x32_bf16 v[74:77], v[154:157], v[224:227], v[74:77]
	v_mfma_f32_16x16x32_bf16 v[126:129], v[150:153], v[204:207], v[126:129]
	v_mfma_f32_16x16x32_bf16 v[122:125], v[158:161], v[204:207], v[122:125]
	v_mfma_f32_16x16x32_bf16 v[110:113], v[150:153], v[212:215], v[110:113]
	v_mfma_f32_16x16x32_bf16 v[106:109], v[158:161], v[212:215], v[106:109]
	v_mfma_f32_16x16x32_bf16 v[94:97], v[150:153], v[220:223], v[94:97]
	v_mfma_f32_16x16x32_bf16 v[90:93], v[158:161], v[220:223], v[90:93]
	v_mfma_f32_16x16x32_bf16 v[78:81], v[150:153], v[228:231], v[78:81]
	v_mfma_f32_16x16x32_bf16 v[74:77], v[158:161], v[228:231], v[74:77]
	v_mfma_f32_16x16x32_bf16 v[118:121], v[174:177], v[190:193], v[118:121]
	v_mfma_f32_16x16x32_bf16 v[114:117], v[182:185], v[190:193], v[114:117]
	v_mfma_f32_16x16x32_bf16 v[102:105], v[174:177], v[208:211], v[102:105]
	v_mfma_f32_16x16x32_bf16 v[98:101], v[182:185], v[208:211], v[98:101]
	v_mfma_f32_16x16x32_bf16 v[86:89], v[174:177], v[216:219], v[86:89]
	v_mfma_f32_16x16x32_bf16 v[82:85], v[182:185], v[216:219], v[82:85]
	v_mfma_f32_16x16x32_bf16 v[70:73], v[174:177], v[224:227], v[70:73]
	v_mfma_f32_16x16x32_bf16 v[66:69], v[182:185], v[224:227], v[66:69]
	v_mfma_f32_16x16x32_bf16 v[118:121], v[178:181], v[204:207], v[118:121]
	v_mfma_f32_16x16x32_bf16 v[114:117], v[186:189], v[204:207], v[114:117]
	v_mfma_f32_16x16x32_bf16 v[102:105], v[178:181], v[212:215], v[102:105]
	v_mfma_f32_16x16x32_bf16 v[98:101], v[186:189], v[212:215], v[98:101]
	v_mfma_f32_16x16x32_bf16 v[86:89], v[178:181], v[220:223], v[86:89]
	v_mfma_f32_16x16x32_bf16 v[82:85], v[186:189], v[220:223], v[82:85]
	v_mfma_f32_16x16x32_bf16 v[70:73], v[178:181], v[228:231], v[70:73]
	v_mfma_f32_16x16x32_bf16 v[66:69], v[186:189], v[228:231], v[66:69]
	s_barrier
	s_setprio 0
	s_add_i32 s29, s29, s4
	v_lshl_add_u64 v[170:171], v[170:171], 0, s[24:25]
	s_mov_b32 m0, s29
	ds_read_b128 v[190:193], v196 offset:49152
	ds_read_b128 v[204:207], v196 offset:50176
	ds_read_b128 v[208:211], v196 offset:51200
	ds_read_b128 v[212:215], v196 offset:52224
	ds_read_b128 v[216:219], v196 offset:53248
	ds_read_b128 v[220:223], v196 offset:54272
	ds_read_b128 v[224:227], v196 offset:55296
	ds_read_b128 v[228:231], v196 offset:56320
	global_load_lds_dwordx4 v[170:171], off
	s_add_i32 m0, s29, 0x2000
	s_add_u32 s42, s42, 0x40080
	v_lshl_add_u64 v[170:171], v[172:173], 0, s[24:25]
	s_addc_u32 s43, s43, 0
	s_add_i32 s29, s37, s4
	global_load_lds_dwordx4 v[170:171], off
	s_mov_b32 m0, s29
	s_nop 0
	global_load_lds_dwordx4 v138, s[42:43]
	s_add_i32 m0, s29, 0x2000
	s_nop 0
	global_load_lds_dwordx4 v134, s[42:43]
	v_lshl_add_u64 v[170:171], v[198:199], 0, s[24:25]
	s_mov_b32 m0, s33
	s_nop 0
	global_load_lds_dwordx4 v[170:171], off
	v_lshl_add_u64 v[170:171], v[232:233], 0, s[24:25]
	s_mov_b32 m0, s72
	s_nop 0
	global_load_lds_dwordx4 v[170:171], off
	s_waitcnt vmcnt(8)
	s_waitcnt lgkmcnt(0)
	s_setprio 1
	s_barrier
	v_mfma_f32_16x16x32_bf16 v[62:65], v[130:133], v[190:193], v[62:65]
	v_mfma_f32_16x16x32_bf16 v[58:61], v[154:157], v[190:193], v[58:61]
	v_mfma_f32_16x16x32_bf16 v[46:49], v[130:133], v[208:211], v[46:49]
	v_mfma_f32_16x16x32_bf16 v[42:45], v[154:157], v[208:211], v[42:45]
	v_mfma_f32_16x16x32_bf16 v[30:33], v[130:133], v[216:219], v[30:33]
	v_mfma_f32_16x16x32_bf16 v[26:29], v[154:157], v[216:219], v[26:29]
	v_mfma_f32_16x16x32_bf16 v[14:17], v[130:133], v[224:227], v[14:17]
	v_mfma_f32_16x16x32_bf16 v[10:13], v[154:157], v[224:227], v[10:13]
	v_mfma_f32_16x16x32_bf16 v[62:65], v[150:153], v[204:207], v[62:65]
	v_mfma_f32_16x16x32_bf16 v[58:61], v[158:161], v[204:207], v[58:61]
	v_mfma_f32_16x16x32_bf16 v[46:49], v[150:153], v[212:215], v[46:49]
	v_mfma_f32_16x16x32_bf16 v[42:45], v[158:161], v[212:215], v[42:45]
	v_mfma_f32_16x16x32_bf16 v[30:33], v[150:153], v[220:223], v[30:33]
	v_mfma_f32_16x16x32_bf16 v[26:29], v[158:161], v[220:223], v[26:29]
	v_mfma_f32_16x16x32_bf16 v[14:17], v[150:153], v[228:231], v[14:17]
	v_mfma_f32_16x16x32_bf16 v[10:13], v[158:161], v[228:231], v[10:13]
	v_mfma_f32_16x16x32_bf16 v[54:57], v[174:177], v[190:193], v[54:57]
	v_mfma_f32_16x16x32_bf16 v[50:53], v[182:185], v[190:193], v[50:53]
	v_mfma_f32_16x16x32_bf16 v[38:41], v[174:177], v[208:211], v[38:41]
	v_mfma_f32_16x16x32_bf16 v[34:37], v[182:185], v[208:211], v[34:37]
	v_mfma_f32_16x16x32_bf16 v[22:25], v[174:177], v[216:219], v[22:25]
	v_mfma_f32_16x16x32_bf16 v[18:21], v[182:185], v[216:219], v[18:21]
	v_mfma_f32_16x16x32_bf16 v[6:9], v[174:177], v[224:227], v[6:9]
	v_mfma_f32_16x16x32_bf16 v[2:5], v[182:185], v[224:227], v[2:5]
	v_mfma_f32_16x16x32_bf16 v[54:57], v[178:181], v[204:207], v[54:57]
	v_mfma_f32_16x16x32_bf16 v[50:53], v[186:189], v[204:207], v[50:53]
	v_mfma_f32_16x16x32_bf16 v[38:41], v[178:181], v[212:215], v[38:41]
	v_mfma_f32_16x16x32_bf16 v[34:37], v[186:189], v[212:215], v[34:37]
	v_mfma_f32_16x16x32_bf16 v[22:25], v[178:181], v[220:223], v[22:25]
	v_mfma_f32_16x16x32_bf16 v[18:21], v[186:189], v[220:223], v[18:21]
	v_mfma_f32_16x16x32_bf16 v[6:9], v[178:181], v[228:231], v[6:9]
	v_mfma_f32_16x16x32_bf16 v[2:5], v[186:189], v[228:231], v[2:5]
	s_barrier
	s_setprio 0
	s_add_u32 s16, s16, 0x100
	s_addc_u32 s17, s17, 0
	s_add_u32 s48, s48, 0x100
	s_addc_u32 s49, s49, 0
	s_cmp_ge_i32 s56, s3
	s_mov_b32 s42, s56
	s_cbranch_scc0 .LBB7_523
	s_branch .Lpeelx_523
	.p2align	8

.Lpeel_676:
	s_add_i32 s29, s37, 2
	s_add_u32 s44, s42, 0x100
	s_addc_u32 s45, s43, 0
	s_add_i32 s74, 0, 0x10000
	v_add_u32_e32 v81, s74, v79
	ds_read_b128 v[82:85], v81
	ds_read_b128 v[86:89], v81 offset:1024
	ds_read_b128 v[90:93], v81 offset:2048
	ds_read_b128 v[94:97], v81 offset:3072
	s_cmp_eq_u32 s53, s37
	s_cselect_b32 s51, s56, s45
	s_cselect_b32 s50, s57, s44
	s_cselect_b32 s49, s72, s85
	s_cselect_b32 s48, s73, s84
	v_lshl_add_u64 v[130:131], s[42:43], 0, v[74:75]
	s_add_i32 m0, s5, 0xc000
	ds_read_b128 v[98:101], v80
	ds_read_b128 v[102:105], v80 offset:1024
	ds_read_b128 v[106:109], v80 offset:2048
	ds_read_b128 v[110:113], v80 offset:3072
	ds_read_b128 v[114:117], v80 offset:4096
	ds_read_b128 v[118:121], v80 offset:5120
	ds_read_b128 v[122:125], v80 offset:6144
	ds_read_b128 v[126:129], v80 offset:7168
	global_load_lds_dwordx4 v[130:131], off
	v_lshl_add_u64 v[130:131], s[42:43], 0, v[76:77]
	s_add_i32 m0, s5, 0xe000
	s_nop 0
	global_load_lds_dwordx4 v[130:131], off
	s_waitcnt vmcnt(8)
	s_waitcnt lgkmcnt(0)
	s_setprio 1
	s_barrier
	v_mfma_f32_16x16x32_bf16 v[62:65], v[82:85], v[98:101], 0
	v_mfma_f32_16x16x32_bf16 v[58:61], v[90:93], v[98:101], 0
	v_mfma_f32_16x16x32_bf16 v[54:57], v[82:85], v[106:109], 0
	v_mfma_f32_16x16x32_bf16 v[50:53], v[90:93], v[106:109], 0
	v_mfma_f32_16x16x32_bf16 v[46:49], v[82:85], v[114:117], 0
	v_mfma_f32_16x16x32_bf16 v[42:45], v[90:93], v[114:117], 0
	v_mfma_f32_16x16x32_bf16 v[38:41], v[82:85], v[122:125], 0
	v_mfma_f32_16x16x32_bf16 v[34:37], v[90:93], v[122:125], 0
	v_mfma_f32_16x16x32_bf16 v[62:65], v[86:89], v[102:105], v[62:65]
	v_mfma_f32_16x16x32_bf16 v[58:61], v[94:97], v[102:105], v[58:61]
	v_mfma_f32_16x16x32_bf16 v[54:57], v[86:89], v[110:113], v[54:57]
	v_mfma_f32_16x16x32_bf16 v[50:53], v[94:97], v[110:113], v[50:53]
	v_mfma_f32_16x16x32_bf16 v[46:49], v[86:89], v[118:121], v[46:49]
	v_mfma_f32_16x16x32_bf16 v[42:45], v[94:97], v[118:121], v[42:45]
	v_mfma_f32_16x16x32_bf16 v[38:41], v[86:89], v[126:129], v[38:41]
	v_mfma_f32_16x16x32_bf16 v[34:37], v[94:97], v[126:129], v[34:37]
	s_barrier
	s_setprio 0
	s_add_i32 s37, s74, s4
	v_lshl_add_u64 v[130:131], s[48:49], 0, v[70:71]
	s_mov_b32 m0, s37
	ds_read_b128 v[98:101], v80 offset:16384
	ds_read_b128 v[102:105], v80 offset:17408
	ds_read_b128 v[106:109], v80 offset:18432
	ds_read_b128 v[110:113], v80 offset:19456
	ds_read_b128 v[114:117], v80 offset:20480
	ds_read_b128 v[118:121], v80 offset:21504
	ds_read_b128 v[122:125], v80 offset:22528
	ds_read_b128 v[126:129], v80 offset:23552
	global_load_lds_dwordx4 v[130:131], off
	s_add_i32 m0, s37, 0x2000
	s_add_u32 s42, s48, 0x20000
	v_lshl_add_u64 v[132:133], s[48:49], 0, v[66:67]
	s_addc_u32 s43, s49, 0
	global_load_lds_dwordx4 v[132:133], off
	v_lshl_add_u64 v[134:135], s[42:43], 0, v[70:71]
	s_mov_b32 m0, s10
	v_lshl_add_u64 v[136:137], s[50:51], 0, v[68:69]
	global_load_lds_dwordx4 v[134:135], off
	v_lshl_add_u64 v[134:135], s[42:43], 0, v[66:67]
	s_mov_b32 m0, s20
	s_nop 0
	global_load_lds_dwordx4 v[134:135], off
	v_lshl_add_u64 v[134:135], s[50:51], 0, v[0:1]
	s_mov_b32 m0, s5
	s_nop 0
	global_load_lds_dwordx4 v[134:135], off
	s_mov_b32 m0, s22
	s_nop 0
	global_load_lds_dwordx4 v[136:137], off
	s_waitcnt vmcnt(8)
	s_waitcnt lgkmcnt(0)
	s_setprio 1
	s_barrier
	v_mfma_f32_16x16x32_bf16 v[30:33], v[82:85], v[98:101], 0
	v_mfma_f32_16x16x32_bf16 v[26:29], v[90:93], v[98:101], 0
	v_mfma_f32_16x16x32_bf16 v[22:25], v[82:85], v[106:109], 0
	v_mfma_f32_16x16x32_bf16 v[18:21], v[90:93], v[106:109], 0
	v_mfma_f32_16x16x32_bf16 v[14:17], v[82:85], v[114:117], 0
	v_mfma_f32_16x16x32_bf16 v[10:13], v[90:93], v[114:117], 0
	v_mfma_f32_16x16x32_bf16 v[6:9], v[82:85], v[122:125], 0
	v_mfma_f32_16x16x32_bf16 v[2:5], v[90:93], v[122:125], 0
	v_mfma_f32_16x16x32_bf16 v[30:33], v[86:89], v[102:105], v[30:33]
	v_mfma_f32_16x16x32_bf16 v[26:29], v[94:97], v[102:105], v[26:29]
	v_mfma_f32_16x16x32_bf16 v[22:25], v[86:89], v[110:113], v[22:25]
	v_mfma_f32_16x16x32_bf16 v[18:21], v[94:97], v[110:113], v[18:21]
	v_mfma_f32_16x16x32_bf16 v[14:17], v[86:89], v[118:121], v[14:17]
	v_mfma_f32_16x16x32_bf16 v[10:13], v[94:97], v[118:121], v[10:13]
	v_mfma_f32_16x16x32_bf16 v[6:9], v[86:89], v[126:129], v[6:9]
	v_mfma_f32_16x16x32_bf16 v[2:5], v[94:97], v[126:129], v[2:5]
	s_barrier
	s_setprio 0
	s_add_i32 s37, 0, 0x18000
	v_add_u32_e32 v81, s37, v79
	ds_read_b128 v[82:85], v81
	ds_read_b128 v[86:89], v81 offset:1024
	ds_read_b128 v[90:93], v81 offset:2048
	ds_read_b128 v[94:97], v81 offset:3072
	s_add_u32 s42, s50, 0x28000
	s_addc_u32 s43, s51, 0
	s_mov_b32 m0, s23
	v_lshl_add_u64 v[138:139], s[42:43], 0, v[0:1]
	ds_read_b128 v[98:101], v80 offset:32768
	ds_read_b128 v[102:105], v80 offset:33792
	ds_read_b128 v[106:109], v80 offset:34816
	ds_read_b128 v[110:113], v80 offset:35840
	ds_read_b128 v[114:117], v80 offset:36864
	ds_read_b128 v[118:121], v80 offset:37888
	ds_read_b128 v[122:125], v80 offset:38912
	ds_read_b128 v[126:129], v80 offset:39936
	global_load_lds_dwordx4 v[138:139], off
	v_lshl_add_u64 v[138:139], s[42:43], 0, v[68:69]
	s_mov_b32 m0, s28
	s_nop 0
	global_load_lds_dwordx4 v[138:139], off
	s_waitcnt vmcnt(8)
	s_waitcnt lgkmcnt(0)
	s_setprio 1
	s_barrier
	v_mfma_f32_16x16x32_bf16 v[62:65], v[82:85], v[98:101], v[62:65]
	v_mfma_f32_16x16x32_bf16 v[58:61], v[90:93], v[98:101], v[58:61]
	v_mfma_f32_16x16x32_bf16 v[54:57], v[82:85], v[106:109], v[54:57]
	v_mfma_f32_16x16x32_bf16 v[50:53], v[90:93], v[106:109], v[50:53]
	v_mfma_f32_16x16x32_bf16 v[46:49], v[82:85], v[114:117], v[46:49]
	v_mfma_f32_16x16x32_bf16 v[42:45], v[90:93], v[114:117], v[42:45]
	v_mfma_f32_16x16x32_bf16 v[38:41], v[82:85], v[122:125], v[38:41]
	v_mfma_f32_16x16x32_bf16 v[34:37], v[90:93], v[122:125], v[34:37]
	v_mfma_f32_16x16x32_bf16 v[62:65], v[86:89], v[102:105], v[62:65]
	v_mfma_f32_16x16x32_bf16 v[58:61], v[94:97], v[102:105], v[58:61]
	v_mfma_f32_16x16x32_bf16 v[54:57], v[86:89], v[110:113], v[54:57]
	v_mfma_f32_16x16x32_bf16 v[50:53], v[94:97], v[110:113], v[50:53]
	v_mfma_f32_16x16x32_bf16 v[46:49], v[86:89], v[118:121], v[46:49]
	v_mfma_f32_16x16x32_bf16 v[42:45], v[94:97], v[118:121], v[42:45]
	v_mfma_f32_16x16x32_bf16 v[38:41], v[86:89], v[126:129], v[38:41]
	v_mfma_f32_16x16x32_bf16 v[34:37], v[94:97], v[126:129], v[34:37]
	s_barrier
	s_setprio 0
	s_add_i32 s37, s37, s4
	v_lshl_add_u64 v[130:131], v[130:131], 0, s[24:25]
	s_mov_b32 m0, s37
	ds_read_b128 v[98:101], v80 offset:49152
	ds_read_b128 v[102:105], v80 offset:50176
	ds_read_b128 v[106:109], v80 offset:51200
	ds_read_b128 v[110:113], v80 offset:52224
	ds_read_b128 v[114:117], v80 offset:53248
	ds_read_b128 v[118:121], v80 offset:54272
	ds_read_b128 v[122:125], v80 offset:55296
	ds_read_b128 v[126:129], v80 offset:56320
	global_load_lds_dwordx4 v[130:131], off
	s_add_i32 m0, s37, 0x2000
	s_add_u32 s42, s48, 0x20080
	v_lshl_add_u64 v[130:131], v[132:133], 0, s[24:25]
	s_addc_u32 s43, s49, 0
	global_load_lds_dwordx4 v[130:131], off
	v_lshl_add_u64 v[130:131], s[42:43], 0, v[70:71]
	s_mov_b32 m0, s38
	s_nop 0
	global_load_lds_dwordx4 v[130:131], off
	v_lshl_add_u64 v[130:131], s[42:43], 0, v[66:67]
	s_mov_b32 m0, s39
	s_nop 0
	global_load_lds_dwordx4 v[130:131], off
	v_lshl_add_u64 v[130:131], v[134:135], 0, s[24:25]
	s_mov_b32 m0, s31
	s_nop 0
	global_load_lds_dwordx4 v[130:131], off
	v_lshl_add_u64 v[130:131], v[136:137], 0, s[24:25]
	s_mov_b32 m0, s33
	s_nop 0
	global_load_lds_dwordx4 v[130:131], off
	s_waitcnt vmcnt(8)
	s_waitcnt lgkmcnt(0)
	s_setprio 1
	s_barrier
	v_mfma_f32_16x16x32_bf16 v[30:33], v[82:85], v[98:101], v[30:33]
	v_mfma_f32_16x16x32_bf16 v[26:29], v[90:93], v[98:101], v[26:29]
	v_mfma_f32_16x16x32_bf16 v[22:25], v[82:85], v[106:109], v[22:25]
	v_mfma_f32_16x16x32_bf16 v[18:21], v[90:93], v[106:109], v[18:21]
	v_mfma_f32_16x16x32_bf16 v[14:17], v[82:85], v[114:117], v[14:17]
	v_mfma_f32_16x16x32_bf16 v[10:13], v[90:93], v[114:117], v[10:13]
	v_mfma_f32_16x16x32_bf16 v[6:9], v[82:85], v[122:125], v[6:9]
	v_mfma_f32_16x16x32_bf16 v[2:5], v[90:93], v[122:125], v[2:5]
	v_mfma_f32_16x16x32_bf16 v[30:33], v[86:89], v[102:105], v[30:33]
	v_mfma_f32_16x16x32_bf16 v[26:29], v[94:97], v[102:105], v[26:29]
	v_mfma_f32_16x16x32_bf16 v[22:25], v[86:89], v[110:113], v[22:25]
	v_mfma_f32_16x16x32_bf16 v[18:21], v[94:97], v[110:113], v[18:21]
	v_mfma_f32_16x16x32_bf16 v[14:17], v[86:89], v[118:121], v[14:17]
	v_mfma_f32_16x16x32_bf16 v[10:13], v[94:97], v[118:121], v[10:13]
	v_mfma_f32_16x16x32_bf16 v[6:9], v[86:89], v[126:129], v[6:9]
	v_mfma_f32_16x16x32_bf16 v[2:5], v[94:97], v[126:129], v[2:5]
	s_barrier
	s_setprio 0
	s_add_u32 s84, s84, 0x100
	s_addc_u32 s85, s85, 0
	s_cmp_ge_i32 s29, s3
	s_mov_b64 s[42:43], s[44:45]
	s_mov_b32 s37, s29
	s_cbranch_scc0 .LBB7_676
	s_branch .Lpeelx_676
	.p2align	8

.Lpeel_886:
	s_add_i32 s37, s44, 2
	s_add_u32 s42, s16, 0x100
	s_addc_u32 s43, s17, 0
	s_add_i32 s29, 0, 0x10000
	s_cmp_eq_u32 s57, s44
	s_cselect_b32 s49, s39, s43
	s_cselect_b32 s48, s54, s42
	s_cselect_b32 s45, s55, s73
	s_cselect_b32 s44, s56, s72
	s_add_i32 s74, 0, 0x14000
	v_add_u32_e32 v142, s29, v193
	v_add_u32_e32 v158, s74, v193
	ds_read_b128 v[74:77], v142
	ds_read_b128 v[78:81], v142 offset:1024
	ds_read_b128 v[138:141], v142 offset:2048
	ds_read_b128 v[142:145], v142 offset:3072
	ds_read_b128 v[146:149], v158
	ds_read_b128 v[150:153], v158 offset:1024
	ds_read_b128 v[154:157], v158 offset:2048
	ds_read_b128 v[158:161], v158 offset:3072
	v_lshl_add_u64 v[170:171], s[16:17], 0, v[184:185]
	s_add_i32 m0, s5, 0xc000
	ds_read_b128 v[188:191], v195
	ds_read_b128 v[196:199], v195 offset:1024
	ds_read_b128 v[204:207], v195 offset:2048
	ds_read_b128 v[208:211], v195 offset:3072
	ds_read_b128 v[212:215], v195 offset:4096
	ds_read_b128 v[216:219], v195 offset:5120
	ds_read_b128 v[220:223], v195 offset:6144
	ds_read_b128 v[224:227], v195 offset:7168
	global_load_lds_dwordx4 v[170:171], off
	v_lshl_add_u64 v[170:171], s[16:17], 0, v[186:187]
	s_add_i32 m0, s5, 0xe000
	s_nop 0
	global_load_lds_dwordx4 v[170:171], off
	s_waitcnt vmcnt(8)
	s_waitcnt lgkmcnt(0)
	s_setprio 1
	s_barrier
	v_mfma_f32_16x16x32_bf16 v[134:137], v[74:77], v[188:191], 0
	v_mfma_f32_16x16x32_bf16 v[130:133], v[138:141], v[188:191], 0
	v_mfma_f32_16x16x32_bf16 v[118:121], v[74:77], v[204:207], 0
	v_mfma_f32_16x16x32_bf16 v[114:117], v[138:141], v[204:207], 0
	v_mfma_f32_16x16x32_bf16 v[102:105], v[74:77], v[212:215], 0
	v_mfma_f32_16x16x32_bf16 v[98:101], v[138:141], v[212:215], 0
	v_mfma_f32_16x16x32_bf16 v[86:89], v[74:77], v[220:223], 0
	v_mfma_f32_16x16x32_bf16 v[82:85], v[138:141], v[220:223], 0
	v_mfma_f32_16x16x32_bf16 v[134:137], v[78:81], v[196:199], v[134:137]
	v_mfma_f32_16x16x32_bf16 v[130:133], v[142:145], v[196:199], v[130:133]
	v_mfma_f32_16x16x32_bf16 v[118:121], v[78:81], v[208:211], v[118:121]
	v_mfma_f32_16x16x32_bf16 v[114:117], v[142:145], v[208:211], v[114:117]
	v_mfma_f32_16x16x32_bf16 v[102:105], v[78:81], v[216:219], v[102:105]
	v_mfma_f32_16x16x32_bf16 v[98:101], v[142:145], v[216:219], v[98:101]
	v_mfma_f32_16x16x32_bf16 v[86:89], v[78:81], v[224:227], v[86:89]
	v_mfma_f32_16x16x32_bf16 v[82:85], v[142:145], v[224:227], v[82:85]
	v_mfma_f32_16x16x32_bf16 v[126:129], v[146:149], v[188:191], 0
	v_mfma_f32_16x16x32_bf16 v[122:125], v[154:157], v[188:191], 0
	v_mfma_f32_16x16x32_bf16 v[110:113], v[146:149], v[204:207], 0
	v_mfma_f32_16x16x32_bf16 v[106:109], v[154:157], v[204:207], 0
	v_mfma_f32_16x16x32_bf16 v[94:97], v[146:149], v[212:215], 0
	v_mfma_f32_16x16x32_bf16 v[90:93], v[154:157], v[212:215], 0
	v_mfma_f32_16x16x32_bf16 v[70:73], v[146:149], v[220:223], 0
	v_mfma_f32_16x16x32_bf16 v[66:69], v[154:157], v[220:223], 0
	v_mfma_f32_16x16x32_bf16 v[126:129], v[150:153], v[196:199], v[126:129]
	v_mfma_f32_16x16x32_bf16 v[122:125], v[158:161], v[196:199], v[122:125]
	v_mfma_f32_16x16x32_bf16 v[110:113], v[150:153], v[208:211], v[110:113]
	v_mfma_f32_16x16x32_bf16 v[106:109], v[158:161], v[208:211], v[106:109]
	v_mfma_f32_16x16x32_bf16 v[94:97], v[150:153], v[216:219], v[94:97]
	v_mfma_f32_16x16x32_bf16 v[90:93], v[158:161], v[216:219], v[90:93]
	v_mfma_f32_16x16x32_bf16 v[70:73], v[150:153], v[224:227], v[70:73]
	v_mfma_f32_16x16x32_bf16 v[66:69], v[158:161], v[224:227], v[66:69]
	s_barrier
	s_setprio 0
	s_add_i32 s16, s29, s4
	v_lshl_add_u64 v[170:171], s[44:45], 0, v[178:179]
	s_mov_b32 m0, s16
	ds_read_b128 v[188:191], v195 offset:16384
	ds_read_b128 v[196:199], v195 offset:17408
	ds_read_b128 v[204:207], v195 offset:18432
	ds_read_b128 v[208:211], v195 offset:19456
	ds_read_b128 v[212:215], v195 offset:20480
	ds_read_b128 v[216:219], v195 offset:21504
	ds_read_b128 v[220:223], v195 offset:22528
	ds_read_b128 v[224:227], v195 offset:23552
	global_load_lds_dwordx4 v[170:171], off
	s_add_i32 m0, s16, 0x2000
	s_add_u32 s16, s44, 0x28000
	v_lshl_add_u64 v[172:173], s[44:45], 0, v[174:175]
	s_addc_u32 s17, s45, 0
	s_add_i32 s29, s74, s4
	global_load_lds_dwordx4 v[172:173], off
	v_lshl_add_u64 v[228:229], s[16:17], 0, v[178:179]
	s_mov_b32 m0, s29
	v_lshl_add_u64 v[230:231], s[48:49], 0, v[176:177]
	global_load_lds_dwordx4 v[228:229], off
	v_lshl_add_u64 v[228:229], s[16:17], 0, v[174:175]
	s_add_i32 m0, s29, 0x2000
	s_nop 0
	global_load_lds_dwordx4 v[228:229], off
	v_lshl_add_u64 v[228:229], s[48:49], 0, v[180:181]
	s_mov_b32 m0, s5
	s_nop 0
	global_load_lds_dwordx4 v[228:229], off
	s_mov_b32 m0, s20
	s_nop 0
	global_load_lds_dwordx4 v[230:231], off
	s_waitcnt vmcnt(8)
	s_waitcnt lgkmcnt(0)
	s_setprio 1
	s_barrier
	v_mfma_f32_16x16x32_bf16 v[62:65], v[74:77], v[188:191], 0
	v_mfma_f32_16x16x32_bf16 v[58:61], v[138:141], v[188:191], 0
	v_mfma_f32_16x16x32_bf16 v[46:49], v[74:77], v[204:207], 0
	v_mfma_f32_16x16x32_bf16 v[42:45], v[138:141], v[204:207], 0
	v_mfma_f32_16x16x32_bf16 v[30:33], v[74:77], v[212:215], 0
	v_mfma_f32_16x16x32_bf16 v[26:29], v[138:141], v[212:215], 0
	v_mfma_f32_16x16x32_bf16 v[14:17], v[74:77], v[220:223], 0
	v_mfma_f32_16x16x32_bf16 v[10:13], v[138:141], v[220:223], 0
	v_mfma_f32_16x16x32_bf16 v[62:65], v[78:81], v[196:199], v[62:65]
	v_mfma_f32_16x16x32_bf16 v[58:61], v[142:145], v[196:199], v[58:61]
	v_mfma_f32_16x16x32_bf16 v[46:49], v[78:81], v[208:211], v[46:49]
	v_mfma_f32_16x16x32_bf16 v[42:45], v[142:145], v[208:211], v[42:45]
	v_mfma_f32_16x16x32_bf16 v[30:33], v[78:81], v[216:219], v[30:33]
	v_mfma_f32_16x16x32_bf16 v[26:29], v[142:145], v[216:219], v[26:29]
	v_mfma_f32_16x16x32_bf16 v[14:17], v[78:81], v[224:227], v[14:17]
	v_mfma_f32_16x16x32_bf16 v[10:13], v[142:145], v[224:227], v[10:13]
	v_mfma_f32_16x16x32_bf16 v[54:57], v[146:149], v[188:191], 0
	v_mfma_f32_16x16x32_bf16 v[50:53], v[154:157], v[188:191], 0
	v_mfma_f32_16x16x32_bf16 v[38:41], v[146:149], v[204:207], 0
	v_mfma_f32_16x16x32_bf16 v[34:37], v[154:157], v[204:207], 0
	v_mfma_f32_16x16x32_bf16 v[22:25], v[146:149], v[212:215], 0
	v_mfma_f32_16x16x32_bf16 v[18:21], v[154:157], v[212:215], 0
	v_mfma_f32_16x16x32_bf16 v[6:9], v[146:149], v[220:223], 0
	v_mfma_f32_16x16x32_bf16 v[2:5], v[154:157], v[220:223], 0
	v_mfma_f32_16x16x32_bf16 v[54:57], v[150:153], v[196:199], v[54:57]
	v_mfma_f32_16x16x32_bf16 v[50:53], v[158:161], v[196:199], v[50:53]
	v_mfma_f32_16x16x32_bf16 v[38:41], v[150:153], v[208:211], v[38:41]
	v_mfma_f32_16x16x32_bf16 v[34:37], v[158:161], v[208:211], v[34:37]
	v_mfma_f32_16x16x32_bf16 v[22:25], v[150:153], v[216:219], v[22:25]
	v_mfma_f32_16x16x32_bf16 v[18:21], v[158:161], v[216:219], v[18:21]
	v_mfma_f32_16x16x32_bf16 v[6:9], v[150:153], v[224:227], v[6:9]
	v_mfma_f32_16x16x32_bf16 v[2:5], v[158:161], v[224:227], v[2:5]
	s_barrier
	s_setprio 0
	s_add_i32 s29, 0, 0x18000
	s_add_i32 s74, 0, 0x1c000
	v_add_u32_e32 v142, s29, v193
	v_add_u32_e32 v158, s74, v193
	ds_read_b128 v[74:77], v142
	ds_read_b128 v[78:81], v142 offset:1024
	ds_read_b128 v[138:141], v142 offset:2048
	ds_read_b128 v[142:145], v142 offset:3072
	ds_read_b128 v[146:149], v158
	ds_read_b128 v[150:153], v158 offset:1024
	ds_read_b128 v[154:157], v158 offset:2048
	ds_read_b128 v[158:161], v158 offset:3072
	s_add_u32 s16, s48, 0x28000
	s_addc_u32 s17, s49, 0
	s_mov_b32 m0, s22
	v_lshl_add_u64 v[232:233], s[16:17], 0, v[180:181]
	ds_read_b128 v[188:191], v195 offset:32768
	ds_read_b128 v[196:199], v195 offset:33792
	ds_read_b128 v[204:207], v195 offset:34816
	ds_read_b128 v[208:211], v195 offset:35840
	ds_read_b128 v[212:215], v195 offset:36864
	ds_read_b128 v[216:219], v195 offset:37888
	ds_read_b128 v[220:223], v195 offset:38912
	ds_read_b128 v[224:227], v195 offset:39936
	global_load_lds_dwordx4 v[232:233], off
	v_lshl_add_u64 v[232:233], s[16:17], 0, v[176:177]
	s_mov_b32 m0, s23
	s_nop 0
	global_load_lds_dwordx4 v[232:233], off
	s_waitcnt vmcnt(8)
	s_waitcnt lgkmcnt(0)
	s_setprio 1
	s_barrier
	v_mfma_f32_16x16x32_bf16 v[134:137], v[74:77], v[188:191], v[134:137]
	v_mfma_f32_16x16x32_bf16 v[130:133], v[138:141], v[188:191], v[130:133]
	v_mfma_f32_16x16x32_bf16 v[118:121], v[74:77], v[204:207], v[118:121]
	v_mfma_f32_16x16x32_bf16 v[114:117], v[138:141], v[204:207], v[114:117]
	v_mfma_f32_16x16x32_bf16 v[102:105], v[74:77], v[212:215], v[102:105]
	v_mfma_f32_16x16x32_bf16 v[98:101], v[138:141], v[212:215], v[98:101]
	v_mfma_f32_16x16x32_bf16 v[86:89], v[74:77], v[220:223], v[86:89]
	v_mfma_f32_16x16x32_bf16 v[82:85], v[138:141], v[220:223], v[82:85]
	v_mfma_f32_16x16x32_bf16 v[134:137], v[78:81], v[196:199], v[134:137]
	v_mfma_f32_16x16x32_bf16 v[130:133], v[142:145], v[196:199], v[130:133]
	v_mfma_f32_16x16x32_bf16 v[118:121], v[78:81], v[208:211], v[118:121]
	v_mfma_f32_16x16x32_bf16 v[114:117], v[142:145], v[208:211], v[114:117]
	v_mfma_f32_16x16x32_bf16 v[102:105], v[78:81], v[216:219], v[102:105]
	v_mfma_f32_16x16x32_bf16 v[98:101], v[142:145], v[216:219], v[98:101]
	v_mfma_f32_16x16x32_bf16 v[86:89], v[78:81], v[224:227], v[86:89]
	v_mfma_f32_16x16x32_bf16 v[82:85], v[142:145], v[224:227], v[82:85]
	v_mfma_f32_16x16x32_bf16 v[126:129], v[146:149], v[188:191], v[126:129]
	v_mfma_f32_16x16x32_bf16 v[122:125], v[154:157], v[188:191], v[122:125]
	v_mfma_f32_16x16x32_bf16 v[110:113], v[146:149], v[204:207], v[110:113]
	v_mfma_f32_16x16x32_bf16 v[106:109], v[154:157], v[204:207], v[106:109]
	v_mfma_f32_16x16x32_bf16 v[94:97], v[146:149], v[212:215], v[94:97]
	v_mfma_f32_16x16x32_bf16 v[90:93], v[154:157], v[212:215], v[90:93]
	v_mfma_f32_16x16x32_bf16 v[70:73], v[146:149], v[220:223], v[70:73]
	v_mfma_f32_16x16x32_bf16 v[66:69], v[154:157], v[220:223], v[66:69]
	v_mfma_f32_16x16x32_bf16 v[126:129], v[150:153], v[196:199], v[126:129]
	v_mfma_f32_16x16x32_bf16 v[122:125], v[158:161], v[196:199], v[122:125]
	v_mfma_f32_16x16x32_bf16 v[110:113], v[150:153], v[208:211], v[110:113]
	v_mfma_f32_16x16x32_bf16 v[106:109], v[158:161], v[208:211], v[106:109]
	v_mfma_f32_16x16x32_bf16 v[94:97], v[150:153], v[216:219], v[94:97]
	v_mfma_f32_16x16x32_bf16 v[90:93], v[158:161], v[216:219], v[90:93]
	v_mfma_f32_16x16x32_bf16 v[70:73], v[150:153], v[224:227], v[70:73]
	v_mfma_f32_16x16x32_bf16 v[66:69], v[158:161], v[224:227], v[66:69]
	s_barrier
	s_setprio 0
	s_add_i32 s16, s29, s4
	v_lshl_add_u64 v[170:171], v[170:171], 0, s[24:25]
	s_mov_b32 m0, s16
	ds_read_b128 v[188:191], v195 offset:49152
	ds_read_b128 v[196:199], v195 offset:50176
	ds_read_b128 v[204:207], v195 offset:51200
	ds_read_b128 v[208:211], v195 offset:52224
	ds_read_b128 v[212:215], v195 offset:53248
	ds_read_b128 v[216:219], v195 offset:54272
	ds_read_b128 v[220:223], v195 offset:55296
	ds_read_b128 v[224:227], v195 offset:56320
	global_load_lds_dwordx4 v[170:171], off
	s_add_i32 m0, s16, 0x2000
	s_add_u32 s16, s44, 0x28080
	v_lshl_add_u64 v[170:171], v[172:173], 0, s[24:25]
	s_addc_u32 s17, s45, 0
	s_add_i32 s29, s74, s4
	global_load_lds_dwordx4 v[170:171], off
	v_lshl_add_u64 v[170:171], s[16:17], 0, v[178:179]
	s_mov_b32 m0, s29
	s_nop 0
	global_load_lds_dwordx4 v[170:171], off
	v_lshl_add_u64 v[170:171], s[16:17], 0, v[174:175]
	s_add_i32 m0, s29, 0x2000
	s_nop 0
	global_load_lds_dwordx4 v[170:171], off
	v_lshl_add_u64 v[170:171], v[228:229], 0, s[24:25]
	s_mov_b32 m0, s31
	s_nop 0
	global_load_lds_dwordx4 v[170:171], off
	v_lshl_add_u64 v[170:171], v[230:231], 0, s[24:25]
	s_mov_b32 m0, s33
	s_nop 0
	global_load_lds_dwordx4 v[170:171], off
	s_waitcnt vmcnt(8)
	s_waitcnt lgkmcnt(0)
	s_setprio 1
	s_barrier
	v_mfma_f32_16x16x32_bf16 v[62:65], v[74:77], v[188:191], v[62:65]
	v_mfma_f32_16x16x32_bf16 v[58:61], v[138:141], v[188:191], v[58:61]
	v_mfma_f32_16x16x32_bf16 v[46:49], v[74:77], v[204:207], v[46:49]
	v_mfma_f32_16x16x32_bf16 v[42:45], v[138:141], v[204:207], v[42:45]
	v_mfma_f32_16x16x32_bf16 v[30:33], v[74:77], v[212:215], v[30:33]
	v_mfma_f32_16x16x32_bf16 v[26:29], v[138:141], v[212:215], v[26:29]
	v_mfma_f32_16x16x32_bf16 v[14:17], v[74:77], v[220:223], v[14:17]
	v_mfma_f32_16x16x32_bf16 v[10:13], v[138:141], v[220:223], v[10:13]
	v_mfma_f32_16x16x32_bf16 v[62:65], v[78:81], v[196:199], v[62:65]
	v_mfma_f32_16x16x32_bf16 v[58:61], v[142:145], v[196:199], v[58:61]
	v_mfma_f32_16x16x32_bf16 v[46:49], v[78:81], v[208:211], v[46:49]
	v_mfma_f32_16x16x32_bf16 v[42:45], v[142:145], v[208:211], v[42:45]
	v_mfma_f32_16x16x32_bf16 v[30:33], v[78:81], v[216:219], v[30:33]
	v_mfma_f32_16x16x32_bf16 v[26:29], v[142:145], v[216:219], v[26:29]
	v_mfma_f32_16x16x32_bf16 v[14:17], v[78:81], v[224:227], v[14:17]
	v_mfma_f32_16x16x32_bf16 v[10:13], v[142:145], v[224:227], v[10:13]
	v_mfma_f32_16x16x32_bf16 v[54:57], v[146:149], v[188:191], v[54:57]
	v_mfma_f32_16x16x32_bf16 v[50:53], v[154:157], v[188:191], v[50:53]
	v_mfma_f32_16x16x32_bf16 v[38:41], v[146:149], v[204:207], v[38:41]
	v_mfma_f32_16x16x32_bf16 v[34:37], v[154:157], v[204:207], v[34:37]
	v_mfma_f32_16x16x32_bf16 v[22:25], v[146:149], v[212:215], v[22:25]
	v_mfma_f32_16x16x32_bf16 v[18:21], v[154:157], v[212:215], v[18:21]
	v_mfma_f32_16x16x32_bf16 v[6:9], v[146:149], v[220:223], v[6:9]
	v_mfma_f32_16x16x32_bf16 v[2:5], v[154:157], v[220:223], v[2:5]
	v_mfma_f32_16x16x32_bf16 v[54:57], v[150:153], v[196:199], v[54:57]
	v_mfma_f32_16x16x32_bf16 v[50:53], v[158:161], v[196:199], v[50:53]
	v_mfma_f32_16x16x32_bf16 v[38:41], v[150:153], v[208:211], v[38:41]
	v_mfma_f32_16x16x32_bf16 v[34:37], v[158:161], v[208:211], v[34:37]
	v_mfma_f32_16x16x32_bf16 v[22:25], v[150:153], v[216:219], v[22:25]
	v_mfma_f32_16x16x32_bf16 v[18:21], v[158:161], v[216:219], v[18:21]
	v_mfma_f32_16x16x32_bf16 v[6:9], v[150:153], v[224:227], v[6:9]
	v_mfma_f32_16x16x32_bf16 v[2:5], v[158:161], v[224:227], v[2:5]
	s_barrier
	s_setprio 0
	s_add_u32 s72, s72, 0x100
	s_addc_u32 s73, s73, 0
	s_cmp_ge_i32 s37, s38
	s_mov_b64 s[16:17], s[42:43]
	s_mov_b32 s44, s37
	s_cbranch_scc0 .LBB7_886
	s_branch .Lpeelx_886
	.p2align	8

.Lpeel_963:
	s_add_i32 s37, s48, 2
	s_add_u32 s42, s16, 0x100
	s_addc_u32 s43, s17, 0
	s_add_i32 s29, 0, 0x10000
	s_cmp_eq_u32 s53, s48
	s_cselect_b32 s51, s38, s43
	s_cselect_b32 s50, s39, s42
	s_cselect_b32 s49, s56, s73
	s_cselect_b32 s48, s57, s72
	s_add_i32 s74, 0, 0x14000
	v_add_u32_e32 v142, s29, v197
	v_add_u32_e32 v158, s74, v197
	ds_read_b128 v[130:133], v142
	ds_read_b128 v[134:137], v142 offset:1024
	ds_read_b128 v[138:141], v142 offset:2048
	ds_read_b128 v[142:145], v142 offset:3072
	ds_read_b128 v[146:149], v158
	ds_read_b128 v[150:153], v158 offset:1024
	ds_read_b128 v[154:157], v158 offset:2048
	ds_read_b128 v[158:161], v158 offset:3072
	v_lshl_add_u64 v[170:171], s[16:17], 0, v[180:181]
	s_add_i32 m0, s5, 0xc000
	ds_read_b128 v[184:187], v199
	ds_read_b128 v[188:191], v199 offset:1024
	ds_read_b128 v[192:195], v199 offset:2048
	ds_read_b128 v[204:207], v199 offset:3072
	ds_read_b128 v[208:211], v199 offset:4096
	ds_read_b128 v[212:215], v199 offset:5120
	ds_read_b128 v[216:219], v199 offset:6144
	ds_read_b128 v[220:223], v199 offset:7168
	global_load_lds_dwordx4 v[170:171], off
	v_lshl_add_u64 v[170:171], s[16:17], 0, v[182:183]
	s_add_i32 m0, s5, 0xe000
	s_nop 0
	global_load_lds_dwordx4 v[170:171], off
	s_waitcnt vmcnt(8)
	s_waitcnt lgkmcnt(0)
	s_setprio 1
	s_barrier
	v_mfma_f32_16x16x32_bf16 v[126:129], v[130:133], v[184:187], 0
	v_mfma_f32_16x16x32_bf16 v[122:125], v[138:141], v[184:187], 0
	v_mfma_f32_16x16x32_bf16 v[110:113], v[130:133], v[192:195], 0
	v_mfma_f32_16x16x32_bf16 v[106:109], v[138:141], v[192:195], 0
	v_mfma_f32_16x16x32_bf16 v[94:97], v[130:133], v[208:211], 0
	v_mfma_f32_16x16x32_bf16 v[90:93], v[138:141], v[208:211], 0
	v_mfma_f32_16x16x32_bf16 v[78:81], v[130:133], v[216:219], 0
	v_mfma_f32_16x16x32_bf16 v[74:77], v[138:141], v[216:219], 0
	v_mfma_f32_16x16x32_bf16 v[126:129], v[134:137], v[188:191], v[126:129]
	v_mfma_f32_16x16x32_bf16 v[122:125], v[142:145], v[188:191], v[122:125]
	v_mfma_f32_16x16x32_bf16 v[110:113], v[134:137], v[204:207], v[110:113]
	v_mfma_f32_16x16x32_bf16 v[106:109], v[142:145], v[204:207], v[106:109]
	v_mfma_f32_16x16x32_bf16 v[94:97], v[134:137], v[212:215], v[94:97]
	v_mfma_f32_16x16x32_bf16 v[90:93], v[142:145], v[212:215], v[90:93]
	v_mfma_f32_16x16x32_bf16 v[78:81], v[134:137], v[220:223], v[78:81]
	v_mfma_f32_16x16x32_bf16 v[74:77], v[142:145], v[220:223], v[74:77]
	v_mfma_f32_16x16x32_bf16 v[118:121], v[146:149], v[184:187], 0
	v_mfma_f32_16x16x32_bf16 v[114:117], v[154:157], v[184:187], 0
	v_mfma_f32_16x16x32_bf16 v[102:105], v[146:149], v[192:195], 0
	v_mfma_f32_16x16x32_bf16 v[98:101], v[154:157], v[192:195], 0
	v_mfma_f32_16x16x32_bf16 v[86:89], v[146:149], v[208:211], 0
	v_mfma_f32_16x16x32_bf16 v[82:85], v[154:157], v[208:211], 0
	v_mfma_f32_16x16x32_bf16 v[70:73], v[146:149], v[216:219], 0
	v_mfma_f32_16x16x32_bf16 v[66:69], v[154:157], v[216:219], 0
	v_mfma_f32_16x16x32_bf16 v[118:121], v[150:153], v[188:191], v[118:121]
	v_mfma_f32_16x16x32_bf16 v[114:117], v[158:161], v[188:191], v[114:117]
	v_mfma_f32_16x16x32_bf16 v[102:105], v[150:153], v[204:207], v[102:105]
	v_mfma_f32_16x16x32_bf16 v[98:101], v[158:161], v[204:207], v[98:101]
	v_mfma_f32_16x16x32_bf16 v[86:89], v[150:153], v[212:215], v[86:89]
	v_mfma_f32_16x16x32_bf16 v[82:85], v[158:161], v[212:215], v[82:85]
	v_mfma_f32_16x16x32_bf16 v[70:73], v[150:153], v[220:223], v[70:73]
	v_mfma_f32_16x16x32_bf16 v[66:69], v[158:161], v[220:223], v[66:69]
	s_barrier
	s_setprio 0
	s_add_i32 s16, s29, s4
	v_lshl_add_u64 v[170:171], s[48:49], 0, v[0:1]
	s_mov_b32 m0, s16
	ds_read_b128 v[184:187], v199 offset:16384
	ds_read_b128 v[188:191], v199 offset:17408
	ds_read_b128 v[192:195], v199 offset:18432
	ds_read_b128 v[204:207], v199 offset:19456
	ds_read_b128 v[208:211], v199 offset:20480
	ds_read_b128 v[212:215], v199 offset:21504
	ds_read_b128 v[216:219], v199 offset:22528
	ds_read_b128 v[220:223], v199 offset:23552
	global_load_lds_dwordx4 v[170:171], off
	s_add_i32 m0, s16, 0x2000
	s_add_u32 s16, s48, 0x18000
	v_lshl_add_u64 v[172:173], s[48:49], 0, v[174:175]
	s_addc_u32 s17, s49, 0
	s_add_i32 s29, s74, s4
	global_load_lds_dwordx4 v[172:173], off
	v_lshl_add_u64 v[224:225], s[16:17], 0, v[0:1]
	s_mov_b32 m0, s29
	v_lshl_add_u64 v[226:227], s[50:51], 0, v[176:177]
	global_load_lds_dwordx4 v[224:225], off
	v_lshl_add_u64 v[224:225], s[16:17], 0, v[174:175]
	s_add_i32 m0, s29, 0x2000
	s_nop 0
	global_load_lds_dwordx4 v[224:225], off
	v_lshl_add_u64 v[224:225], s[50:51], 0, v[178:179]
	s_mov_b32 m0, s5
	s_nop 0
	global_load_lds_dwordx4 v[224:225], off
	s_mov_b32 m0, s20
	s_nop 0
	global_load_lds_dwordx4 v[226:227], off
	s_waitcnt vmcnt(8)
	s_waitcnt lgkmcnt(0)
	s_setprio 1
	s_barrier
	v_mfma_f32_16x16x32_bf16 v[62:65], v[130:133], v[184:187], 0
	v_mfma_f32_16x16x32_bf16 v[58:61], v[138:141], v[184:187], 0
	v_mfma_f32_16x16x32_bf16 v[46:49], v[130:133], v[192:195], 0
	v_mfma_f32_16x16x32_bf16 v[42:45], v[138:141], v[192:195], 0
	v_mfma_f32_16x16x32_bf16 v[30:33], v[130:133], v[208:211], 0
	v_mfma_f32_16x16x32_bf16 v[26:29], v[138:141], v[208:211], 0
	v_mfma_f32_16x16x32_bf16 v[14:17], v[130:133], v[216:219], 0
	v_mfma_f32_16x16x32_bf16 v[10:13], v[138:141], v[216:219], 0
	v_mfma_f32_16x16x32_bf16 v[62:65], v[134:137], v[188:191], v[62:65]
	v_mfma_f32_16x16x32_bf16 v[58:61], v[142:145], v[188:191], v[58:61]
	v_mfma_f32_16x16x32_bf16 v[46:49], v[134:137], v[204:207], v[46:49]
	v_mfma_f32_16x16x32_bf16 v[42:45], v[142:145], v[204:207], v[42:45]
	v_mfma_f32_16x16x32_bf16 v[30:33], v[134:137], v[212:215], v[30:33]
	v_mfma_f32_16x16x32_bf16 v[26:29], v[142:145], v[212:215], v[26:29]
	v_mfma_f32_16x16x32_bf16 v[14:17], v[134:137], v[220:223], v[14:17]
	v_mfma_f32_16x16x32_bf16 v[10:13], v[142:145], v[220:223], v[10:13]
	v_mfma_f32_16x16x32_bf16 v[54:57], v[146:149], v[184:187], 0
	v_mfma_f32_16x16x32_bf16 v[50:53], v[154:157], v[184:187], 0
	v_mfma_f32_16x16x32_bf16 v[38:41], v[146:149], v[192:195], 0
	v_mfma_f32_16x16x32_bf16 v[34:37], v[154:157], v[192:195], 0
	v_mfma_f32_16x16x32_bf16 v[22:25], v[146:149], v[208:211], 0
	v_mfma_f32_16x16x32_bf16 v[18:21], v[154:157], v[208:211], 0
	v_mfma_f32_16x16x32_bf16 v[6:9], v[146:149], v[216:219], 0
	v_mfma_f32_16x16x32_bf16 v[2:5], v[154:157], v[216:219], 0
	v_mfma_f32_16x16x32_bf16 v[54:57], v[150:153], v[188:191], v[54:57]
	v_mfma_f32_16x16x32_bf16 v[50:53], v[158:161], v[188:191], v[50:53]
	v_mfma_f32_16x16x32_bf16 v[38:41], v[150:153], v[204:207], v[38:41]
	v_mfma_f32_16x16x32_bf16 v[34:37], v[158:161], v[204:207], v[34:37]
	v_mfma_f32_16x16x32_bf16 v[22:25], v[150:153], v[212:215], v[22:25]
	v_mfma_f32_16x16x32_bf16 v[18:21], v[158:161], v[212:215], v[18:21]
	v_mfma_f32_16x16x32_bf16 v[6:9], v[150:153], v[220:223], v[6:9]
	v_mfma_f32_16x16x32_bf16 v[2:5], v[158:161], v[220:223], v[2:5]
	s_barrier
	s_setprio 0
	s_add_i32 s29, 0, 0x18000
	s_add_i32 s74, 0, 0x1c000
	v_add_u32_e32 v142, s29, v197
	v_add_u32_e32 v158, s74, v197
	ds_read_b128 v[130:133], v142
	ds_read_b128 v[134:137], v142 offset:1024
	ds_read_b128 v[138:141], v142 offset:2048
	ds_read_b128 v[142:145], v142 offset:3072
	ds_read_b128 v[146:149], v158
	ds_read_b128 v[150:153], v158 offset:1024
	ds_read_b128 v[154:157], v158 offset:2048
	ds_read_b128 v[158:161], v158 offset:3072
	s_add_u32 s16, s50, 0x18000
	s_addc_u32 s17, s51, 0
	s_mov_b32 m0, s22
	v_lshl_add_u64 v[228:229], s[16:17], 0, v[178:179]
	ds_read_b128 v[184:187], v199 offset:32768
	ds_read_b128 v[188:191], v199 offset:33792
	ds_read_b128 v[192:195], v199 offset:34816
	ds_read_b128 v[204:207], v199 offset:35840
	ds_read_b128 v[208:211], v199 offset:36864
	ds_read_b128 v[212:215], v199 offset:37888
	ds_read_b128 v[216:219], v199 offset:38912
	ds_read_b128 v[220:223], v199 offset:39936
	global_load_lds_dwordx4 v[228:229], off
	v_lshl_add_u64 v[228:229], s[16:17], 0, v[176:177]
	s_mov_b32 m0, s23
	s_nop 0
	global_load_lds_dwordx4 v[228:229], off
	s_waitcnt vmcnt(8)
	s_waitcnt lgkmcnt(0)
	s_setprio 1
	s_barrier
	v_mfma_f32_16x16x32_bf16 v[126:129], v[130:133], v[184:187], v[126:129]
	v_mfma_f32_16x16x32_bf16 v[122:125], v[138:141], v[184:187], v[122:125]
	v_mfma_f32_16x16x32_bf16 v[110:113], v[130:133], v[192:195], v[110:113]
	v_mfma_f32_16x16x32_bf16 v[106:109], v[138:141], v[192:195], v[106:109]
	v_mfma_f32_16x16x32_bf16 v[94:97], v[130:133], v[208:211], v[94:97]
	v_mfma_f32_16x16x32_bf16 v[90:93], v[138:141], v[208:211], v[90:93]
	v_mfma_f32_16x16x32_bf16 v[78:81], v[130:133], v[216:219], v[78:81]
	v_mfma_f32_16x16x32_bf16 v[74:77], v[138:141], v[216:219], v[74:77]
	v_mfma_f32_16x16x32_bf16 v[126:129], v[134:137], v[188:191], v[126:129]
	v_mfma_f32_16x16x32_bf16 v[122:125], v[142:145], v[188:191], v[122:125]
	v_mfma_f32_16x16x32_bf16 v[110:113], v[134:137], v[204:207], v[110:113]
	v_mfma_f32_16x16x32_bf16 v[106:109], v[142:145], v[204:207], v[106:109]
	v_mfma_f32_16x16x32_bf16 v[94:97], v[134:137], v[212:215], v[94:97]
	v_mfma_f32_16x16x32_bf16 v[90:93], v[142:145], v[212:215], v[90:93]
	v_mfma_f32_16x16x32_bf16 v[78:81], v[134:137], v[220:223], v[78:81]
	v_mfma_f32_16x16x32_bf16 v[74:77], v[142:145], v[220:223], v[74:77]
	v_mfma_f32_16x16x32_bf16 v[118:121], v[146:149], v[184:187], v[118:121]
	v_mfma_f32_16x16x32_bf16 v[114:117], v[154:157], v[184:187], v[114:117]
	v_mfma_f32_16x16x32_bf16 v[102:105], v[146:149], v[192:195], v[102:105]
	v_mfma_f32_16x16x32_bf16 v[98:101], v[154:157], v[192:195], v[98:101]
	v_mfma_f32_16x16x32_bf16 v[86:89], v[146:149], v[208:211], v[86:89]
	v_mfma_f32_16x16x32_bf16 v[82:85], v[154:157], v[208:211], v[82:85]
	v_mfma_f32_16x16x32_bf16 v[70:73], v[146:149], v[216:219], v[70:73]
	v_mfma_f32_16x16x32_bf16 v[66:69], v[154:157], v[216:219], v[66:69]
	v_mfma_f32_16x16x32_bf16 v[118:121], v[150:153], v[188:191], v[118:121]
	v_mfma_f32_16x16x32_bf16 v[114:117], v[158:161], v[188:191], v[114:117]
	v_mfma_f32_16x16x32_bf16 v[102:105], v[150:153], v[204:207], v[102:105]
	v_mfma_f32_16x16x32_bf16 v[98:101], v[158:161], v[204:207], v[98:101]
	v_mfma_f32_16x16x32_bf16 v[86:89], v[150:153], v[212:215], v[86:89]
	v_mfma_f32_16x16x32_bf16 v[82:85], v[158:161], v[212:215], v[82:85]
	v_mfma_f32_16x16x32_bf16 v[70:73], v[150:153], v[220:223], v[70:73]
	v_mfma_f32_16x16x32_bf16 v[66:69], v[158:161], v[220:223], v[66:69]
	s_barrier
	s_setprio 0
	s_add_i32 s16, s29, s4
	v_lshl_add_u64 v[170:171], v[170:171], 0, s[24:25]
	s_mov_b32 m0, s16
	ds_read_b128 v[184:187], v199 offset:49152
	ds_read_b128 v[188:191], v199 offset:50176
	ds_read_b128 v[192:195], v199 offset:51200
	ds_read_b128 v[204:207], v199 offset:52224
	ds_read_b128 v[208:211], v199 offset:53248
	ds_read_b128 v[212:215], v199 offset:54272
	ds_read_b128 v[216:219], v199 offset:55296
	ds_read_b128 v[220:223], v199 offset:56320
	global_load_lds_dwordx4 v[170:171], off
	s_add_i32 m0, s16, 0x2000
	s_add_u32 s16, s48, 0x18080
	v_lshl_add_u64 v[170:171], v[172:173], 0, s[24:25]
	s_addc_u32 s17, s49, 0
	s_add_i32 s29, s74, s4
	global_load_lds_dwordx4 v[170:171], off
	v_lshl_add_u64 v[170:171], s[16:17], 0, v[0:1]
	s_mov_b32 m0, s29
	s_nop 0
	global_load_lds_dwordx4 v[170:171], off
	v_lshl_add_u64 v[170:171], s[16:17], 0, v[174:175]
	s_add_i32 m0, s29, 0x2000
	s_nop 0
	global_load_lds_dwordx4 v[170:171], off
	v_lshl_add_u64 v[170:171], v[224:225], 0, s[24:25]
	s_mov_b32 m0, s31
	s_nop 0
	global_load_lds_dwordx4 v[170:171], off
	v_lshl_add_u64 v[170:171], v[226:227], 0, s[24:25]
	s_mov_b32 m0, s33
	s_nop 0
	global_load_lds_dwordx4 v[170:171], off
	s_waitcnt vmcnt(8)
	s_waitcnt lgkmcnt(0)
	s_setprio 1
	s_barrier
	v_mfma_f32_16x16x32_bf16 v[62:65], v[130:133], v[184:187], v[62:65]
	v_mfma_f32_16x16x32_bf16 v[58:61], v[138:141], v[184:187], v[58:61]
	v_mfma_f32_16x16x32_bf16 v[46:49], v[130:133], v[192:195], v[46:49]
	v_mfma_f32_16x16x32_bf16 v[42:45], v[138:141], v[192:195], v[42:45]
	v_mfma_f32_16x16x32_bf16 v[30:33], v[130:133], v[208:211], v[30:33]
	v_mfma_f32_16x16x32_bf16 v[26:29], v[138:141], v[208:211], v[26:29]
	v_mfma_f32_16x16x32_bf16 v[14:17], v[130:133], v[216:219], v[14:17]
	v_mfma_f32_16x16x32_bf16 v[10:13], v[138:141], v[216:219], v[10:13]
	v_mfma_f32_16x16x32_bf16 v[62:65], v[134:137], v[188:191], v[62:65]
	v_mfma_f32_16x16x32_bf16 v[58:61], v[142:145], v[188:191], v[58:61]
	v_mfma_f32_16x16x32_bf16 v[46:49], v[134:137], v[204:207], v[46:49]
	v_mfma_f32_16x16x32_bf16 v[42:45], v[142:145], v[204:207], v[42:45]
	v_mfma_f32_16x16x32_bf16 v[30:33], v[134:137], v[212:215], v[30:33]
	v_mfma_f32_16x16x32_bf16 v[26:29], v[142:145], v[212:215], v[26:29]
	v_mfma_f32_16x16x32_bf16 v[14:17], v[134:137], v[220:223], v[14:17]
	v_mfma_f32_16x16x32_bf16 v[10:13], v[142:145], v[220:223], v[10:13]
	v_mfma_f32_16x16x32_bf16 v[54:57], v[146:149], v[184:187], v[54:57]
	v_mfma_f32_16x16x32_bf16 v[50:53], v[154:157], v[184:187], v[50:53]
	v_mfma_f32_16x16x32_bf16 v[38:41], v[146:149], v[192:195], v[38:41]
	v_mfma_f32_16x16x32_bf16 v[34:37], v[154:157], v[192:195], v[34:37]
	v_mfma_f32_16x16x32_bf16 v[22:25], v[146:149], v[208:211], v[22:25]
	v_mfma_f32_16x16x32_bf16 v[18:21], v[154:157], v[208:211], v[18:21]
	v_mfma_f32_16x16x32_bf16 v[6:9], v[146:149], v[216:219], v[6:9]
	v_mfma_f32_16x16x32_bf16 v[2:5], v[154:157], v[216:219], v[2:5]
	v_mfma_f32_16x16x32_bf16 v[54:57], v[150:153], v[188:191], v[54:57]
	v_mfma_f32_16x16x32_bf16 v[50:53], v[158:161], v[188:191], v[50:53]
	v_mfma_f32_16x16x32_bf16 v[38:41], v[150:153], v[204:207], v[38:41]
	v_mfma_f32_16x16x32_bf16 v[34:37], v[158:161], v[204:207], v[34:37]
	v_mfma_f32_16x16x32_bf16 v[22:25], v[150:153], v[212:215], v[22:25]
	v_mfma_f32_16x16x32_bf16 v[18:21], v[158:161], v[212:215], v[18:21]
	v_mfma_f32_16x16x32_bf16 v[6:9], v[150:153], v[220:223], v[6:9]
	v_mfma_f32_16x16x32_bf16 v[2:5], v[158:161], v[220:223], v[2:5]
	s_barrier
	s_setprio 0
	s_add_u32 s72, s72, 0x100
	s_addc_u32 s73, s73, 0
	s_cmp_ge_i32 s37, s3
	s_mov_b64 s[16:17], s[42:43]
	s_mov_b32 s48, s37
	s_cbranch_scc0 .LBB7_963
	s_branch .Lpeelx_963
	.p2align	8

.Lpeel_1104:
	s_add_i32 s74, s72, 2
	s_add_u32 s75, vcc_lo, 0xfffc0080
	s_addc_u32 s73, vcc_hi, -1
	s_add_i32 s76, 0, 0x10000
	s_cmp_eq_u32 s39, s72
	s_cselect_b32 s73, s19, s73
	s_cselect_b32 s72, s20, s75
	v_add_u32_e32 v0, s76, v205
	s_cselect_b32 s85, s28, s49
	s_cselect_b32 s84, s29, s37
	s_add_i32 s75, 0, 0x14000
	ds_read_b128 v[132:135], v0
	ds_read_b128 v[136:139], v0 offset:1024
	ds_read_b128 v[140:143], v0 offset:2048
	ds_read_b128 v[144:147], v0 offset:3072
	v_add_u32_e32 v0, s75, v205
	ds_read_b128 v[148:151], v0
	ds_read_b128 v[152:155], v0 offset:1024
	ds_read_b128 v[156:159], v0 offset:2048
	ds_read_b128 v[184:187], v0 offset:3072
	s_waitcnt lgkmcnt(0)
	s_add_i32 m0, s5, 0xc000
	ds_read_b128 v[188:191], v207
	ds_read_b128 v[192:195], v207 offset:1024
	ds_read_b128 v[196:199], v207 offset:2048
	ds_read_b128 v[208:211], v207 offset:3072
	ds_read_b128 v[212:215], v207 offset:4096
	ds_read_b128 v[216:219], v207 offset:5120
	ds_read_b128 v[220:223], v207 offset:6144
	ds_read_b128 v[224:227], v207 offset:7168
	global_load_lds_dwordx4 v180, vcc
	s_add_i32 m0, s5, 0xe000
	s_nop 0
	global_load_lds_dwordx4 v182, vcc
	s_waitcnt vmcnt(8)
	s_waitcnt lgkmcnt(0)
	s_setprio 1
	s_barrier
	v_mfma_f32_16x16x32_bf16 v[128:131], v[132:135], v[188:191], 0
	v_mfma_f32_16x16x32_bf16 v[124:127], v[140:143], v[188:191], 0
	v_mfma_f32_16x16x32_bf16 v[120:123], v[132:135], v[196:199], 0
	v_mfma_f32_16x16x32_bf16 v[116:119], v[140:143], v[196:199], 0
	v_mfma_f32_16x16x32_bf16 v[112:115], v[132:135], v[212:215], 0
	v_mfma_f32_16x16x32_bf16 v[108:111], v[140:143], v[212:215], 0
	v_mfma_f32_16x16x32_bf16 v[104:107], v[132:135], v[220:223], 0
	v_mfma_f32_16x16x32_bf16 v[100:103], v[140:143], v[220:223], 0
	v_mfma_f32_16x16x32_bf16 v[128:131], v[136:139], v[192:195], v[128:131]
	v_mfma_f32_16x16x32_bf16 v[124:127], v[144:147], v[192:195], v[124:127]
	v_mfma_f32_16x16x32_bf16 v[120:123], v[136:139], v[208:211], v[120:123]
	v_mfma_f32_16x16x32_bf16 v[116:119], v[144:147], v[208:211], v[116:119]
	v_mfma_f32_16x16x32_bf16 v[112:115], v[136:139], v[216:219], v[112:115]
	v_mfma_f32_16x16x32_bf16 v[108:111], v[144:147], v[216:219], v[108:111]
	v_mfma_f32_16x16x32_bf16 v[104:107], v[136:139], v[224:227], v[104:107]
	v_mfma_f32_16x16x32_bf16 v[100:103], v[144:147], v[224:227], v[100:103]
	v_mfma_f32_16x16x32_bf16 v[96:99], v[148:151], v[188:191], 0
	v_mfma_f32_16x16x32_bf16 v[92:95], v[156:159], v[188:191], 0
	v_mfma_f32_16x16x32_bf16 v[88:91], v[148:151], v[196:199], 0
	v_mfma_f32_16x16x32_bf16 v[84:87], v[156:159], v[196:199], 0
	v_mfma_f32_16x16x32_bf16 v[80:83], v[148:151], v[212:215], 0
	v_mfma_f32_16x16x32_bf16 v[76:79], v[156:159], v[212:215], 0
	v_mfma_f32_16x16x32_bf16 v[72:75], v[148:151], v[220:223], 0
	v_mfma_f32_16x16x32_bf16 v[68:71], v[156:159], v[220:223], 0
	v_mfma_f32_16x16x32_bf16 v[96:99], v[152:155], v[192:195], v[96:99]
	v_mfma_f32_16x16x32_bf16 v[92:95], v[184:187], v[192:195], v[92:95]
	v_mfma_f32_16x16x32_bf16 v[88:91], v[152:155], v[208:211], v[88:91]
	v_mfma_f32_16x16x32_bf16 v[84:87], v[184:187], v[208:211], v[84:87]
	v_mfma_f32_16x16x32_bf16 v[80:83], v[152:155], v[216:219], v[80:83]
	v_mfma_f32_16x16x32_bf16 v[76:79], v[184:187], v[216:219], v[76:79]
	v_mfma_f32_16x16x32_bf16 v[72:75], v[152:155], v[224:227], v[72:75]
	v_mfma_f32_16x16x32_bf16 v[68:71], v[184:187], v[224:227], v[68:71]
	s_barrier
	s_setprio 0
	s_add_i32 s76, s76, s4
	v_lshl_add_u64 v[170:171], s[84:85], 0, v[176:177]
	s_mov_b32 m0, s76
	ds_read_b128 v[188:191], v207 offset:16384
	ds_read_b128 v[192:195], v207 offset:17408
	ds_read_b128 v[196:199], v207 offset:18432
	ds_read_b128 v[208:211], v207 offset:19456
	ds_read_b128 v[212:215], v207 offset:20480
	ds_read_b128 v[216:219], v207 offset:21504
	ds_read_b128 v[220:223], v207 offset:22528
	ds_read_b128 v[224:227], v207 offset:23552
	global_load_lds_dwordx4 v[170:171], off
	s_add_i32 m0, s76, 0x2000
	s_add_u32 s76, s84, 0x40000
	v_lshl_add_u64 v[172:173], s[84:85], 0, v[160:161]
	s_addc_u32 s77, s85, 0
	s_add_i32 s75, s75, s4
	global_load_lds_dwordx4 v[172:173], off
	s_mov_b32 m0, s75
	v_lshl_add_u64 v[228:229], s[72:73], 0, v[178:179]
	global_load_lds_dwordx4 v176, s[76:77]
	s_add_i32 m0, s75, 0x2000
	v_lshl_add_u64 v[230:231], s[72:73], 0, v[174:175]
	global_load_lds_dwordx4 v160, s[76:77]
	s_mov_b32 m0, s5
	s_nop 0
	global_load_lds_dwordx4 v[228:229], off
	s_mov_b32 m0, s22
	s_nop 0
	global_load_lds_dwordx4 v[230:231], off
	s_waitcnt vmcnt(8)
	s_waitcnt lgkmcnt(0)
	s_setprio 1
	s_barrier
	v_mfma_f32_16x16x32_bf16 v[64:67], v[132:135], v[188:191], 0
	v_mfma_f32_16x16x32_bf16 v[60:63], v[140:143], v[188:191], 0
	v_mfma_f32_16x16x32_bf16 v[56:59], v[132:135], v[196:199], 0
	v_mfma_f32_16x16x32_bf16 v[52:55], v[140:143], v[196:199], 0
	v_mfma_f32_16x16x32_bf16 v[48:51], v[132:135], v[212:215], 0
	v_mfma_f32_16x16x32_bf16 v[44:47], v[140:143], v[212:215], 0
	v_mfma_f32_16x16x32_bf16 v[40:43], v[132:135], v[220:223], 0
	v_mfma_f32_16x16x32_bf16 v[36:39], v[140:143], v[220:223], 0
	v_mfma_f32_16x16x32_bf16 v[64:67], v[136:139], v[192:195], v[64:67]
	v_mfma_f32_16x16x32_bf16 v[60:63], v[144:147], v[192:195], v[60:63]
	v_mfma_f32_16x16x32_bf16 v[56:59], v[136:139], v[208:211], v[56:59]
	v_mfma_f32_16x16x32_bf16 v[52:55], v[144:147], v[208:211], v[52:55]
	v_mfma_f32_16x16x32_bf16 v[48:51], v[136:139], v[216:219], v[48:51]
	v_mfma_f32_16x16x32_bf16 v[44:47], v[144:147], v[216:219], v[44:47]
	v_mfma_f32_16x16x32_bf16 v[40:43], v[136:139], v[224:227], v[40:43]
	v_mfma_f32_16x16x32_bf16 v[36:39], v[144:147], v[224:227], v[36:39]
	v_mfma_f32_16x16x32_bf16 v[32:35], v[148:151], v[188:191], 0
	v_mfma_f32_16x16x32_bf16 v[28:31], v[156:159], v[188:191], 0
	v_mfma_f32_16x16x32_bf16 v[24:27], v[148:151], v[196:199], 0
	v_mfma_f32_16x16x32_bf16 v[20:23], v[156:159], v[196:199], 0
	v_mfma_f32_16x16x32_bf16 v[16:19], v[148:151], v[212:215], 0
	v_mfma_f32_16x16x32_bf16 v[12:15], v[156:159], v[212:215], 0
	v_mfma_f32_16x16x32_bf16 v[8:11], v[148:151], v[220:223], 0
	v_mfma_f32_16x16x32_bf16 v[2:5], v[156:159], v[220:223], 0
	v_mfma_f32_16x16x32_bf16 v[32:35], v[152:155], v[192:195], v[32:35]
	v_mfma_f32_16x16x32_bf16 v[28:31], v[184:187], v[192:195], v[28:31]
	v_mfma_f32_16x16x32_bf16 v[24:27], v[152:155], v[208:211], v[24:27]
	v_mfma_f32_16x16x32_bf16 v[20:23], v[184:187], v[208:211], v[20:23]
	v_mfma_f32_16x16x32_bf16 v[16:19], v[152:155], v[216:219], v[16:19]
	v_mfma_f32_16x16x32_bf16 v[12:15], v[184:187], v[216:219], v[12:15]
	v_mfma_f32_16x16x32_bf16 v[8:11], v[152:155], v[224:227], v[8:11]
	v_mfma_f32_16x16x32_bf16 v[2:5], v[184:187], v[224:227], v[2:5]
	s_barrier
	s_setprio 0
	s_add_i32 s75, 0, 0x18000
	v_add_u32_e32 v0, s75, v205
	s_add_i32 s76, 0, 0x1c000
	ds_read_b128 v[132:135], v0
	ds_read_b128 v[136:139], v0 offset:1024
	ds_read_b128 v[140:143], v0 offset:2048
	ds_read_b128 v[144:147], v0 offset:3072
	v_add_u32_e32 v0, s76, v205
	ds_read_b128 v[148:151], v0
	ds_read_b128 v[152:155], v0 offset:1024
	ds_read_b128 v[156:159], v0 offset:2048
	ds_read_b128 v[184:187], v0 offset:3072
	s_add_u32 s72, s72, 0x40000
	s_addc_u32 s73, s73, 0
	s_mov_b32 m0, s23
	ds_read_b128 v[188:191], v207 offset:32768
	ds_read_b128 v[192:195], v207 offset:33792
	ds_read_b128 v[196:199], v207 offset:34816
	ds_read_b128 v[208:211], v207 offset:35840
	ds_read_b128 v[212:215], v207 offset:36864
	ds_read_b128 v[216:219], v207 offset:37888
	ds_read_b128 v[220:223], v207 offset:38912
	ds_read_b128 v[224:227], v207 offset:39936
	global_load_lds_dwordx4 v178, s[72:73]
	s_mov_b32 m0, s31
	s_nop 0
	global_load_lds_dwordx4 v174, s[72:73]
	s_waitcnt vmcnt(8)
	s_waitcnt lgkmcnt(0)
	s_setprio 1
	s_barrier
	v_mfma_f32_16x16x32_bf16 v[128:131], v[132:135], v[188:191], v[128:131]
	v_mfma_f32_16x16x32_bf16 v[124:127], v[140:143], v[188:191], v[124:127]
	v_mfma_f32_16x16x32_bf16 v[120:123], v[132:135], v[196:199], v[120:123]
	v_mfma_f32_16x16x32_bf16 v[116:119], v[140:143], v[196:199], v[116:119]
	v_mfma_f32_16x16x32_bf16 v[112:115], v[132:135], v[212:215], v[112:115]
	v_mfma_f32_16x16x32_bf16 v[108:111], v[140:143], v[212:215], v[108:111]
	v_mfma_f32_16x16x32_bf16 v[104:107], v[132:135], v[220:223], v[104:107]
	v_mfma_f32_16x16x32_bf16 v[100:103], v[140:143], v[220:223], v[100:103]
	v_mfma_f32_16x16x32_bf16 v[128:131], v[136:139], v[192:195], v[128:131]
	v_mfma_f32_16x16x32_bf16 v[124:127], v[144:147], v[192:195], v[124:127]
	v_mfma_f32_16x16x32_bf16 v[120:123], v[136:139], v[208:211], v[120:123]
	v_mfma_f32_16x16x32_bf16 v[116:119], v[144:147], v[208:211], v[116:119]
	v_mfma_f32_16x16x32_bf16 v[112:115], v[136:139], v[216:219], v[112:115]
	v_mfma_f32_16x16x32_bf16 v[108:111], v[144:147], v[216:219], v[108:111]
	v_mfma_f32_16x16x32_bf16 v[104:107], v[136:139], v[224:227], v[104:107]
	v_mfma_f32_16x16x32_bf16 v[100:103], v[144:147], v[224:227], v[100:103]
	v_mfma_f32_16x16x32_bf16 v[96:99], v[148:151], v[188:191], v[96:99]
	v_mfma_f32_16x16x32_bf16 v[92:95], v[156:159], v[188:191], v[92:95]
	v_mfma_f32_16x16x32_bf16 v[88:91], v[148:151], v[196:199], v[88:91]
	v_mfma_f32_16x16x32_bf16 v[84:87], v[156:159], v[196:199], v[84:87]
	v_mfma_f32_16x16x32_bf16 v[80:83], v[148:151], v[212:215], v[80:83]
	v_mfma_f32_16x16x32_bf16 v[76:79], v[156:159], v[212:215], v[76:79]
	v_mfma_f32_16x16x32_bf16 v[72:75], v[148:151], v[220:223], v[72:75]
	v_mfma_f32_16x16x32_bf16 v[68:71], v[156:159], v[220:223], v[68:71]
	v_mfma_f32_16x16x32_bf16 v[96:99], v[152:155], v[192:195], v[96:99]
	v_mfma_f32_16x16x32_bf16 v[92:95], v[184:187], v[192:195], v[92:95]
	v_mfma_f32_16x16x32_bf16 v[88:91], v[152:155], v[208:211], v[88:91]
	v_mfma_f32_16x16x32_bf16 v[84:87], v[184:187], v[208:211], v[84:87]
	v_mfma_f32_16x16x32_bf16 v[80:83], v[152:155], v[216:219], v[80:83]
	v_mfma_f32_16x16x32_bf16 v[76:79], v[184:187], v[216:219], v[76:79]
	v_mfma_f32_16x16x32_bf16 v[72:75], v[152:155], v[224:227], v[72:75]
	v_mfma_f32_16x16x32_bf16 v[68:71], v[184:187], v[224:227], v[68:71]
	s_barrier
	s_setprio 0
	s_add_i32 s72, s75, s4
	v_lshl_add_u64 v[6:7], v[170:171], 0, s[24:25]
	s_mov_b32 m0, s72
	ds_read_b128 v[188:191], v207 offset:49152
	ds_read_b128 v[192:195], v207 offset:50176
	ds_read_b128 v[196:199], v207 offset:51200
	ds_read_b128 v[208:211], v207 offset:52224
	ds_read_b128 v[212:215], v207 offset:53248
	ds_read_b128 v[216:219], v207 offset:54272
	ds_read_b128 v[220:223], v207 offset:55296
	ds_read_b128 v[224:227], v207 offset:56320
	global_load_lds_dwordx4 v[6:7], off
	s_add_i32 m0, s72, 0x2000
	s_add_u32 s72, s84, 0x40080
	v_lshl_add_u64 v[6:7], v[172:173], 0, s[24:25]
	s_addc_u32 s73, s85, 0
	s_add_i32 s75, s76, s4
	global_load_lds_dwordx4 v[6:7], off
	s_mov_b32 m0, s75
	s_nop 0
	global_load_lds_dwordx4 v176, s[72:73]
	s_add_i32 m0, s75, 0x2000
	s_nop 0
	global_load_lds_dwordx4 v160, s[72:73]
	v_lshl_add_u64 v[6:7], v[228:229], 0, s[24:25]
	s_mov_b32 m0, s33
	s_nop 0
	global_load_lds_dwordx4 v[6:7], off
	v_lshl_add_u64 v[6:7], v[230:231], 0, s[24:25]
	s_mov_b32 m0, s38
	s_nop 0
	global_load_lds_dwordx4 v[6:7], off
	s_waitcnt vmcnt(8)
	s_waitcnt lgkmcnt(0)
	s_setprio 1
	s_barrier
	v_mfma_f32_16x16x32_bf16 v[64:67], v[132:135], v[188:191], v[64:67]
	v_mfma_f32_16x16x32_bf16 v[60:63], v[140:143], v[188:191], v[60:63]
	v_mfma_f32_16x16x32_bf16 v[56:59], v[132:135], v[196:199], v[56:59]
	v_mfma_f32_16x16x32_bf16 v[52:55], v[140:143], v[196:199], v[52:55]
	v_mfma_f32_16x16x32_bf16 v[48:51], v[132:135], v[212:215], v[48:51]
	v_mfma_f32_16x16x32_bf16 v[44:47], v[140:143], v[212:215], v[44:47]
	v_mfma_f32_16x16x32_bf16 v[40:43], v[132:135], v[220:223], v[40:43]
	v_mfma_f32_16x16x32_bf16 v[36:39], v[140:143], v[220:223], v[36:39]
	v_mfma_f32_16x16x32_bf16 v[64:67], v[136:139], v[192:195], v[64:67]
	v_mfma_f32_16x16x32_bf16 v[60:63], v[144:147], v[192:195], v[60:63]
	v_mfma_f32_16x16x32_bf16 v[56:59], v[136:139], v[208:211], v[56:59]
	v_mfma_f32_16x16x32_bf16 v[52:55], v[144:147], v[208:211], v[52:55]
	v_mfma_f32_16x16x32_bf16 v[48:51], v[136:139], v[216:219], v[48:51]
	v_mfma_f32_16x16x32_bf16 v[44:47], v[144:147], v[216:219], v[44:47]
	v_mfma_f32_16x16x32_bf16 v[40:43], v[136:139], v[224:227], v[40:43]
	v_mfma_f32_16x16x32_bf16 v[36:39], v[144:147], v[224:227], v[36:39]
	v_mfma_f32_16x16x32_bf16 v[32:35], v[148:151], v[188:191], v[32:35]
	v_mfma_f32_16x16x32_bf16 v[28:31], v[156:159], v[188:191], v[28:31]
	v_mfma_f32_16x16x32_bf16 v[24:27], v[148:151], v[196:199], v[24:27]
	v_mfma_f32_16x16x32_bf16 v[20:23], v[156:159], v[196:199], v[20:23]
	v_mfma_f32_16x16x32_bf16 v[16:19], v[148:151], v[212:215], v[16:19]
	v_mfma_f32_16x16x32_bf16 v[12:15], v[156:159], v[212:215], v[12:15]
	v_mfma_f32_16x16x32_bf16 v[6:9], v[148:151], v[220:223], v[8:11]
	v_mfma_f32_16x16x32_bf16 v[2:5], v[156:159], v[220:223], v[2:5]
	v_mfma_f32_16x16x32_bf16 v[32:35], v[152:155], v[192:195], v[32:35]
	v_mfma_f32_16x16x32_bf16 v[28:31], v[184:187], v[192:195], v[28:31]
	v_mfma_f32_16x16x32_bf16 v[24:27], v[152:155], v[208:211], v[24:27]
	v_mfma_f32_16x16x32_bf16 v[20:23], v[184:187], v[208:211], v[20:23]
	v_mfma_f32_16x16x32_bf16 v[16:19], v[152:155], v[216:219], v[16:19]
	v_mfma_f32_16x16x32_bf16 v[12:15], v[184:187], v[216:219], v[12:15]
	v_mfma_f32_16x16x32_bf16 v[8:11], v[152:155], v[224:227], v[6:9]
	v_mfma_f32_16x16x32_bf16 v[4:7], v[184:187], v[224:227], v[2:5]
	s_barrier
	s_setprio 0
	s_add_u32 s37, s37, 0x100
	s_addc_u32 s49, s49, 0
	s_add_u32 vcc_lo, vcc_lo, 0x100
	s_addc_u32 vcc_hi, vcc_hi, 0
	s_cmp_ge_i32 s74, s3
	s_mov_b32 s72, s74
	s_cbranch_scc0 .LBB7_1104
	s_branch .Lpeelx_1104
	.p2align	8

.Lpeel_1196:
	s_add_i32 s72, s42, 2
	s_add_u32 s29, s16, 0xfffc0080
	s_addc_u32 s37, s17, -1
	s_add_i32 s73, 0, 0x10000
	s_cmp_eq_u32 s55, s42
	s_cselect_b32 s53, s13, s37
	s_cselect_b32 s52, s15, s29
	v_add_u32_e32 v146, s73, v153
	s_cselect_b32 s43, s28, s57
	s_cselect_b32 s42, s39, s56
	s_add_i32 s29, 0, 0x14000
	ds_read_b128 v[130:133], v146
	ds_read_b128 v[156:159], v146 offset:1024
	ds_read_b128 v[174:177], v146 offset:2048
	ds_read_b128 v[178:181], v146 offset:3072
	v_add_u32_e32 v146, s29, v153
	ds_read_b128 v[182:185], v146
	ds_read_b128 v[186:189], v146 offset:1024
	ds_read_b128 v[190:193], v146 offset:2048
	ds_read_b128 v[194:197], v146 offset:3072
	s_add_i32 m0, s5, 0xc000
	ds_read_b128 v[204:207], v161
	ds_read_b128 v[208:211], v161 offset:1024
	ds_read_b128 v[212:215], v161 offset:2048
	ds_read_b128 v[216:219], v161 offset:3072
	ds_read_b128 v[220:223], v161 offset:4096
	ds_read_b128 v[224:227], v161 offset:5120
	ds_read_b128 v[228:231], v161 offset:6144
	ds_read_b128 v[232:235], v161 offset:7168
	global_load_lds_dwordx4 v142, s[16:17]
	s_add_i32 m0, s5, 0xe000
	s_nop 0
	global_load_lds_dwordx4 v144, s[16:17]
	s_waitcnt vmcnt(8)
	s_waitcnt lgkmcnt(0)
	s_setprio 1
	s_barrier
	v_mfma_f32_16x16x32_bf16 v[126:129], v[130:133], v[204:207], 0
	v_mfma_f32_16x16x32_bf16 v[122:125], v[174:177], v[204:207], 0
	v_mfma_f32_16x16x32_bf16 v[110:113], v[130:133], v[212:215], 0
	v_mfma_f32_16x16x32_bf16 v[106:109], v[174:177], v[212:215], 0
	v_mfma_f32_16x16x32_bf16 v[94:97], v[130:133], v[220:223], 0
	v_mfma_f32_16x16x32_bf16 v[90:93], v[174:177], v[220:223], 0
	v_mfma_f32_16x16x32_bf16 v[78:81], v[130:133], v[228:231], 0
	v_mfma_f32_16x16x32_bf16 v[74:77], v[174:177], v[228:231], 0
	v_mfma_f32_16x16x32_bf16 v[126:129], v[156:159], v[208:211], v[126:129]
	v_mfma_f32_16x16x32_bf16 v[122:125], v[178:181], v[208:211], v[122:125]
	v_mfma_f32_16x16x32_bf16 v[110:113], v[156:159], v[216:219], v[110:113]
	v_mfma_f32_16x16x32_bf16 v[106:109], v[178:181], v[216:219], v[106:109]
	v_mfma_f32_16x16x32_bf16 v[94:97], v[156:159], v[224:227], v[94:97]
	v_mfma_f32_16x16x32_bf16 v[90:93], v[178:181], v[224:227], v[90:93]
	v_mfma_f32_16x16x32_bf16 v[78:81], v[156:159], v[232:235], v[78:81]
	v_mfma_f32_16x16x32_bf16 v[74:77], v[178:181], v[232:235], v[74:77]
	v_mfma_f32_16x16x32_bf16 v[118:121], v[182:185], v[204:207], 0
	v_mfma_f32_16x16x32_bf16 v[114:117], v[190:193], v[204:207], 0
	v_mfma_f32_16x16x32_bf16 v[102:105], v[182:185], v[212:215], 0
	v_mfma_f32_16x16x32_bf16 v[98:101], v[190:193], v[212:215], 0
	v_mfma_f32_16x16x32_bf16 v[86:89], v[182:185], v[220:223], 0
	v_mfma_f32_16x16x32_bf16 v[82:85], v[190:193], v[220:223], 0
	v_mfma_f32_16x16x32_bf16 v[70:73], v[182:185], v[228:231], 0
	v_mfma_f32_16x16x32_bf16 v[66:69], v[190:193], v[228:231], 0
	v_mfma_f32_16x16x32_bf16 v[118:121], v[186:189], v[208:211], v[118:121]
	v_mfma_f32_16x16x32_bf16 v[114:117], v[194:197], v[208:211], v[114:117]
	v_mfma_f32_16x16x32_bf16 v[102:105], v[186:189], v[216:219], v[102:105]
	v_mfma_f32_16x16x32_bf16 v[98:101], v[194:197], v[216:219], v[98:101]
	v_mfma_f32_16x16x32_bf16 v[86:89], v[186:189], v[224:227], v[86:89]
	v_mfma_f32_16x16x32_bf16 v[82:85], v[194:197], v[224:227], v[82:85]
	v_mfma_f32_16x16x32_bf16 v[70:73], v[186:189], v[232:235], v[70:73]
	v_mfma_f32_16x16x32_bf16 v[66:69], v[194:197], v[232:235], v[66:69]
	s_barrier
	s_setprio 0
	s_add_i32 s37, s73, s4
	v_lshl_add_u64 v[146:147], s[42:43], 0, v[0:1]
	s_mov_b32 m0, s37
	ds_read_b128 v[204:207], v161 offset:16384
	ds_read_b128 v[208:211], v161 offset:17408
	ds_read_b128 v[212:215], v161 offset:18432
	ds_read_b128 v[216:219], v161 offset:19456
	ds_read_b128 v[220:223], v161 offset:20480
	ds_read_b128 v[224:227], v161 offset:21504
	ds_read_b128 v[228:231], v161 offset:22528
	ds_read_b128 v[232:235], v161 offset:23552
	global_load_lds_dwordx4 v[146:147], off
	s_add_i32 m0, s37, 0x2000
	s_add_u32 s74, s42, 0x40000
	v_lshl_add_u64 v[150:151], s[42:43], 0, v[134:135]
	s_addc_u32 s75, s43, 0
	s_add_i32 s29, s29, s4
	global_load_lds_dwordx4 v[150:151], off
	s_mov_b32 m0, s29
	v_lshl_add_u64 v[172:173], s[52:53], 0, v[136:137]
	global_load_lds_dwordx4 v0, s[74:75]
	s_add_i32 m0, s29, 0x2000
	s_nop 0
	global_load_lds_dwordx4 v134, s[74:75]
	v_lshl_add_u64 v[170:171], s[52:53], 0, v[138:139]
	s_mov_b32 m0, s5
	s_nop 0
	global_load_lds_dwordx4 v[170:171], off
	s_mov_b32 m0, s20
	s_nop 0
	global_load_lds_dwordx4 v[172:173], off
	s_lshl_b32 s101, s10, 14
	s_add_i32 s101, s101, s5
	s_add_u32 s100, s66, s101
	s_addc_u32 s101, s67, 0
	v_lshlrev_b32_e32 v2, 4, v163
	v_add_u32_e32 v3, 0x2000, v2
	s_add_i32 m0, s5, 0x20000
	s_nop 0
	global_load_lds_dwordx4 v2, s[100:101]
	s_add_i32 m0, s5, 0x22000
	s_nop 0
	global_load_lds_dwordx4 v3, s[100:101]
	s_waitcnt vmcnt(8)
	s_waitcnt lgkmcnt(0)
	s_setprio 1
	s_barrier
	v_mfma_f32_16x16x32_bf16 v[62:65], v[130:133], v[204:207], 0
	v_mfma_f32_16x16x32_bf16 v[58:61], v[174:177], v[204:207], 0
	v_mfma_f32_16x16x32_bf16 v[46:49], v[130:133], v[212:215], 0
	v_mfma_f32_16x16x32_bf16 v[42:45], v[174:177], v[212:215], 0
	v_mfma_f32_16x16x32_bf16 v[30:33], v[130:133], v[220:223], 0
	v_mfma_f32_16x16x32_bf16 v[26:29], v[174:177], v[220:223], 0
	v_mfma_f32_16x16x32_bf16 v[14:17], v[130:133], v[228:231], 0
	v_mfma_f32_16x16x32_bf16 v[10:13], v[174:177], v[228:231], 0
	v_mfma_f32_16x16x32_bf16 v[62:65], v[156:159], v[208:211], v[62:65]
	v_mfma_f32_16x16x32_bf16 v[58:61], v[178:181], v[208:211], v[58:61]
	v_mfma_f32_16x16x32_bf16 v[46:49], v[156:159], v[216:219], v[46:49]
	v_mfma_f32_16x16x32_bf16 v[42:45], v[178:181], v[216:219], v[42:45]
	v_mfma_f32_16x16x32_bf16 v[30:33], v[156:159], v[224:227], v[30:33]
	v_mfma_f32_16x16x32_bf16 v[26:29], v[178:181], v[224:227], v[26:29]
	v_mfma_f32_16x16x32_bf16 v[14:17], v[156:159], v[232:235], v[14:17]
	v_mfma_f32_16x16x32_bf16 v[10:13], v[178:181], v[232:235], v[10:13]
	v_mfma_f32_16x16x32_bf16 v[54:57], v[182:185], v[204:207], 0
	v_mfma_f32_16x16x32_bf16 v[50:53], v[190:193], v[204:207], 0
	v_mfma_f32_16x16x32_bf16 v[38:41], v[182:185], v[212:215], 0
	v_mfma_f32_16x16x32_bf16 v[34:37], v[190:193], v[212:215], 0
	v_mfma_f32_16x16x32_bf16 v[22:25], v[182:185], v[220:223], 0
	v_mfma_f32_16x16x32_bf16 v[18:21], v[190:193], v[220:223], 0
	v_mfma_f32_16x16x32_bf16 v[6:9], v[182:185], v[228:231], 0
	v_mfma_f32_16x16x32_bf16 v[2:5], v[190:193], v[228:231], 0
	v_mfma_f32_16x16x32_bf16 v[54:57], v[186:189], v[208:211], v[54:57]
	v_mfma_f32_16x16x32_bf16 v[50:53], v[194:197], v[208:211], v[50:53]
	v_mfma_f32_16x16x32_bf16 v[38:41], v[186:189], v[216:219], v[38:41]
	v_mfma_f32_16x16x32_bf16 v[34:37], v[194:197], v[216:219], v[34:37]
	v_mfma_f32_16x16x32_bf16 v[22:25], v[186:189], v[224:227], v[22:25]
	v_mfma_f32_16x16x32_bf16 v[18:21], v[194:197], v[224:227], v[18:21]
	v_mfma_f32_16x16x32_bf16 v[6:9], v[186:189], v[232:235], v[6:9]
	v_mfma_f32_16x16x32_bf16 v[2:5], v[194:197], v[232:235], v[2:5]
	s_barrier
	s_setprio 0
	s_add_i32 s29, 0, 0x18000
	v_add_u32_e32 v148, s29, v153
	s_add_i32 s37, 0, 0x1c000
	ds_read_b128 v[130:133], v148
	ds_read_b128 v[156:159], v148 offset:1024
	ds_read_b128 v[174:177], v148 offset:2048
	ds_read_b128 v[178:181], v148 offset:3072
	v_add_u32_e32 v148, s37, v153
	ds_read_b128 v[182:185], v148
	ds_read_b128 v[186:189], v148 offset:1024
	ds_read_b128 v[190:193], v148 offset:2048
	ds_read_b128 v[194:197], v148 offset:3072
	s_add_u32 s52, s52, 0x40000
	s_addc_u32 s53, s53, 0
	s_mov_b32 m0, s22
	ds_read_b128 v[204:207], v161 offset:32768
	ds_read_b128 v[208:211], v161 offset:33792
	ds_read_b128 v[212:215], v161 offset:34816
	ds_read_b128 v[216:219], v161 offset:35840
	ds_read_b128 v[220:223], v161 offset:36864
	ds_read_b128 v[224:227], v161 offset:37888
	ds_read_b128 v[228:231], v161 offset:38912
	ds_read_b128 v[232:235], v161 offset:39936
	global_load_lds_dwordx4 v138, s[52:53]
	s_mov_b32 m0, s23
	s_nop 0
	global_load_lds_dwordx4 v136, s[52:53]
	s_waitcnt vmcnt(8)
	s_waitcnt lgkmcnt(0)
	s_setprio 1
	s_barrier
	v_mfma_f32_16x16x32_bf16 v[126:129], v[130:133], v[204:207], v[126:129]
	v_mfma_f32_16x16x32_bf16 v[122:125], v[174:177], v[204:207], v[122:125]
	v_mfma_f32_16x16x32_bf16 v[110:113], v[130:133], v[212:215], v[110:113]
	v_mfma_f32_16x16x32_bf16 v[106:109], v[174:177], v[212:215], v[106:109]
	v_mfma_f32_16x16x32_bf16 v[94:97], v[130:133], v[220:223], v[94:97]
	v_mfma_f32_16x16x32_bf16 v[90:93], v[174:177], v[220:223], v[90:93]
	v_mfma_f32_16x16x32_bf16 v[78:81], v[130:133], v[228:231], v[78:81]
	v_mfma_f32_16x16x32_bf16 v[74:77], v[174:177], v[228:231], v[74:77]
	v_mfma_f32_16x16x32_bf16 v[126:129], v[156:159], v[208:211], v[126:129]
	v_mfma_f32_16x16x32_bf16 v[122:125], v[178:181], v[208:211], v[122:125]
	v_mfma_f32_16x16x32_bf16 v[110:113], v[156:159], v[216:219], v[110:113]
	v_mfma_f32_16x16x32_bf16 v[106:109], v[178:181], v[216:219], v[106:109]
	v_mfma_f32_16x16x32_bf16 v[94:97], v[156:159], v[224:227], v[94:97]
	v_mfma_f32_16x16x32_bf16 v[90:93], v[178:181], v[224:227], v[90:93]
	v_mfma_f32_16x16x32_bf16 v[78:81], v[156:159], v[232:235], v[78:81]
	v_mfma_f32_16x16x32_bf16 v[74:77], v[178:181], v[232:235], v[74:77]
	v_mfma_f32_16x16x32_bf16 v[118:121], v[182:185], v[204:207], v[118:121]
	v_mfma_f32_16x16x32_bf16 v[114:117], v[190:193], v[204:207], v[114:117]
	v_mfma_f32_16x16x32_bf16 v[102:105], v[182:185], v[212:215], v[102:105]
	v_mfma_f32_16x16x32_bf16 v[98:101], v[190:193], v[212:215], v[98:101]
	v_mfma_f32_16x16x32_bf16 v[86:89], v[182:185], v[220:223], v[86:89]
	v_mfma_f32_16x16x32_bf16 v[82:85], v[190:193], v[220:223], v[82:85]
	v_mfma_f32_16x16x32_bf16 v[70:73], v[182:185], v[228:231], v[70:73]
	v_mfma_f32_16x16x32_bf16 v[66:69], v[190:193], v[228:231], v[66:69]
	v_mfma_f32_16x16x32_bf16 v[118:121], v[186:189], v[208:211], v[118:121]
	v_mfma_f32_16x16x32_bf16 v[114:117], v[194:197], v[208:211], v[114:117]
	v_mfma_f32_16x16x32_bf16 v[102:105], v[186:189], v[216:219], v[102:105]
	v_mfma_f32_16x16x32_bf16 v[98:101], v[194:197], v[216:219], v[98:101]
	v_mfma_f32_16x16x32_bf16 v[86:89], v[186:189], v[224:227], v[86:89]
	v_mfma_f32_16x16x32_bf16 v[82:85], v[194:197], v[224:227], v[82:85]
	v_mfma_f32_16x16x32_bf16 v[70:73], v[186:189], v[232:235], v[70:73]
	v_mfma_f32_16x16x32_bf16 v[66:69], v[194:197], v[232:235], v[66:69]
	s_barrier
	s_setprio 0
	s_add_i32 s29, s29, s4
	v_lshl_add_u64 v[146:147], v[146:147], 0, s[24:25]
	s_mov_b32 m0, s29
	ds_read_b128 v[204:207], v161 offset:49152
	ds_read_b128 v[208:211], v161 offset:50176
	ds_read_b128 v[212:215], v161 offset:51200
	ds_read_b128 v[216:219], v161 offset:52224
	ds_read_b128 v[220:223], v161 offset:53248
	ds_read_b128 v[224:227], v161 offset:54272
	ds_read_b128 v[228:231], v161 offset:55296
	ds_read_b128 v[232:235], v161 offset:56320
	global_load_lds_dwordx4 v[146:147], off
	s_add_i32 m0, s29, 0x2000
	s_add_u32 s42, s42, 0x40080
	v_lshl_add_u64 v[146:147], v[150:151], 0, s[24:25]
	s_addc_u32 s43, s43, 0
	s_add_i32 s29, s37, s4
	global_load_lds_dwordx4 v[146:147], off
	s_mov_b32 m0, s29
	s_nop 0
	global_load_lds_dwordx4 v0, s[42:43]
	s_add_i32 m0, s29, 0x2000
	s_nop 0
	global_load_lds_dwordx4 v134, s[42:43]
	v_lshl_add_u64 v[146:147], v[170:171], 0, s[24:25]
	s_mov_b32 m0, s31
	s_nop 0
	global_load_lds_dwordx4 v[146:147], off
	v_lshl_add_u64 v[146:147], v[172:173], 0, s[24:25]
	s_mov_b32 m0, s33
	s_nop 0
	global_load_lds_dwordx4 v[146:147], off
	s_waitcnt vmcnt(8)
	s_waitcnt lgkmcnt(0)
	s_setprio 1
	s_barrier
	v_mfma_f32_16x16x32_bf16 v[62:65], v[130:133], v[204:207], v[62:65]
	v_mfma_f32_16x16x32_bf16 v[58:61], v[174:177], v[204:207], v[58:61]
	v_mfma_f32_16x16x32_bf16 v[46:49], v[130:133], v[212:215], v[46:49]
	v_mfma_f32_16x16x32_bf16 v[42:45], v[174:177], v[212:215], v[42:45]
	v_mfma_f32_16x16x32_bf16 v[30:33], v[130:133], v[220:223], v[30:33]
	v_mfma_f32_16x16x32_bf16 v[26:29], v[174:177], v[220:223], v[26:29]
	v_mfma_f32_16x16x32_bf16 v[14:17], v[130:133], v[228:231], v[14:17]
	v_mfma_f32_16x16x32_bf16 v[10:13], v[174:177], v[228:231], v[10:13]
	v_mfma_f32_16x16x32_bf16 v[62:65], v[156:159], v[208:211], v[62:65]
	v_mfma_f32_16x16x32_bf16 v[58:61], v[178:181], v[208:211], v[58:61]
	v_mfma_f32_16x16x32_bf16 v[46:49], v[156:159], v[216:219], v[46:49]
	v_mfma_f32_16x16x32_bf16 v[42:45], v[178:181], v[216:219], v[42:45]
	v_mfma_f32_16x16x32_bf16 v[30:33], v[156:159], v[224:227], v[30:33]
	v_mfma_f32_16x16x32_bf16 v[26:29], v[178:181], v[224:227], v[26:29]
	v_mfma_f32_16x16x32_bf16 v[14:17], v[156:159], v[232:235], v[14:17]
	v_mfma_f32_16x16x32_bf16 v[10:13], v[178:181], v[232:235], v[10:13]
	v_mfma_f32_16x16x32_bf16 v[54:57], v[182:185], v[204:207], v[54:57]
	v_mfma_f32_16x16x32_bf16 v[50:53], v[190:193], v[204:207], v[50:53]
	v_mfma_f32_16x16x32_bf16 v[38:41], v[182:185], v[212:215], v[38:41]
	v_mfma_f32_16x16x32_bf16 v[34:37], v[190:193], v[212:215], v[34:37]
	v_mfma_f32_16x16x32_bf16 v[22:25], v[182:185], v[220:223], v[22:25]
	v_mfma_f32_16x16x32_bf16 v[18:21], v[190:193], v[220:223], v[18:21]
	v_mfma_f32_16x16x32_bf16 v[6:9], v[182:185], v[228:231], v[6:9]
	v_mfma_f32_16x16x32_bf16 v[2:5], v[190:193], v[228:231], v[2:5]
	v_mfma_f32_16x16x32_bf16 v[54:57], v[186:189], v[208:211], v[54:57]
	v_mfma_f32_16x16x32_bf16 v[50:53], v[194:197], v[208:211], v[50:53]
	v_mfma_f32_16x16x32_bf16 v[38:41], v[186:189], v[216:219], v[38:41]
	v_mfma_f32_16x16x32_bf16 v[34:37], v[194:197], v[216:219], v[34:37]
	v_mfma_f32_16x16x32_bf16 v[22:25], v[186:189], v[224:227], v[22:25]
	v_mfma_f32_16x16x32_bf16 v[18:21], v[194:197], v[224:227], v[18:21]
	v_mfma_f32_16x16x32_bf16 v[6:9], v[186:189], v[232:235], v[6:9]
	v_mfma_f32_16x16x32_bf16 v[2:5], v[194:197], v[232:235], v[2:5]
	s_barrier
	s_setprio 0
	s_add_u32 s16, s16, 0x100
	s_addc_u32 s17, s17, 0
	s_add_u32 s56, s56, 0x100
	s_addc_u32 s57, s57, 0
	s_cmp_ge_i32 s72, s3
	s_mov_b32 s42, s72
	s_cbranch_scc0 .LBB7_1196
	s_branch .Lpeelx_1196
	.p2align	8

.Lpeel_1219:
	s_add_i32 s56, s52, 2
	s_add_u32 s29, s16, 0xfffc0080
	s_addc_u32 s37, s17, -1
	s_add_i32 s57, 0, 0x10000
	s_cmp_eq_u32 s84, s52
	s_cselect_b32 s55, s10, s37
	s_cselect_b32 s54, s13, s29
	s_cselect_b32 s53, s15, s39
	s_cselect_b32 s52, s28, s38
	s_add_i32 s29, 0, 0x14000
	v_add_u32_e32 v152, s57, v157
	v_add_u32_e32 v170, s29, v157
	ds_read_b128 v[140:143], v152
	ds_read_b128 v[144:147], v152 offset:1024
	ds_read_b128 v[148:151], v152 offset:2048
	ds_read_b128 v[152:155], v152 offset:3072
	ds_read_b128 v[184:187], v170
	ds_read_b128 v[188:191], v170 offset:1024
	ds_read_b128 v[192:195], v170 offset:2048
	ds_read_b128 v[196:199], v170 offset:3072
	s_add_i32 m0, s5, 0xc000
	ds_read_b128 v[204:207], v181
	ds_read_b128 v[208:211], v181 offset:1024
	ds_read_b128 v[212:215], v181 offset:2048
	ds_read_b128 v[216:219], v181 offset:3072
	ds_read_b128 v[220:223], v181 offset:4096
	ds_read_b128 v[224:227], v181 offset:5120
	ds_read_b128 v[228:231], v181 offset:6144
	ds_read_b128 v[232:235], v181 offset:7168
	global_load_lds_dwordx4 v136, s[16:17]
	s_add_i32 m0, s5, 0xe000
	s_nop 0
	global_load_lds_dwordx4 v138, s[16:17]
	s_waitcnt vmcnt(8)
	s_waitcnt lgkmcnt(0)
	s_setprio 1
	s_barrier
	v_mfma_f32_16x16x32_bf16 v[126:129], v[140:143], v[204:207], 0
	v_mfma_f32_16x16x32_bf16 v[122:125], v[148:151], v[204:207], 0
	v_mfma_f32_16x16x32_bf16 v[118:121], v[140:143], v[212:215], 0
	v_mfma_f32_16x16x32_bf16 v[114:117], v[148:151], v[212:215], 0
	v_mfma_f32_16x16x32_bf16 v[106:109], v[140:143], v[220:223], 0
	v_mfma_f32_16x16x32_bf16 v[98:101], v[148:151], v[220:223], 0
	v_mfma_f32_16x16x32_bf16 v[90:93], v[140:143], v[228:231], 0
	v_mfma_f32_16x16x32_bf16 v[82:85], v[148:151], v[228:231], 0
	v_mfma_f32_16x16x32_bf16 v[126:129], v[144:147], v[208:211], v[126:129]
	v_mfma_f32_16x16x32_bf16 v[122:125], v[152:155], v[208:211], v[122:125]
	v_mfma_f32_16x16x32_bf16 v[118:121], v[144:147], v[216:219], v[118:121]
	v_mfma_f32_16x16x32_bf16 v[114:117], v[152:155], v[216:219], v[114:117]
	v_mfma_f32_16x16x32_bf16 v[106:109], v[144:147], v[224:227], v[106:109]
	v_mfma_f32_16x16x32_bf16 v[98:101], v[152:155], v[224:227], v[98:101]
	v_mfma_f32_16x16x32_bf16 v[90:93], v[144:147], v[232:235], v[90:93]
	v_mfma_f32_16x16x32_bf16 v[82:85], v[152:155], v[232:235], v[82:85]
	v_mfma_f32_16x16x32_bf16 v[110:113], v[184:187], v[204:207], 0
	v_mfma_f32_16x16x32_bf16 v[102:105], v[192:195], v[204:207], 0
	v_mfma_f32_16x16x32_bf16 v[94:97], v[184:187], v[212:215], 0
	v_mfma_f32_16x16x32_bf16 v[86:89], v[192:195], v[212:215], 0
	v_mfma_f32_16x16x32_bf16 v[78:81], v[184:187], v[220:223], 0
	v_mfma_f32_16x16x32_bf16 v[74:77], v[192:195], v[220:223], 0
	v_mfma_f32_16x16x32_bf16 v[70:73], v[184:187], v[228:231], 0
	v_mfma_f32_16x16x32_bf16 v[66:69], v[192:195], v[228:231], 0
	v_mfma_f32_16x16x32_bf16 v[110:113], v[188:191], v[208:211], v[110:113]
	v_mfma_f32_16x16x32_bf16 v[102:105], v[196:199], v[208:211], v[102:105]
	v_mfma_f32_16x16x32_bf16 v[94:97], v[188:191], v[216:219], v[94:97]
	v_mfma_f32_16x16x32_bf16 v[86:89], v[196:199], v[216:219], v[86:89]
	v_mfma_f32_16x16x32_bf16 v[78:81], v[188:191], v[224:227], v[78:81]
	v_mfma_f32_16x16x32_bf16 v[74:77], v[196:199], v[224:227], v[74:77]
	v_mfma_f32_16x16x32_bf16 v[70:73], v[188:191], v[232:235], v[70:73]
	v_mfma_f32_16x16x32_bf16 v[66:69], v[196:199], v[232:235], v[66:69]
	s_barrier
	s_setprio 0
	s_add_i32 s37, s57, s4
	v_lshl_add_u64 v[170:171], s[52:53], 0, v[0:1]
	s_mov_b32 m0, s37
	ds_read_b128 v[204:207], v181 offset:16384
	ds_read_b128 v[208:211], v181 offset:17408
	ds_read_b128 v[212:215], v181 offset:18432
	ds_read_b128 v[216:219], v181 offset:19456
	ds_read_b128 v[220:223], v181 offset:20480
	ds_read_b128 v[224:227], v181 offset:21504
	ds_read_b128 v[228:231], v181 offset:22528
	ds_read_b128 v[232:235], v181 offset:23552
	global_load_lds_dwordx4 v[170:171], off
	s_add_i32 m0, s37, 0x2000
	s_add_u32 s74, s52, 0x40000
	v_lshl_add_u64 v[172:173], s[52:53], 0, v[130:131]
	s_addc_u32 s75, s53, 0
	s_add_i32 s29, s29, s4
	global_load_lds_dwordx4 v[172:173], off
	s_mov_b32 m0, s29
	v_lshl_add_u64 v[238:239], s[54:55], 0, v[132:133]
	global_load_lds_dwordx4 v0, s[74:75]
	s_add_i32 m0, s29, 0x2000
	s_nop 0
	global_load_lds_dwordx4 v130, s[74:75]
	v_lshl_add_u64 v[236:237], s[54:55], 0, v[134:135]
	s_mov_b32 m0, s5
	s_nop 0
	global_load_lds_dwordx4 v[236:237], off
	s_mov_b32 m0, s20
	s_nop 0
	global_load_lds_dwordx4 v[238:239], off
	s_waitcnt vmcnt(8)
	s_waitcnt lgkmcnt(0)
	s_setprio 1
	s_barrier
	v_mfma_f32_16x16x32_bf16 v[62:65], v[140:143], v[204:207], 0
	v_mfma_f32_16x16x32_bf16 v[58:61], v[148:151], v[204:207], 0
	v_mfma_f32_16x16x32_bf16 v[54:57], v[140:143], v[212:215], 0
	v_mfma_f32_16x16x32_bf16 v[50:53], v[148:151], v[212:215], 0
	v_mfma_f32_16x16x32_bf16 v[42:45], v[140:143], v[220:223], 0
	v_mfma_f32_16x16x32_bf16 v[34:37], v[148:151], v[220:223], 0
	v_mfma_f32_16x16x32_bf16 v[26:29], v[140:143], v[228:231], 0
	v_mfma_f32_16x16x32_bf16 v[18:21], v[148:151], v[228:231], 0
	v_mfma_f32_16x16x32_bf16 v[62:65], v[144:147], v[208:211], v[62:65]
	v_mfma_f32_16x16x32_bf16 v[58:61], v[152:155], v[208:211], v[58:61]
	v_mfma_f32_16x16x32_bf16 v[54:57], v[144:147], v[216:219], v[54:57]
	v_mfma_f32_16x16x32_bf16 v[50:53], v[152:155], v[216:219], v[50:53]
	v_mfma_f32_16x16x32_bf16 v[42:45], v[144:147], v[224:227], v[42:45]
	v_mfma_f32_16x16x32_bf16 v[34:37], v[152:155], v[224:227], v[34:37]
	v_mfma_f32_16x16x32_bf16 v[26:29], v[144:147], v[232:235], v[26:29]
	v_mfma_f32_16x16x32_bf16 v[18:21], v[152:155], v[232:235], v[18:21]
	v_mfma_f32_16x16x32_bf16 v[46:49], v[184:187], v[204:207], 0
	v_mfma_f32_16x16x32_bf16 v[38:41], v[192:195], v[204:207], 0
	v_mfma_f32_16x16x32_bf16 v[30:33], v[184:187], v[212:215], 0
	v_mfma_f32_16x16x32_bf16 v[22:25], v[192:195], v[212:215], 0
	v_mfma_f32_16x16x32_bf16 v[14:17], v[184:187], v[220:223], 0
	v_mfma_f32_16x16x32_bf16 v[10:13], v[192:195], v[220:223], 0
	v_mfma_f32_16x16x32_bf16 v[6:9], v[184:187], v[228:231], 0
	v_mfma_f32_16x16x32_bf16 v[2:5], v[192:195], v[228:231], 0
	v_mfma_f32_16x16x32_bf16 v[46:49], v[188:191], v[208:211], v[46:49]
	v_mfma_f32_16x16x32_bf16 v[38:41], v[196:199], v[208:211], v[38:41]
	v_mfma_f32_16x16x32_bf16 v[30:33], v[188:191], v[216:219], v[30:33]
	v_mfma_f32_16x16x32_bf16 v[22:25], v[196:199], v[216:219], v[22:25]
	v_mfma_f32_16x16x32_bf16 v[14:17], v[188:191], v[224:227], v[14:17]
	v_mfma_f32_16x16x32_bf16 v[10:13], v[196:199], v[224:227], v[10:13]
	v_mfma_f32_16x16x32_bf16 v[6:9], v[188:191], v[232:235], v[6:9]
	v_mfma_f32_16x16x32_bf16 v[2:5], v[196:199], v[232:235], v[2:5]
	s_barrier
	s_setprio 0
	s_add_i32 s29, 0, 0x18000
	s_add_i32 s37, 0, 0x1c000
	v_add_u32_e32 v152, s29, v157
	v_add_u32_e32 v183, s37, v157
	ds_read_b128 v[140:143], v152
	ds_read_b128 v[144:147], v152 offset:1024
	ds_read_b128 v[148:151], v152 offset:2048
	ds_read_b128 v[152:155], v152 offset:3072
	ds_read_b128 v[184:187], v183
	ds_read_b128 v[188:191], v183 offset:1024
	ds_read_b128 v[192:195], v183 offset:2048
	ds_read_b128 v[196:199], v183 offset:3072
	s_add_u32 s54, s54, 0x40000
	s_addc_u32 s55, s55, 0
	s_mov_b32 m0, s22
	ds_read_b128 v[204:207], v181 offset:32768
	ds_read_b128 v[208:211], v181 offset:33792
	ds_read_b128 v[212:215], v181 offset:34816
	ds_read_b128 v[216:219], v181 offset:35840
	ds_read_b128 v[220:223], v181 offset:36864
	ds_read_b128 v[224:227], v181 offset:37888
	ds_read_b128 v[228:231], v181 offset:38912
	ds_read_b128 v[232:235], v181 offset:39936
	global_load_lds_dwordx4 v134, s[54:55]
	s_mov_b32 m0, s23
	s_nop 0
	global_load_lds_dwordx4 v132, s[54:55]
	s_waitcnt vmcnt(8)
	s_waitcnt lgkmcnt(0)
	s_setprio 1
	s_barrier
	v_mfma_f32_16x16x32_bf16 v[126:129], v[140:143], v[204:207], v[126:129]
	v_mfma_f32_16x16x32_bf16 v[122:125], v[148:151], v[204:207], v[122:125]
	v_mfma_f32_16x16x32_bf16 v[118:121], v[140:143], v[212:215], v[118:121]
	v_mfma_f32_16x16x32_bf16 v[114:117], v[148:151], v[212:215], v[114:117]
	v_mfma_f32_16x16x32_bf16 v[106:109], v[140:143], v[220:223], v[106:109]
	v_mfma_f32_16x16x32_bf16 v[98:101], v[148:151], v[220:223], v[98:101]
	v_mfma_f32_16x16x32_bf16 v[90:93], v[140:143], v[228:231], v[90:93]
	v_mfma_f32_16x16x32_bf16 v[82:85], v[148:151], v[228:231], v[82:85]
	v_mfma_f32_16x16x32_bf16 v[126:129], v[144:147], v[208:211], v[126:129]
	v_mfma_f32_16x16x32_bf16 v[122:125], v[152:155], v[208:211], v[122:125]
	v_mfma_f32_16x16x32_bf16 v[118:121], v[144:147], v[216:219], v[118:121]
	v_mfma_f32_16x16x32_bf16 v[114:117], v[152:155], v[216:219], v[114:117]
	v_mfma_f32_16x16x32_bf16 v[106:109], v[144:147], v[224:227], v[106:109]
	v_mfma_f32_16x16x32_bf16 v[98:101], v[152:155], v[224:227], v[98:101]
	v_mfma_f32_16x16x32_bf16 v[90:93], v[144:147], v[232:235], v[90:93]
	v_mfma_f32_16x16x32_bf16 v[82:85], v[152:155], v[232:235], v[82:85]
	v_mfma_f32_16x16x32_bf16 v[110:113], v[184:187], v[204:207], v[110:113]
	v_mfma_f32_16x16x32_bf16 v[102:105], v[192:195], v[204:207], v[102:105]
	v_mfma_f32_16x16x32_bf16 v[94:97], v[184:187], v[212:215], v[94:97]
	v_mfma_f32_16x16x32_bf16 v[86:89], v[192:195], v[212:215], v[86:89]
	v_mfma_f32_16x16x32_bf16 v[78:81], v[184:187], v[220:223], v[78:81]
	v_mfma_f32_16x16x32_bf16 v[74:77], v[192:195], v[220:223], v[74:77]
	v_mfma_f32_16x16x32_bf16 v[70:73], v[184:187], v[228:231], v[70:73]
	v_mfma_f32_16x16x32_bf16 v[66:69], v[192:195], v[228:231], v[66:69]
	v_mfma_f32_16x16x32_bf16 v[110:113], v[188:191], v[208:211], v[110:113]
	v_mfma_f32_16x16x32_bf16 v[102:105], v[196:199], v[208:211], v[102:105]
	v_mfma_f32_16x16x32_bf16 v[94:97], v[188:191], v[216:219], v[94:97]
	v_mfma_f32_16x16x32_bf16 v[86:89], v[196:199], v[216:219], v[86:89]
	v_mfma_f32_16x16x32_bf16 v[78:81], v[188:191], v[224:227], v[78:81]
	v_mfma_f32_16x16x32_bf16 v[74:77], v[196:199], v[224:227], v[74:77]
	v_mfma_f32_16x16x32_bf16 v[70:73], v[188:191], v[232:235], v[70:73]
	v_mfma_f32_16x16x32_bf16 v[66:69], v[196:199], v[232:235], v[66:69]
	s_barrier
	s_setprio 0
	s_add_i32 s29, s29, s4
	v_lshl_add_u64 v[170:171], v[170:171], 0, s[24:25]
	s_mov_b32 m0, s29
	ds_read_b128 v[204:207], v181 offset:49152
	ds_read_b128 v[208:211], v181 offset:50176
	ds_read_b128 v[212:215], v181 offset:51200
	ds_read_b128 v[216:219], v181 offset:52224
	ds_read_b128 v[220:223], v181 offset:53248
	ds_read_b128 v[224:227], v181 offset:54272
	ds_read_b128 v[228:231], v181 offset:55296
	ds_read_b128 v[232:235], v181 offset:56320
	global_load_lds_dwordx4 v[170:171], off
	s_add_i32 m0, s29, 0x2000
	s_add_u32 s52, s52, 0x40080
	v_lshl_add_u64 v[170:171], v[172:173], 0, s[24:25]
	s_addc_u32 s53, s53, 0
	s_add_i32 s29, s37, s4
	global_load_lds_dwordx4 v[170:171], off
	s_mov_b32 m0, s29
	s_nop 0
	global_load_lds_dwordx4 v0, s[52:53]
	s_add_i32 m0, s29, 0x2000
	s_nop 0
	global_load_lds_dwordx4 v130, s[52:53]
	v_lshl_add_u64 v[170:171], v[236:237], 0, s[24:25]
	s_mov_b32 m0, s31
	s_nop 0
	global_load_lds_dwordx4 v[170:171], off
	v_lshl_add_u64 v[170:171], v[238:239], 0, s[24:25]
	s_mov_b32 m0, s33
	s_nop 0
	global_load_lds_dwordx4 v[170:171], off
	s_waitcnt vmcnt(8)
	s_waitcnt lgkmcnt(0)
	s_setprio 1
	s_barrier
	v_mfma_f32_16x16x32_bf16 v[62:65], v[140:143], v[204:207], v[62:65]
	v_mfma_f32_16x16x32_bf16 v[58:61], v[148:151], v[204:207], v[58:61]
	v_mfma_f32_16x16x32_bf16 v[54:57], v[140:143], v[212:215], v[54:57]
	v_mfma_f32_16x16x32_bf16 v[50:53], v[148:151], v[212:215], v[50:53]
	v_mfma_f32_16x16x32_bf16 v[42:45], v[140:143], v[220:223], v[42:45]
	v_mfma_f32_16x16x32_bf16 v[34:37], v[148:151], v[220:223], v[34:37]
	v_mfma_f32_16x16x32_bf16 v[26:29], v[140:143], v[228:231], v[26:29]
	v_mfma_f32_16x16x32_bf16 v[18:21], v[148:151], v[228:231], v[18:21]
	v_mfma_f32_16x16x32_bf16 v[62:65], v[144:147], v[208:211], v[62:65]
	v_mfma_f32_16x16x32_bf16 v[58:61], v[152:155], v[208:211], v[58:61]
	v_mfma_f32_16x16x32_bf16 v[54:57], v[144:147], v[216:219], v[54:57]
	v_mfma_f32_16x16x32_bf16 v[50:53], v[152:155], v[216:219], v[50:53]
	v_mfma_f32_16x16x32_bf16 v[42:45], v[144:147], v[224:227], v[42:45]
	v_mfma_f32_16x16x32_bf16 v[34:37], v[152:155], v[224:227], v[34:37]
	v_mfma_f32_16x16x32_bf16 v[26:29], v[144:147], v[232:235], v[26:29]
	v_mfma_f32_16x16x32_bf16 v[18:21], v[152:155], v[232:235], v[18:21]
	v_mfma_f32_16x16x32_bf16 v[46:49], v[184:187], v[204:207], v[46:49]
	v_mfma_f32_16x16x32_bf16 v[38:41], v[192:195], v[204:207], v[38:41]
	v_mfma_f32_16x16x32_bf16 v[30:33], v[184:187], v[212:215], v[30:33]
	v_mfma_f32_16x16x32_bf16 v[22:25], v[192:195], v[212:215], v[22:25]
	v_mfma_f32_16x16x32_bf16 v[14:17], v[184:187], v[220:223], v[14:17]
	v_mfma_f32_16x16x32_bf16 v[10:13], v[192:195], v[220:223], v[10:13]
	v_mfma_f32_16x16x32_bf16 v[6:9], v[184:187], v[228:231], v[6:9]
	v_mfma_f32_16x16x32_bf16 v[2:5], v[192:195], v[228:231], v[2:5]
	v_mfma_f32_16x16x32_bf16 v[46:49], v[188:191], v[208:211], v[46:49]
	v_mfma_f32_16x16x32_bf16 v[38:41], v[196:199], v[208:211], v[38:41]
	v_mfma_f32_16x16x32_bf16 v[30:33], v[188:191], v[216:219], v[30:33]
	v_mfma_f32_16x16x32_bf16 v[22:25], v[196:199], v[216:219], v[22:25]
	v_mfma_f32_16x16x32_bf16 v[14:17], v[188:191], v[224:227], v[14:17]
	v_mfma_f32_16x16x32_bf16 v[10:13], v[196:199], v[224:227], v[10:13]
	v_mfma_f32_16x16x32_bf16 v[6:9], v[188:191], v[232:235], v[6:9]
	v_mfma_f32_16x16x32_bf16 v[2:5], v[196:199], v[232:235], v[2:5]
	s_barrier
	s_setprio 0
	s_add_u32 s16, s16, 0x100
	s_addc_u32 s17, s17, 0
	s_add_u32 s38, s38, 0x100
	s_addc_u32 s39, s39, 0
	s_cmp_ge_i32 s56, s3
	s_mov_b32 s52, s56
	s_cbranch_scc0 .LBB7_1219
	s_branch .Lpeelx_1219
	.p2align	8

.Lpeel_1274:
	s_add_i32 s72, s50, 2
	s_add_u32 s29, s48, 0xfffc0080
	s_addc_u32 s37, s49, -1
	s_add_i32 s73, 0, 0x10000
	s_cmp_eq_u32 s33, s50
	s_cselect_b32 s53, s13, s37
	s_cselect_b32 s52, s15, s29
	s_cselect_b32 s51, s54, s57
	s_cselect_b32 s50, s55, s56
	s_add_i32 s29, 0, 0x14000
	v_add_u32_e32 v156, s73, v141
	v_add_u32_e32 v160, s29, v141
	ds_read_b128 v[144:147], v156
	ds_read_b128 v[148:151], v156 offset:1024
	ds_read_b128 v[152:155], v156 offset:2048
	ds_read_b128 v[156:159], v156 offset:3072
	ds_read_b128 v[174:177], v160
	ds_read_b128 v[178:181], v160 offset:1024
	ds_read_b128 v[182:185], v160 offset:2048
	ds_read_b128 v[186:189], v160 offset:3072
	s_add_i32 m0, s5, 0xc000
	ds_read_b128 v[190:193], v143
	ds_read_b128 v[194:197], v143 offset:1024
	ds_read_b128 v[204:207], v143 offset:2048
	ds_read_b128 v[208:211], v143 offset:3072
	ds_read_b128 v[212:215], v143 offset:4096
	ds_read_b128 v[216:219], v143 offset:5120
	ds_read_b128 v[220:223], v143 offset:6144
	ds_read_b128 v[224:227], v143 offset:7168
	global_load_lds_dwordx4 v136, s[48:49]
	s_add_i32 m0, s5, 0xe000
	s_nop 0
	global_load_lds_dwordx4 v138, s[48:49]
	s_waitcnt vmcnt(8)
	s_waitcnt lgkmcnt(0)
	s_setprio 1
	s_barrier
	v_mfma_f32_16x16x32_bf16 v[126:129], v[144:147], v[190:193], 0
	v_mfma_f32_16x16x32_bf16 v[122:125], v[152:155], v[190:193], 0
	v_mfma_f32_16x16x32_bf16 v[110:113], v[144:147], v[204:207], 0
	v_mfma_f32_16x16x32_bf16 v[106:109], v[152:155], v[204:207], 0
	v_mfma_f32_16x16x32_bf16 v[94:97], v[144:147], v[212:215], 0
	v_mfma_f32_16x16x32_bf16 v[90:93], v[152:155], v[212:215], 0
	v_mfma_f32_16x16x32_bf16 v[78:81], v[144:147], v[220:223], 0
	v_mfma_f32_16x16x32_bf16 v[74:77], v[152:155], v[220:223], 0
	v_mfma_f32_16x16x32_bf16 v[126:129], v[148:151], v[194:197], v[126:129]
	v_mfma_f32_16x16x32_bf16 v[122:125], v[156:159], v[194:197], v[122:125]
	v_mfma_f32_16x16x32_bf16 v[110:113], v[148:151], v[208:211], v[110:113]
	v_mfma_f32_16x16x32_bf16 v[106:109], v[156:159], v[208:211], v[106:109]
	v_mfma_f32_16x16x32_bf16 v[94:97], v[148:151], v[216:219], v[94:97]
	v_mfma_f32_16x16x32_bf16 v[90:93], v[156:159], v[216:219], v[90:93]
	v_mfma_f32_16x16x32_bf16 v[78:81], v[148:151], v[224:227], v[78:81]
	v_mfma_f32_16x16x32_bf16 v[74:77], v[156:159], v[224:227], v[74:77]
	v_mfma_f32_16x16x32_bf16 v[118:121], v[174:177], v[190:193], 0
	v_mfma_f32_16x16x32_bf16 v[114:117], v[182:185], v[190:193], 0
	v_mfma_f32_16x16x32_bf16 v[102:105], v[174:177], v[204:207], 0
	v_mfma_f32_16x16x32_bf16 v[98:101], v[182:185], v[204:207], 0
	v_mfma_f32_16x16x32_bf16 v[86:89], v[174:177], v[212:215], 0
	v_mfma_f32_16x16x32_bf16 v[82:85], v[182:185], v[212:215], 0
	v_mfma_f32_16x16x32_bf16 v[70:73], v[174:177], v[220:223], 0
	v_mfma_f32_16x16x32_bf16 v[66:69], v[182:185], v[220:223], 0
	v_mfma_f32_16x16x32_bf16 v[118:121], v[178:181], v[194:197], v[118:121]
	v_mfma_f32_16x16x32_bf16 v[114:117], v[186:189], v[194:197], v[114:117]
	v_mfma_f32_16x16x32_bf16 v[102:105], v[178:181], v[208:211], v[102:105]
	v_mfma_f32_16x16x32_bf16 v[98:101], v[186:189], v[208:211], v[98:101]
	v_mfma_f32_16x16x32_bf16 v[86:89], v[178:181], v[216:219], v[86:89]
	v_mfma_f32_16x16x32_bf16 v[82:85], v[186:189], v[216:219], v[82:85]
	v_mfma_f32_16x16x32_bf16 v[70:73], v[178:181], v[224:227], v[70:73]
	v_mfma_f32_16x16x32_bf16 v[66:69], v[186:189], v[224:227], v[66:69]
	s_barrier
	s_setprio 0
	s_add_i32 s37, s73, s4
	v_lshl_add_u64 v[160:161], s[50:51], 0, v[0:1]
	s_mov_b32 m0, s37
	ds_read_b128 v[190:193], v143 offset:16384
	ds_read_b128 v[194:197], v143 offset:17408
	ds_read_b128 v[204:207], v143 offset:18432
	ds_read_b128 v[208:211], v143 offset:19456
	ds_read_b128 v[212:215], v143 offset:20480
	ds_read_b128 v[216:219], v143 offset:21504
	ds_read_b128 v[220:223], v143 offset:22528
	ds_read_b128 v[224:227], v143 offset:23552
	global_load_lds_dwordx4 v[160:161], off
	s_add_i32 m0, s37, 0x2000
	s_add_u32 s74, s50, 0x100000
	v_lshl_add_u64 v[170:171], s[50:51], 0, v[130:131]
	s_addc_u32 s75, s51, 0
	s_add_i32 s29, s29, s4
	global_load_lds_dwordx4 v[170:171], off
	s_mov_b32 m0, s29
	v_lshl_add_u64 v[198:199], s[52:53], 0, v[132:133]
	global_load_lds_dwordx4 v0, s[74:75]
	s_add_i32 m0, s29, 0x2000
	s_nop 0
	global_load_lds_dwordx4 v130, s[74:75]
	v_lshl_add_u64 v[172:173], s[52:53], 0, v[134:135]
	s_mov_b32 m0, s5
	s_nop 0
	global_load_lds_dwordx4 v[172:173], off
	s_mov_b32 m0, s10
	s_nop 0
	global_load_lds_dwordx4 v[198:199], off
	s_waitcnt vmcnt(8)
	s_waitcnt lgkmcnt(0)
	s_setprio 1
	s_barrier
	v_mfma_f32_16x16x32_bf16 v[62:65], v[144:147], v[190:193], 0
	v_mfma_f32_16x16x32_bf16 v[58:61], v[152:155], v[190:193], 0
	v_mfma_f32_16x16x32_bf16 v[46:49], v[144:147], v[204:207], 0
	v_mfma_f32_16x16x32_bf16 v[42:45], v[152:155], v[204:207], 0
	v_mfma_f32_16x16x32_bf16 v[30:33], v[144:147], v[212:215], 0
	v_mfma_f32_16x16x32_bf16 v[26:29], v[152:155], v[212:215], 0
	v_mfma_f32_16x16x32_bf16 v[14:17], v[144:147], v[220:223], 0
	v_mfma_f32_16x16x32_bf16 v[10:13], v[152:155], v[220:223], 0
	v_mfma_f32_16x16x32_bf16 v[62:65], v[148:151], v[194:197], v[62:65]
	v_mfma_f32_16x16x32_bf16 v[58:61], v[156:159], v[194:197], v[58:61]
	v_mfma_f32_16x16x32_bf16 v[46:49], v[148:151], v[208:211], v[46:49]
	v_mfma_f32_16x16x32_bf16 v[42:45], v[156:159], v[208:211], v[42:45]
	v_mfma_f32_16x16x32_bf16 v[30:33], v[148:151], v[216:219], v[30:33]
	v_mfma_f32_16x16x32_bf16 v[26:29], v[156:159], v[216:219], v[26:29]
	v_mfma_f32_16x16x32_bf16 v[14:17], v[148:151], v[224:227], v[14:17]
	v_mfma_f32_16x16x32_bf16 v[10:13], v[156:159], v[224:227], v[10:13]
	v_mfma_f32_16x16x32_bf16 v[54:57], v[174:177], v[190:193], 0
	v_mfma_f32_16x16x32_bf16 v[50:53], v[182:185], v[190:193], 0
	v_mfma_f32_16x16x32_bf16 v[38:41], v[174:177], v[204:207], 0
	v_mfma_f32_16x16x32_bf16 v[34:37], v[182:185], v[204:207], 0
	v_mfma_f32_16x16x32_bf16 v[22:25], v[174:177], v[212:215], 0
	v_mfma_f32_16x16x32_bf16 v[18:21], v[182:185], v[212:215], 0
	v_mfma_f32_16x16x32_bf16 v[6:9], v[174:177], v[220:223], 0
	v_mfma_f32_16x16x32_bf16 v[2:5], v[182:185], v[220:223], 0
	v_mfma_f32_16x16x32_bf16 v[54:57], v[178:181], v[194:197], v[54:57]
	v_mfma_f32_16x16x32_bf16 v[50:53], v[186:189], v[194:197], v[50:53]
	v_mfma_f32_16x16x32_bf16 v[38:41], v[178:181], v[208:211], v[38:41]
	v_mfma_f32_16x16x32_bf16 v[34:37], v[186:189], v[208:211], v[34:37]
	v_mfma_f32_16x16x32_bf16 v[22:25], v[178:181], v[216:219], v[22:25]
	v_mfma_f32_16x16x32_bf16 v[18:21], v[186:189], v[216:219], v[18:21]
	v_mfma_f32_16x16x32_bf16 v[6:9], v[178:181], v[224:227], v[6:9]
	v_mfma_f32_16x16x32_bf16 v[2:5], v[186:189], v[224:227], v[2:5]
	s_barrier
	s_setprio 0
	s_add_i32 s29, 0, 0x18000
	s_add_i32 s37, 0, 0x1c000
	v_add_u32_e32 v156, s29, v141
	v_add_u32_e32 v186, s37, v141
	ds_read_b128 v[144:147], v156
	ds_read_b128 v[148:151], v156 offset:1024
	ds_read_b128 v[152:155], v156 offset:2048
	ds_read_b128 v[156:159], v156 offset:3072
	ds_read_b128 v[174:177], v186
	ds_read_b128 v[178:181], v186 offset:1024
	ds_read_b128 v[182:185], v186 offset:2048
	ds_read_b128 v[186:189], v186 offset:3072
	s_add_u32 s52, s52, 0x40000
	s_addc_u32 s53, s53, 0
	s_mov_b32 m0, s20
	ds_read_b128 v[190:193], v143 offset:32768
	ds_read_b128 v[194:197], v143 offset:33792
	ds_read_b128 v[204:207], v143 offset:34816
	ds_read_b128 v[208:211], v143 offset:35840
	ds_read_b128 v[212:215], v143 offset:36864
	ds_read_b128 v[216:219], v143 offset:37888
	ds_read_b128 v[220:223], v143 offset:38912
	ds_read_b128 v[224:227], v143 offset:39936
	global_load_lds_dwordx4 v134, s[52:53]
	s_mov_b32 m0, s22
	s_nop 0
	global_load_lds_dwordx4 v132, s[52:53]
	s_waitcnt vmcnt(8)
	s_waitcnt lgkmcnt(0)
	s_setprio 1
	s_barrier
	v_mfma_f32_16x16x32_bf16 v[126:129], v[144:147], v[190:193], v[126:129]
	v_mfma_f32_16x16x32_bf16 v[122:125], v[152:155], v[190:193], v[122:125]
	v_mfma_f32_16x16x32_bf16 v[110:113], v[144:147], v[204:207], v[110:113]
	v_mfma_f32_16x16x32_bf16 v[106:109], v[152:155], v[204:207], v[106:109]
	v_mfma_f32_16x16x32_bf16 v[94:97], v[144:147], v[212:215], v[94:97]
	v_mfma_f32_16x16x32_bf16 v[90:93], v[152:155], v[212:215], v[90:93]
	v_mfma_f32_16x16x32_bf16 v[78:81], v[144:147], v[220:223], v[78:81]
	v_mfma_f32_16x16x32_bf16 v[74:77], v[152:155], v[220:223], v[74:77]
	v_mfma_f32_16x16x32_bf16 v[126:129], v[148:151], v[194:197], v[126:129]
	v_mfma_f32_16x16x32_bf16 v[122:125], v[156:159], v[194:197], v[122:125]
	v_mfma_f32_16x16x32_bf16 v[110:113], v[148:151], v[208:211], v[110:113]
	v_mfma_f32_16x16x32_bf16 v[106:109], v[156:159], v[208:211], v[106:109]
	v_mfma_f32_16x16x32_bf16 v[94:97], v[148:151], v[216:219], v[94:97]
	v_mfma_f32_16x16x32_bf16 v[90:93], v[156:159], v[216:219], v[90:93]
	v_mfma_f32_16x16x32_bf16 v[78:81], v[148:151], v[224:227], v[78:81]
	v_mfma_f32_16x16x32_bf16 v[74:77], v[156:159], v[224:227], v[74:77]
	v_mfma_f32_16x16x32_bf16 v[118:121], v[174:177], v[190:193], v[118:121]
	v_mfma_f32_16x16x32_bf16 v[114:117], v[182:185], v[190:193], v[114:117]
	v_mfma_f32_16x16x32_bf16 v[102:105], v[174:177], v[204:207], v[102:105]
	v_mfma_f32_16x16x32_bf16 v[98:101], v[182:185], v[204:207], v[98:101]
	v_mfma_f32_16x16x32_bf16 v[86:89], v[174:177], v[212:215], v[86:89]
	v_mfma_f32_16x16x32_bf16 v[82:85], v[182:185], v[212:215], v[82:85]
	v_mfma_f32_16x16x32_bf16 v[70:73], v[174:177], v[220:223], v[70:73]
	v_mfma_f32_16x16x32_bf16 v[66:69], v[182:185], v[220:223], v[66:69]
	v_mfma_f32_16x16x32_bf16 v[118:121], v[178:181], v[194:197], v[118:121]
	v_mfma_f32_16x16x32_bf16 v[114:117], v[186:189], v[194:197], v[114:117]
	v_mfma_f32_16x16x32_bf16 v[102:105], v[178:181], v[208:211], v[102:105]
	v_mfma_f32_16x16x32_bf16 v[98:101], v[186:189], v[208:211], v[98:101]
	v_mfma_f32_16x16x32_bf16 v[86:89], v[178:181], v[216:219], v[86:89]
	v_mfma_f32_16x16x32_bf16 v[82:85], v[186:189], v[216:219], v[82:85]
	v_mfma_f32_16x16x32_bf16 v[70:73], v[178:181], v[224:227], v[70:73]
	v_mfma_f32_16x16x32_bf16 v[66:69], v[186:189], v[224:227], v[66:69]
	s_barrier
	s_setprio 0
	s_add_i32 s29, s29, s4
	v_lshl_add_u64 v[160:161], v[160:161], 0, s[24:25]
	s_mov_b32 m0, s29
	ds_read_b128 v[190:193], v143 offset:49152
	ds_read_b128 v[194:197], v143 offset:50176
	ds_read_b128 v[204:207], v143 offset:51200
	ds_read_b128 v[208:211], v143 offset:52224
	ds_read_b128 v[212:215], v143 offset:53248
	ds_read_b128 v[216:219], v143 offset:54272
	ds_read_b128 v[220:223], v143 offset:55296
	ds_read_b128 v[224:227], v143 offset:56320
	global_load_lds_dwordx4 v[160:161], off
	s_add_i32 m0, s29, 0x2000
	s_add_u32 s50, s50, 0x100080
	v_lshl_add_u64 v[160:161], v[170:171], 0, s[24:25]
	s_addc_u32 s51, s51, 0
	s_add_i32 s29, s37, s4
	global_load_lds_dwordx4 v[160:161], off
	s_mov_b32 m0, s29
	s_nop 0
	global_load_lds_dwordx4 v0, s[50:51]
	s_add_i32 m0, s29, 0x2000
	s_nop 0
	global_load_lds_dwordx4 v130, s[50:51]
	v_lshl_add_u64 v[160:161], v[172:173], 0, s[24:25]
	s_mov_b32 m0, s23
	s_nop 0
	global_load_lds_dwordx4 v[160:161], off
	v_lshl_add_u64 v[160:161], v[198:199], 0, s[24:25]
	s_mov_b32 m0, s28
	s_nop 0
	global_load_lds_dwordx4 v[160:161], off
	s_waitcnt vmcnt(8)
	s_waitcnt lgkmcnt(0)
	s_setprio 1
	s_barrier
	v_mfma_f32_16x16x32_bf16 v[62:65], v[144:147], v[190:193], v[62:65]
	v_mfma_f32_16x16x32_bf16 v[58:61], v[152:155], v[190:193], v[58:61]
	v_mfma_f32_16x16x32_bf16 v[46:49], v[144:147], v[204:207], v[46:49]
	v_mfma_f32_16x16x32_bf16 v[42:45], v[152:155], v[204:207], v[42:45]
	v_mfma_f32_16x16x32_bf16 v[30:33], v[144:147], v[212:215], v[30:33]
	v_mfma_f32_16x16x32_bf16 v[26:29], v[152:155], v[212:215], v[26:29]
	v_mfma_f32_16x16x32_bf16 v[14:17], v[144:147], v[220:223], v[14:17]
	v_mfma_f32_16x16x32_bf16 v[10:13], v[152:155], v[220:223], v[10:13]
	v_mfma_f32_16x16x32_bf16 v[62:65], v[148:151], v[194:197], v[62:65]
	v_mfma_f32_16x16x32_bf16 v[58:61], v[156:159], v[194:197], v[58:61]
	v_mfma_f32_16x16x32_bf16 v[46:49], v[148:151], v[208:211], v[46:49]
	v_mfma_f32_16x16x32_bf16 v[42:45], v[156:159], v[208:211], v[42:45]
	v_mfma_f32_16x16x32_bf16 v[30:33], v[148:151], v[216:219], v[30:33]
	v_mfma_f32_16x16x32_bf16 v[26:29], v[156:159], v[216:219], v[26:29]
	v_mfma_f32_16x16x32_bf16 v[14:17], v[148:151], v[224:227], v[14:17]
	v_mfma_f32_16x16x32_bf16 v[10:13], v[156:159], v[224:227], v[10:13]
	v_mfma_f32_16x16x32_bf16 v[54:57], v[174:177], v[190:193], v[54:57]
	v_mfma_f32_16x16x32_bf16 v[50:53], v[182:185], v[190:193], v[50:53]
	v_mfma_f32_16x16x32_bf16 v[38:41], v[174:177], v[204:207], v[38:41]
	v_mfma_f32_16x16x32_bf16 v[34:37], v[182:185], v[204:207], v[34:37]
	v_mfma_f32_16x16x32_bf16 v[22:25], v[174:177], v[212:215], v[22:25]
	v_mfma_f32_16x16x32_bf16 v[18:21], v[182:185], v[212:215], v[18:21]
	v_mfma_f32_16x16x32_bf16 v[6:9], v[174:177], v[220:223], v[6:9]
	v_mfma_f32_16x16x32_bf16 v[2:5], v[182:185], v[220:223], v[2:5]
	v_mfma_f32_16x16x32_bf16 v[54:57], v[178:181], v[194:197], v[54:57]
	v_mfma_f32_16x16x32_bf16 v[50:53], v[186:189], v[194:197], v[50:53]
	v_mfma_f32_16x16x32_bf16 v[38:41], v[178:181], v[208:211], v[38:41]
	v_mfma_f32_16x16x32_bf16 v[34:37], v[186:189], v[208:211], v[34:37]
	v_mfma_f32_16x16x32_bf16 v[22:25], v[178:181], v[216:219], v[22:25]
	v_mfma_f32_16x16x32_bf16 v[18:21], v[186:189], v[216:219], v[18:21]
	v_mfma_f32_16x16x32_bf16 v[6:9], v[178:181], v[224:227], v[6:9]
	v_mfma_f32_16x16x32_bf16 v[2:5], v[186:189], v[224:227], v[2:5]
	s_barrier
	s_setprio 0
	s_add_u32 s48, s48, 0x100
	s_addc_u32 s49, s49, 0
	s_add_u32 s56, s56, 0x100
	s_addc_u32 s57, s57, 0
	s_cmp_ge_i32 s72, s3
	s_mov_b32 s50, s72
	s_cbranch_scc0 .LBB7_1274
	s_branch .Lpeelx_1274
	.p2align	8
